# v6 + removed the no-op s_setprio 0/1 flip between the two 16-MFMA bursts of every GEMM super-phase (32 pairs)
# speedup vs baseline: 1.0016x; 1.0016x over previous
; #define PG8_STAGE(bufoff, gbase, voff) do { _Pragma("unroll") for (int _i = 0; _i < 2; ++_i) \
;         __builtin_amdgcn_global_load_lds((const unsigned*)((const char*)(gbase) + (voff)[_i]), (PG8_LAS unsigned*)(lds + (bufoff) + ldsw + _i * 8192), 16, 0, 0); } while (0)
; #define PG8_LDA(dst, b, h) do { _Pragma("unroll") for (int m = 0; m < 4; ++m) _Pragma("unroll") for (int k = 0; k < 2; ++k) dst[m][k] = *(const PG8_LAS bf16x8*)(lds + PG8_SA(b, h) + aoff + m * 2048 + k * 1024); } while (0)
; #define PG8_LDB(dst, b, h) do { _Pragma("unroll") for (int n = 0; n < 2; ++n) _Pragma("unroll") for (int k = 0; k < 2; ++k) dst[n][k] = *(const PG8_LAS bf16x8*)(lds + PG8_SB(b, h) + boff + n * 2048 + k * 1024); } while (0)
; #define PG8_MMA(ai, bj, At, Bt) do { __builtin_amdgcn_s_setprio(1); _Pragma("unroll") for (int m = 0; m < 4; ++m) _Pragma("unroll") for (int n = 0; n < 2; ++n) _Pragma("unroll") for (int k = 0; k < 2; ++k) \
;         acc[ai][bj][m][n] = __builtin_amdgcn_mfma_f32_16x16x32_bf16(Bt[n][k], At[m][k], acc[ai][bj][m][n], 0, 0, 0); __builtin_amdgcn_s_setprio(0); } while (0)
; #define PG8_WAIT_V(n) asm volatile("s_waitcnt vmcnt(" #n ")" ::: "memory")
; #define PG8_WAIT_L(n) asm volatile("s_waitcnt lgkmcnt(" #n ")" ::: "memory")
; #define PG8_BAR __builtin_amdgcn_s_barrier()
; #define PG8_SCHED __builtin_amdgcn_sched_barrier(0)
; template <class Epi, class Sched, bool ALIGN_EPI = false, bool SP2 = false>
; __device__ __forceinline__ void gemm_phase(PG8_LAS unsigned char* lds, const Gemm g, const Sched& S, const Epi& E) {
;     ...
;             PG8_LDB(B0, 0, 0); PG8_LDB(B1, 0, 1); PG8_SCHED; PG8_LDA(At, 0, 0); PG8_STAGE(PG8_SA(1, 1), a1 + hstep, voffA);
;             PG8_WAIT_V(8); PG8_WAIT_L(0); PG8_BAR; PG8_MMA(0, 0, At, B0); PG8_MMA(0, 1, At, B1); PG8_BAR; PG8_SCHED;
;             PG8_LDA(At, 0, 1); PG8_STAGE(PG8_SB(0, 0), b2, voffB); PG8_STAGE(PG8_SB(0, 1), b2 + hstep, voffB); PG8_STAGE(PG8_SA(0, 0), a2, voffA);
;             PG8_WAIT_V(8); PG8_WAIT_L(0); PG8_BAR; PG8_MMA(1, 0, At, B0); PG8_MMA(1, 1, At, B1); PG8_BAR; PG8_SCHED;
.LBB0_510:
	ds_read_b128 v[128:131], v184
	ds_read_b128 v[148:151], v184 offset:1024
	ds_read_b128 v[152:155], v184 offset:2048
	ds_read_b128 v[158:161], v184 offset:3072
	ds_read_b128 v[190:193], v185
	ds_read_b128 v[194:197], v185 offset:1024
	ds_read_b128 v[198:201], v185 offset:2048
	ds_read_b128 v[202:205], v185 offset:3072
	s_add_u32 s34, s10, 0xfffc0080
	s_addc_u32 s35, s11, -1
	s_cmp_eq_u32 vcc_lo, 12
	s_cselect_b32 s69, s57, s35
	s_cselect_b32 s68, s63, s34
	s_cselect_b32 s67, s55, s97
	s_cselect_b32 s66, s95, s96
	s_add_i32 m0, s65, 0xc000
	ds_read_b128 v[206:209], v186
	ds_read_b128 v[210:213], v186 offset:1024
	ds_read_b128 v[214:217], v186 offset:2048
	ds_read_b128 v[218:221], v186 offset:3072
	ds_read_b128 v[222:225], v186 offset:4096
	ds_read_b128 v[226:229], v186 offset:5120
	ds_read_b128 v[230:233], v186 offset:6144
	ds_read_b128 v[234:237], v186 offset:7168
	global_load_lds_dwordx4 v142, s[10:11]
	s_add_i32 m0, s65, 0xe000
	s_nop 0
	global_load_lds_dwordx4 v140, s[10:11]
	s_waitcnt vmcnt(8)
	s_waitcnt lgkmcnt(0)
	s_barrier
	s_setprio 1
	s_waitcnt lgkmcnt(0)
	v_mfma_f32_16x16x32_bf16 v[124:127], v[128:131], v[206:209], v[124:127]
	v_mfma_f32_16x16x32_bf16 v[124:127], v[148:151], v[210:213], v[124:127]
	v_mfma_f32_16x16x32_bf16 v[120:123], v[152:155], v[206:209], v[120:123]
	v_mfma_f32_16x16x32_bf16 v[120:123], v[158:161], v[210:213], v[120:123]
	v_mfma_f32_16x16x32_bf16 v[104:107], v[152:155], v[214:217], v[104:107]
	v_mfma_f32_16x16x32_bf16 v[104:107], v[158:161], v[218:221], v[104:107]
	v_mfma_f32_16x16x32_bf16 v[108:111], v[128:131], v[214:217], v[108:111]
	v_mfma_f32_16x16x32_bf16 v[108:111], v[148:151], v[218:221], v[108:111]
	v_mfma_f32_16x16x32_bf16 v[92:95], v[128:131], v[222:225], v[92:95]
	v_mfma_f32_16x16x32_bf16 v[92:95], v[148:151], v[226:229], v[92:95]
	v_mfma_f32_16x16x32_bf16 v[88:91], v[152:155], v[222:225], v[88:91]
	v_mfma_f32_16x16x32_bf16 v[88:91], v[158:161], v[226:229], v[88:91]
	v_mfma_f32_16x16x32_bf16 v[72:75], v[152:155], v[230:233], v[72:75]
	v_mfma_f32_16x16x32_bf16 v[72:75], v[158:161], v[234:237], v[72:75]
	v_mfma_f32_16x16x32_bf16 v[76:79], v[128:131], v[230:233], v[76:79]
	v_mfma_f32_16x16x32_bf16 v[76:79], v[148:151], v[234:237], v[76:79]
	v_mfma_f32_16x16x32_bf16 v[116:119], v[190:193], v[206:209], v[116:119]
	v_mfma_f32_16x16x32_bf16 v[116:119], v[194:197], v[210:213], v[116:119]
	v_mfma_f32_16x16x32_bf16 v[112:115], v[198:201], v[206:209], v[112:115]
	v_mfma_f32_16x16x32_bf16 v[112:115], v[202:205], v[210:213], v[112:115]
	v_mfma_f32_16x16x32_bf16 v[96:99], v[198:201], v[214:217], v[96:99]
	v_mfma_f32_16x16x32_bf16 v[96:99], v[202:205], v[218:221], v[96:99]
	v_mfma_f32_16x16x32_bf16 v[100:103], v[190:193], v[214:217], v[100:103]
	v_mfma_f32_16x16x32_bf16 v[100:103], v[194:197], v[218:221], v[100:103]
	v_mfma_f32_16x16x32_bf16 v[84:87], v[190:193], v[222:225], v[84:87]
	v_mfma_f32_16x16x32_bf16 v[84:87], v[194:197], v[226:229], v[84:87]
	v_mfma_f32_16x16x32_bf16 v[80:83], v[198:201], v[222:225], v[80:83]
	v_mfma_f32_16x16x32_bf16 v[80:83], v[202:205], v[226:229], v[80:83]
	v_mfma_f32_16x16x32_bf16 v[64:67], v[198:201], v[230:233], v[64:67]
	v_mfma_f32_16x16x32_bf16 v[64:67], v[202:205], v[234:237], v[64:67]
	v_mfma_f32_16x16x32_bf16 v[68:71], v[190:193], v[230:233], v[68:71]
	v_mfma_f32_16x16x32_bf16 v[68:71], v[194:197], v[234:237], v[68:71]
	s_setprio 0
	s_barrier
	s_add_i32 s34, s84, s71
	s_mov_b32 m0, s34
	ds_read_b128 v[206:209], v186 offset:16384
	ds_read_b128 v[210:213], v186 offset:17408
	ds_read_b128 v[214:217], v186 offset:18432
	ds_read_b128 v[218:221], v186 offset:19456
	ds_read_b128 v[222:225], v186 offset:20480
	ds_read_b128 v[226:229], v186 offset:21504
	ds_read_b128 v[230:233], v186 offset:22528
	ds_read_b128 v[234:237], v186 offset:23552
	global_load_lds_dwordx4 v134, s[66:67]
	s_add_i32 m0, s34, 0x2000
	s_add_u32 s34, s66, 0x40000
	s_addc_u32 s35, s67, 0
	s_add_i32 vcc_hi, s85, s71
	global_load_lds_dwordx4 v138, s[66:67]
	s_mov_b32 m0, vcc_hi
	s_nop 0
	global_load_lds_dwordx4 v134, s[34:35]
	s_add_i32 m0, vcc_hi, 0x2000
	s_nop 0
	global_load_lds_dwordx4 v138, s[34:35]
	s_mov_b32 m0, s65
	s_nop 0
	global_load_lds_dwordx4 v132, s[68:69]
	s_mov_b32 m0, s73
	s_nop 0
	global_load_lds_dwordx4 v136, s[68:69]
	s_waitcnt vmcnt(8)
	s_waitcnt lgkmcnt(0)
	s_barrier
	s_setprio 1
	s_waitcnt lgkmcnt(0)
	v_mfma_f32_16x16x32_bf16 v[60:63], v[128:131], v[206:209], v[60:63]
	v_mfma_f32_16x16x32_bf16 v[60:63], v[148:151], v[210:213], v[60:63]
	v_mfma_f32_16x16x32_bf16 v[56:59], v[152:155], v[206:209], v[56:59]
	v_mfma_f32_16x16x32_bf16 v[56:59], v[158:161], v[210:213], v[56:59]
	v_mfma_f32_16x16x32_bf16 v[40:43], v[152:155], v[214:217], v[40:43]
	v_mfma_f32_16x16x32_bf16 v[40:43], v[158:161], v[218:221], v[40:43]
	v_mfma_f32_16x16x32_bf16 v[44:47], v[128:131], v[214:217], v[44:47]
	v_mfma_f32_16x16x32_bf16 v[44:47], v[148:151], v[218:221], v[44:47]
	v_mfma_f32_16x16x32_bf16 v[28:31], v[128:131], v[222:225], v[28:31]
	v_mfma_f32_16x16x32_bf16 v[28:31], v[148:151], v[226:229], v[28:31]
	v_mfma_f32_16x16x32_bf16 v[24:27], v[152:155], v[222:225], v[24:27]
	v_mfma_f32_16x16x32_bf16 v[24:27], v[158:161], v[226:229], v[24:27]
	v_mfma_f32_16x16x32_bf16 v[8:11], v[152:155], v[230:233], v[8:11]
	v_mfma_f32_16x16x32_bf16 v[8:11], v[158:161], v[234:237], v[8:11]
	v_mfma_f32_16x16x32_bf16 v[12:15], v[128:131], v[230:233], v[12:15]
	v_mfma_f32_16x16x32_bf16 v[12:15], v[148:151], v[234:237], v[12:15]
	v_mfma_f32_16x16x32_bf16 v[52:55], v[190:193], v[206:209], v[52:55]
	v_mfma_f32_16x16x32_bf16 v[52:55], v[194:197], v[210:213], v[52:55]
	v_mfma_f32_16x16x32_bf16 v[48:51], v[198:201], v[206:209], v[48:51]
	v_mfma_f32_16x16x32_bf16 v[48:51], v[202:205], v[210:213], v[48:51]
	v_mfma_f32_16x16x32_bf16 v[32:35], v[198:201], v[214:217], v[32:35]
	v_mfma_f32_16x16x32_bf16 v[32:35], v[202:205], v[218:221], v[32:35]
	v_mfma_f32_16x16x32_bf16 v[36:39], v[190:193], v[214:217], v[36:39]
	v_mfma_f32_16x16x32_bf16 v[36:39], v[194:197], v[218:221], v[36:39]
	v_mfma_f32_16x16x32_bf16 v[20:23], v[190:193], v[222:225], v[20:23]
	v_mfma_f32_16x16x32_bf16 v[20:23], v[194:197], v[226:229], v[20:23]
	v_mfma_f32_16x16x32_bf16 v[16:19], v[198:201], v[222:225], v[16:19]
	v_mfma_f32_16x16x32_bf16 v[16:19], v[202:205], v[226:229], v[16:19]
	v_mfma_f32_16x16x32_bf16 v[0:3], v[198:201], v[230:233], v[0:3]
	v_mfma_f32_16x16x32_bf16 v[0:3], v[202:205], v[234:237], v[0:3]
	v_mfma_f32_16x16x32_bf16 v[4:7], v[190:193], v[230:233], v[4:7]
	v_mfma_f32_16x16x32_bf16 v[4:7], v[194:197], v[234:237], v[4:7]
	s_setprio 0
	s_barrier
; #define PG8_STAGE(bufoff, gbase, voff) do { _Pragma("unroll") for (int _i = 0; _i < 2; ++_i) \
;         __builtin_amdgcn_global_load_lds((const unsigned*)((const char*)(gbase) + (voff)[_i]), (PG8_LAS unsigned*)(lds + (bufoff) + ldsw + _i * 8192), 16, 0, 0); } while (0)
; #define PG8_LDA(dst, b, h) do { _Pragma("unroll") for (int m = 0; m < 4; ++m) _Pragma("unroll") for (int k = 0; k < 2; ++k) dst[m][k] = *(const PG8_LAS bf16x8*)(lds + PG8_SA(b, h) + aoff + m * 2048 + k * 1024); } while (0)
; #define PG8_LDB(dst, b, h) do { _Pragma("unroll") for (int n = 0; n < 2; ++n) _Pragma("unroll") for (int k = 0; k < 2; ++k) dst[n][k] = *(const PG8_LAS bf16x8*)(lds + PG8_SB(b, h) + boff + n * 2048 + k * 1024); } while (0)
; #define PG8_MMA(ai, bj, At, Bt) do { __builtin_amdgcn_s_setprio(1); _Pragma("unroll") for (int m = 0; m < 4; ++m) _Pragma("unroll") for (int n = 0; n < 2; ++n) _Pragma("unroll") for (int k = 0; k < 2; ++k) \
;         acc[ai][bj][m][n] = __builtin_amdgcn_mfma_f32_16x16x32_bf16(Bt[n][k], At[m][k], acc[ai][bj][m][n], 0, 0, 0); __builtin_amdgcn_s_setprio(0); } while (0)
; #define PG8_WAIT_V(n) asm volatile("s_waitcnt vmcnt(" #n ")" ::: "memory")
; #define PG8_WAIT_L(n) asm volatile("s_waitcnt lgkmcnt(" #n ")" ::: "memory")
; #define PG8_BAR __builtin_amdgcn_s_barrier()
; #define PG8_SCHED __builtin_amdgcn_sched_barrier(0)
; template <class Epi, class Sched, bool ALIGN_EPI = false, bool SP2 = false>
; __device__ __forceinline__ void gemm_phase(PG8_LAS unsigned char* lds, const Gemm g, const Sched& S, const Epi& E) {
;     ...
;             PG8_LDB(B0, 1, 0); PG8_LDB(B1, 1, 1); PG8_SCHED; PG8_LDA(At, 1, 0); PG8_STAGE(PG8_SA(0, 1), a2 + hstep, voffA);
;             PG8_WAIT_V(8); PG8_WAIT_L(0); PG8_BAR; PG8_MMA(0, 0, At, B0); PG8_MMA(0, 1, At, B1); PG8_BAR; PG8_SCHED;
;             PG8_LDA(At, 1, 1); PG8_STAGE(PG8_SB(1, 0), b3, voffB); PG8_STAGE(PG8_SB(1, 1), b3 + hstep, voffB); PG8_STAGE(PG8_SA(1, 0), a3, voffA);
;             PG8_WAIT_V(8); PG8_WAIT_L(0); PG8_BAR; PG8_MMA(1, 0, At, B0); PG8_MMA(1, 1, At, B1); PG8_BAR; PG8_SCHED;
	s_add_i32 vcc_hi, 0, 0x18000
	s_add_i32 s14, 0, 0x1c000
	v_add_u32_e32 v158, vcc_hi, v163
	v_add_u32_e32 v202, s14, v163
	ds_read_b128 v[128:131], v158
	ds_read_b128 v[148:151], v158 offset:1024
	ds_read_b128 v[152:155], v158 offset:2048
	ds_read_b128 v[158:161], v158 offset:3072
	ds_read_b128 v[190:193], v202
	ds_read_b128 v[194:197], v202 offset:1024
	ds_read_b128 v[198:201], v202 offset:2048
	ds_read_b128 v[202:205], v202 offset:3072
	s_add_u32 s34, s68, 0x40000
	s_addc_u32 s35, s69, 0
	s_mov_b32 m0, s74
	ds_read_b128 v[206:209], v186 offset:32768
	ds_read_b128 v[210:213], v186 offset:33792
	ds_read_b128 v[214:217], v186 offset:34816
	ds_read_b128 v[218:221], v186 offset:35840
	ds_read_b128 v[222:225], v186 offset:36864
	ds_read_b128 v[226:229], v186 offset:37888
	ds_read_b128 v[230:233], v186 offset:38912
	ds_read_b128 v[234:237], v186 offset:39936
	global_load_lds_dwordx4 v132, s[34:35]
	s_mov_b32 m0, s75
	s_nop 0
	global_load_lds_dwordx4 v136, s[34:35]
	s_waitcnt vmcnt(8)
	s_waitcnt lgkmcnt(0)
	s_barrier
	s_setprio 1
	s_waitcnt lgkmcnt(0)
	v_mfma_f32_16x16x32_bf16 v[124:127], v[128:131], v[206:209], v[124:127]
	v_mfma_f32_16x16x32_bf16 v[124:127], v[148:151], v[210:213], v[124:127]
	v_mfma_f32_16x16x32_bf16 v[120:123], v[152:155], v[206:209], v[120:123]
	v_mfma_f32_16x16x32_bf16 v[120:123], v[158:161], v[210:213], v[120:123]
	v_mfma_f32_16x16x32_bf16 v[104:107], v[152:155], v[214:217], v[104:107]
	v_mfma_f32_16x16x32_bf16 v[104:107], v[158:161], v[218:221], v[104:107]
	v_mfma_f32_16x16x32_bf16 v[108:111], v[128:131], v[214:217], v[108:111]
	v_mfma_f32_16x16x32_bf16 v[108:111], v[148:151], v[218:221], v[108:111]
	v_mfma_f32_16x16x32_bf16 v[92:95], v[128:131], v[222:225], v[92:95]
	v_mfma_f32_16x16x32_bf16 v[92:95], v[148:151], v[226:229], v[92:95]
	v_mfma_f32_16x16x32_bf16 v[88:91], v[152:155], v[222:225], v[88:91]
	v_mfma_f32_16x16x32_bf16 v[88:91], v[158:161], v[226:229], v[88:91]
	v_mfma_f32_16x16x32_bf16 v[72:75], v[152:155], v[230:233], v[72:75]
	v_mfma_f32_16x16x32_bf16 v[72:75], v[158:161], v[234:237], v[72:75]
	v_mfma_f32_16x16x32_bf16 v[76:79], v[128:131], v[230:233], v[76:79]
	v_mfma_f32_16x16x32_bf16 v[76:79], v[148:151], v[234:237], v[76:79]
	v_mfma_f32_16x16x32_bf16 v[116:119], v[190:193], v[206:209], v[116:119]
	v_mfma_f32_16x16x32_bf16 v[116:119], v[194:197], v[210:213], v[116:119]
	v_mfma_f32_16x16x32_bf16 v[112:115], v[198:201], v[206:209], v[112:115]
	v_mfma_f32_16x16x32_bf16 v[112:115], v[202:205], v[210:213], v[112:115]
	v_mfma_f32_16x16x32_bf16 v[96:99], v[198:201], v[214:217], v[96:99]
	v_mfma_f32_16x16x32_bf16 v[96:99], v[202:205], v[218:221], v[96:99]
	v_mfma_f32_16x16x32_bf16 v[100:103], v[190:193], v[214:217], v[100:103]
	v_mfma_f32_16x16x32_bf16 v[100:103], v[194:197], v[218:221], v[100:103]
	v_mfma_f32_16x16x32_bf16 v[84:87], v[190:193], v[222:225], v[84:87]
	v_mfma_f32_16x16x32_bf16 v[84:87], v[194:197], v[226:229], v[84:87]
	v_mfma_f32_16x16x32_bf16 v[80:83], v[198:201], v[222:225], v[80:83]
	v_mfma_f32_16x16x32_bf16 v[80:83], v[202:205], v[226:229], v[80:83]
	v_mfma_f32_16x16x32_bf16 v[64:67], v[198:201], v[230:233], v[64:67]
	v_mfma_f32_16x16x32_bf16 v[64:67], v[202:205], v[234:237], v[64:67]
	v_mfma_f32_16x16x32_bf16 v[68:71], v[190:193], v[230:233], v[68:71]
	v_mfma_f32_16x16x32_bf16 v[68:71], v[194:197], v[234:237], v[68:71]
	s_setprio 0
	s_barrier
	s_add_i32 s15, vcc_hi, s71
	s_add_u32 s98, s66, s42
	s_addc_u32 s99, s67, s43
	s_add_u32 s100, s68, s42
	s_addc_u32 s101, s69, s43
	s_mov_b32 m0, s15
	ds_read_b128 v[206:209], v186 offset:49152
	ds_read_b128 v[210:213], v186 offset:50176
	ds_read_b128 v[214:217], v186 offset:51200
	ds_read_b128 v[218:221], v186 offset:52224
	ds_read_b128 v[222:225], v186 offset:53248
	ds_read_b128 v[226:229], v186 offset:54272
	ds_read_b128 v[230:233], v186 offset:55296
	ds_read_b128 v[234:237], v186 offset:56320
	global_load_lds_dwordx4 v134, s[98:99]
	s_add_i32 m0, s15, 0x2000
	s_add_u32 s34, s66, 0x40080
	s_addc_u32 s35, s67, 0
	s_add_i32 s14, s14, s71
	global_load_lds_dwordx4 v138, s[98:99]
	s_mov_b32 m0, s14
	s_nop 0
	global_load_lds_dwordx4 v134, s[34:35]
	s_add_i32 m0, s14, 0x2000
	s_nop 0
	global_load_lds_dwordx4 v138, s[34:35]
	s_mov_b32 m0, s78
	s_nop 0
	global_load_lds_dwordx4 v132, s[100:101]
	s_mov_b32 m0, s79
	s_nop 0
	global_load_lds_dwordx4 v136, s[100:101]
	s_waitcnt vmcnt(8)
	s_waitcnt lgkmcnt(0)
	s_barrier
	s_setprio 1
	s_waitcnt lgkmcnt(0)
	v_mfma_f32_16x16x32_bf16 v[60:63], v[128:131], v[206:209], v[60:63]
	v_mfma_f32_16x16x32_bf16 v[60:63], v[148:151], v[210:213], v[60:63]
	v_mfma_f32_16x16x32_bf16 v[56:59], v[152:155], v[206:209], v[56:59]
	v_mfma_f32_16x16x32_bf16 v[56:59], v[158:161], v[210:213], v[56:59]
	v_mfma_f32_16x16x32_bf16 v[40:43], v[152:155], v[214:217], v[40:43]
	v_mfma_f32_16x16x32_bf16 v[40:43], v[158:161], v[218:221], v[40:43]
	v_mfma_f32_16x16x32_bf16 v[44:47], v[128:131], v[214:217], v[44:47]
	v_mfma_f32_16x16x32_bf16 v[44:47], v[148:151], v[218:221], v[44:47]
	v_mfma_f32_16x16x32_bf16 v[28:31], v[128:131], v[222:225], v[28:31]
	v_mfma_f32_16x16x32_bf16 v[28:31], v[148:151], v[226:229], v[28:31]
	v_mfma_f32_16x16x32_bf16 v[24:27], v[152:155], v[222:225], v[24:27]
	v_mfma_f32_16x16x32_bf16 v[24:27], v[158:161], v[226:229], v[24:27]
	v_mfma_f32_16x16x32_bf16 v[8:11], v[152:155], v[230:233], v[8:11]
	v_mfma_f32_16x16x32_bf16 v[8:11], v[158:161], v[234:237], v[8:11]
	v_mfma_f32_16x16x32_bf16 v[12:15], v[128:131], v[230:233], v[12:15]
	v_mfma_f32_16x16x32_bf16 v[12:15], v[148:151], v[234:237], v[12:15]
	v_mfma_f32_16x16x32_bf16 v[52:55], v[190:193], v[206:209], v[52:55]
	v_mfma_f32_16x16x32_bf16 v[52:55], v[194:197], v[210:213], v[52:55]
	v_mfma_f32_16x16x32_bf16 v[48:51], v[198:201], v[206:209], v[48:51]
	v_mfma_f32_16x16x32_bf16 v[48:51], v[202:205], v[210:213], v[48:51]
	v_mfma_f32_16x16x32_bf16 v[32:35], v[198:201], v[214:217], v[32:35]
	v_mfma_f32_16x16x32_bf16 v[32:35], v[202:205], v[218:221], v[32:35]
	v_mfma_f32_16x16x32_bf16 v[36:39], v[190:193], v[214:217], v[36:39]
	v_mfma_f32_16x16x32_bf16 v[36:39], v[194:197], v[218:221], v[36:39]
	v_mfma_f32_16x16x32_bf16 v[20:23], v[190:193], v[222:225], v[20:23]
	v_mfma_f32_16x16x32_bf16 v[20:23], v[194:197], v[226:229], v[20:23]
	v_mfma_f32_16x16x32_bf16 v[16:19], v[198:201], v[222:225], v[16:19]
	v_mfma_f32_16x16x32_bf16 v[16:19], v[202:205], v[226:229], v[16:19]
	v_mfma_f32_16x16x32_bf16 v[0:3], v[198:201], v[230:233], v[0:3]
	v_mfma_f32_16x16x32_bf16 v[0:3], v[202:205], v[234:237], v[0:3]
	v_mfma_f32_16x16x32_bf16 v[4:7], v[190:193], v[230:233], v[4:7]
	v_mfma_f32_16x16x32_bf16 v[4:7], v[194:197], v[234:237], v[4:7]
	s_setprio 0
	s_barrier
	s_add_i32 vcc_lo, vcc_lo, 2
	s_add_u32 s96, s96, 0x100
	s_addc_u32 s97, s97, 0
	s_add_u32 s10, s10, 0x100
	s_addc_u32 s11, s11, 0
	s_cmp_gt_u32 vcc_lo, 13
	s_cbranch_scc0 .LBB0_510
	s_and_b64 vcc, exec, s[44:45]
	s_cbranch_vccz .LBB0_513
	s_barrier

; #define PG8_STAGE(bufoff, gbase, voff) do { _Pragma("unroll") for (int _i = 0; _i < 2; ++_i) \
;         __builtin_amdgcn_global_load_lds((const unsigned*)((const char*)(gbase) + (voff)[_i]), (PG8_LAS unsigned*)(lds + (bufoff) + ldsw + _i * 8192), 16, 0, 0); } while (0)
; #define PG8_LDA(dst, b, h) do { _Pragma("unroll") for (int m = 0; m < 4; ++m) _Pragma("unroll") for (int k = 0; k < 2; ++k) dst[m][k] = *(const PG8_LAS bf16x8*)(lds + PG8_SA(b, h) + aoff + m * 2048 + k * 1024); } while (0)
; #define PG8_LDB(dst, b, h) do { _Pragma("unroll") for (int n = 0; n < 2; ++n) _Pragma("unroll") for (int k = 0; k < 2; ++k) dst[n][k] = *(const PG8_LAS bf16x8*)(lds + PG8_SB(b, h) + boff + n * 2048 + k * 1024); } while (0)
; #define PG8_MMA(ai, bj, At, Bt) do { __builtin_amdgcn_s_setprio(1); _Pragma("unroll") for (int m = 0; m < 4; ++m) _Pragma("unroll") for (int n = 0; n < 2; ++n) _Pragma("unroll") for (int k = 0; k < 2; ++k) \
;         acc[ai][bj][m][n] = __builtin_amdgcn_mfma_f32_16x16x32_bf16(Bt[n][k], At[m][k], acc[ai][bj][m][n], 0, 0, 0); __builtin_amdgcn_s_setprio(0); } while (0)
; #define PG8_WAIT_V(n) asm volatile("s_waitcnt vmcnt(" #n ")" ::: "memory")
; #define PG8_WAIT_L(n) asm volatile("s_waitcnt lgkmcnt(" #n ")" ::: "memory")
; #define PG8_BAR __builtin_amdgcn_s_barrier()
; #define PG8_SCHED __builtin_amdgcn_sched_barrier(0)
; template <class Epi, class Sched, bool ALIGN_EPI = false, bool SP2 = false>
; __device__ __forceinline__ void gemm_phase(PG8_LAS unsigned char* lds, const Gemm g, const Sched& S, const Epi& E) {
;     ...
;             PG8_LDB(B0, 0, 0); PG8_LDB(B1, 0, 1); PG8_SCHED; PG8_LDA(At, 0, 0); PG8_STAGE(PG8_SA(1, 1), a1 + hstep, voffA);
;             PG8_WAIT_V(8); PG8_WAIT_L(0); PG8_BAR; PG8_MMA(0, 0, At, B0); PG8_MMA(0, 1, At, B1); PG8_BAR; PG8_SCHED;
;             PG8_LDA(At, 0, 1); PG8_STAGE(PG8_SB(0, 0), b2, voffB); PG8_STAGE(PG8_SB(0, 1), b2 + hstep, voffB); PG8_STAGE(PG8_SA(0, 0), a2, voffA);
;             PG8_WAIT_V(8); PG8_WAIT_L(0); PG8_BAR; PG8_MMA(1, 0, At, B0); PG8_MMA(1, 1, At, B1); PG8_BAR; PG8_SCHED;
.LBB0_710:
	ds_read_b128 v[128:131], v169
	ds_read_b128 v[132:135], v169 offset:1024
	ds_read_b128 v[136:139], v169 offset:2048
	ds_read_b128 v[140:143], v169 offset:3072
	ds_read_b128 v[162:165], v170
	ds_read_b128 v[172:175], v170 offset:1024
	ds_read_b128 v[176:179], v170 offset:2048
	ds_read_b128 v[184:187], v170 offset:3072
	s_add_u32 s14, s54, 0xfffc0080
	s_addc_u32 s15, s55, -1
	s_cmp_eq_u32 s84, 12
	s_cselect_b32 s59, s45, s15
	s_cselect_b32 s58, s51, s14
	s_cselect_b32 s57, s43, s83
	s_cselect_b32 s56, s53, s82
	s_add_i32 m0, s64, 0xc000
	ds_read_b128 v[188:191], v171
	ds_read_b128 v[192:195], v171 offset:1024
	ds_read_b128 v[196:199], v171 offset:2048
	ds_read_b128 v[200:203], v171 offset:3072
	ds_read_b128 v[204:207], v171 offset:4096
	ds_read_b128 v[208:211], v171 offset:5120
	ds_read_b128 v[212:215], v171 offset:6144
	ds_read_b128 v[216:219], v171 offset:7168
	global_load_lds_dwordx4 v154, s[54:55]
	s_add_i32 m0, s64, 0xe000
	s_nop 0
	global_load_lds_dwordx4 v152, s[54:55]
	s_waitcnt vmcnt(8)
	s_waitcnt lgkmcnt(0)
	s_barrier
	s_setprio 1
	s_waitcnt lgkmcnt(0)
	v_mfma_f32_16x16x32_bf16 v[124:127], v[128:131], v[188:191], v[124:127]
	v_mfma_f32_16x16x32_bf16 v[124:127], v[132:135], v[192:195], v[124:127]
	v_mfma_f32_16x16x32_bf16 v[120:123], v[136:139], v[188:191], v[120:123]
	v_mfma_f32_16x16x32_bf16 v[120:123], v[140:143], v[192:195], v[120:123]
	v_mfma_f32_16x16x32_bf16 v[108:111], v[136:139], v[196:199], v[108:111]
	v_mfma_f32_16x16x32_bf16 v[108:111], v[140:143], v[200:203], v[108:111]
	v_mfma_f32_16x16x32_bf16 v[116:119], v[128:131], v[196:199], v[116:119]
	v_mfma_f32_16x16x32_bf16 v[116:119], v[132:135], v[200:203], v[116:119]
	v_mfma_f32_16x16x32_bf16 v[100:103], v[128:131], v[204:207], v[100:103]
	v_mfma_f32_16x16x32_bf16 v[100:103], v[132:135], v[208:211], v[100:103]
	v_mfma_f32_16x16x32_bf16 v[92:95], v[136:139], v[204:207], v[92:95]
	v_mfma_f32_16x16x32_bf16 v[92:95], v[140:143], v[208:211], v[92:95]
	v_mfma_f32_16x16x32_bf16 v[76:79], v[136:139], v[212:215], v[76:79]
	v_mfma_f32_16x16x32_bf16 v[76:79], v[140:143], v[216:219], v[76:79]
	v_mfma_f32_16x16x32_bf16 v[84:87], v[128:131], v[212:215], v[84:87]
	v_mfma_f32_16x16x32_bf16 v[84:87], v[132:135], v[216:219], v[84:87]
	v_mfma_f32_16x16x32_bf16 v[112:115], v[162:165], v[188:191], v[112:115]
	v_mfma_f32_16x16x32_bf16 v[112:115], v[172:175], v[192:195], v[112:115]
	v_mfma_f32_16x16x32_bf16 v[104:107], v[176:179], v[188:191], v[104:107]
	v_mfma_f32_16x16x32_bf16 v[104:107], v[184:187], v[192:195], v[104:107]
	v_mfma_f32_16x16x32_bf16 v[88:91], v[176:179], v[196:199], v[88:91]
	v_mfma_f32_16x16x32_bf16 v[88:91], v[184:187], v[200:203], v[88:91]
	v_mfma_f32_16x16x32_bf16 v[96:99], v[162:165], v[196:199], v[96:99]
	v_mfma_f32_16x16x32_bf16 v[96:99], v[172:175], v[200:203], v[96:99]
	v_mfma_f32_16x16x32_bf16 v[80:83], v[162:165], v[204:207], v[80:83]
	v_mfma_f32_16x16x32_bf16 v[80:83], v[172:175], v[208:211], v[80:83]
	v_mfma_f32_16x16x32_bf16 v[72:75], v[176:179], v[204:207], v[72:75]
	v_mfma_f32_16x16x32_bf16 v[72:75], v[184:187], v[208:211], v[72:75]
	v_mfma_f32_16x16x32_bf16 v[64:67], v[176:179], v[212:215], v[64:67]
	v_mfma_f32_16x16x32_bf16 v[64:67], v[184:187], v[216:219], v[64:67]
	v_mfma_f32_16x16x32_bf16 v[68:71], v[162:165], v[212:215], v[68:71]
	v_mfma_f32_16x16x32_bf16 v[68:71], v[172:175], v[216:219], v[68:71]
	s_setprio 0
	s_barrier
	s_add_i32 s14, s80, s63
	s_mov_b32 m0, s14
	ds_read_b128 v[188:191], v171 offset:16384
	ds_read_b128 v[192:195], v171 offset:17408
	ds_read_b128 v[196:199], v171 offset:18432
	ds_read_b128 v[200:203], v171 offset:19456
	ds_read_b128 v[204:207], v171 offset:20480
	ds_read_b128 v[208:211], v171 offset:21504
	ds_read_b128 v[212:215], v171 offset:22528
	ds_read_b128 v[216:219], v171 offset:23552
	global_load_lds_dwordx4 v146, s[56:57]
	s_add_i32 m0, s14, 0x2000
	s_add_u32 s34, s56, 0x40000
	s_addc_u32 s35, s57, 0
	s_add_i32 s14, s81, s63
	global_load_lds_dwordx4 v150, s[56:57]
	s_mov_b32 m0, s14
	s_nop 0
	global_load_lds_dwordx4 v146, s[34:35]
	s_add_i32 m0, s14, 0x2000
	s_nop 0
	global_load_lds_dwordx4 v150, s[34:35]
	s_mov_b32 m0, s64
	s_nop 0
	global_load_lds_dwordx4 v144, s[58:59]
	s_mov_b32 m0, s65
	s_nop 0
	global_load_lds_dwordx4 v148, s[58:59]
	s_waitcnt vmcnt(8)
	s_waitcnt lgkmcnt(0)
	s_barrier
	s_setprio 1
	s_waitcnt lgkmcnt(0)
	v_mfma_f32_16x16x32_bf16 v[60:63], v[128:131], v[188:191], v[60:63]
	v_mfma_f32_16x16x32_bf16 v[60:63], v[132:135], v[192:195], v[60:63]
	v_mfma_f32_16x16x32_bf16 v[56:59], v[136:139], v[188:191], v[56:59]
	v_mfma_f32_16x16x32_bf16 v[56:59], v[140:143], v[192:195], v[56:59]
	v_mfma_f32_16x16x32_bf16 v[44:47], v[136:139], v[196:199], v[44:47]
	v_mfma_f32_16x16x32_bf16 v[44:47], v[140:143], v[200:203], v[44:47]
	v_mfma_f32_16x16x32_bf16 v[48:51], v[128:131], v[196:199], v[48:51]
	v_mfma_f32_16x16x32_bf16 v[48:51], v[132:135], v[200:203], v[48:51]
	v_mfma_f32_16x16x32_bf16 v[36:39], v[128:131], v[204:207], v[36:39]
	v_mfma_f32_16x16x32_bf16 v[36:39], v[132:135], v[208:211], v[36:39]
	v_mfma_f32_16x16x32_bf16 v[28:31], v[136:139], v[204:207], v[28:31]
	v_mfma_f32_16x16x32_bf16 v[28:31], v[140:143], v[208:211], v[28:31]
	v_mfma_f32_16x16x32_bf16 v[12:15], v[136:139], v[212:215], v[12:15]
	v_mfma_f32_16x16x32_bf16 v[12:15], v[140:143], v[216:219], v[12:15]
	v_mfma_f32_16x16x32_bf16 v[20:23], v[128:131], v[212:215], v[20:23]
	v_mfma_f32_16x16x32_bf16 v[20:23], v[132:135], v[216:219], v[20:23]
	v_mfma_f32_16x16x32_bf16 v[52:55], v[162:165], v[188:191], v[52:55]
	v_mfma_f32_16x16x32_bf16 v[52:55], v[172:175], v[192:195], v[52:55]
	v_mfma_f32_16x16x32_bf16 v[40:43], v[176:179], v[188:191], v[40:43]
	v_mfma_f32_16x16x32_bf16 v[40:43], v[184:187], v[192:195], v[40:43]
	v_mfma_f32_16x16x32_bf16 v[24:27], v[176:179], v[196:199], v[24:27]
	v_mfma_f32_16x16x32_bf16 v[24:27], v[184:187], v[200:203], v[24:27]
	v_mfma_f32_16x16x32_bf16 v[32:35], v[162:165], v[196:199], v[32:35]
	v_mfma_f32_16x16x32_bf16 v[32:35], v[172:175], v[200:203], v[32:35]
	v_mfma_f32_16x16x32_bf16 v[16:19], v[162:165], v[204:207], v[16:19]
	v_mfma_f32_16x16x32_bf16 v[16:19], v[172:175], v[208:211], v[16:19]
	v_mfma_f32_16x16x32_bf16 v[8:11], v[176:179], v[204:207], v[8:11]
	v_mfma_f32_16x16x32_bf16 v[8:11], v[184:187], v[208:211], v[8:11]
	v_mfma_f32_16x16x32_bf16 v[0:3], v[176:179], v[212:215], v[0:3]
	v_mfma_f32_16x16x32_bf16 v[0:3], v[184:187], v[216:219], v[0:3]
	v_mfma_f32_16x16x32_bf16 v[4:7], v[162:165], v[212:215], v[4:7]
	v_mfma_f32_16x16x32_bf16 v[4:7], v[172:175], v[216:219], v[4:7]
	s_setprio 0
	s_barrier
; #define PG8_STAGE(bufoff, gbase, voff) do { _Pragma("unroll") for (int _i = 0; _i < 2; ++_i) \
;         __builtin_amdgcn_global_load_lds((const unsigned*)((const char*)(gbase) + (voff)[_i]), (PG8_LAS unsigned*)(lds + (bufoff) + ldsw + _i * 8192), 16, 0, 0); } while (0)
; #define PG8_LDA(dst, b, h) do { _Pragma("unroll") for (int m = 0; m < 4; ++m) _Pragma("unroll") for (int k = 0; k < 2; ++k) dst[m][k] = *(const PG8_LAS bf16x8*)(lds + PG8_SA(b, h) + aoff + m * 2048 + k * 1024); } while (0)
; #define PG8_LDB(dst, b, h) do { _Pragma("unroll") for (int n = 0; n < 2; ++n) _Pragma("unroll") for (int k = 0; k < 2; ++k) dst[n][k] = *(const PG8_LAS bf16x8*)(lds + PG8_SB(b, h) + boff + n * 2048 + k * 1024); } while (0)
; #define PG8_MMA(ai, bj, At, Bt) do { __builtin_amdgcn_s_setprio(1); _Pragma("unroll") for (int m = 0; m < 4; ++m) _Pragma("unroll") for (int n = 0; n < 2; ++n) _Pragma("unroll") for (int k = 0; k < 2; ++k) \
;         acc[ai][bj][m][n] = __builtin_amdgcn_mfma_f32_16x16x32_bf16(Bt[n][k], At[m][k], acc[ai][bj][m][n], 0, 0, 0); __builtin_amdgcn_s_setprio(0); } while (0)
; #define PG8_WAIT_V(n) asm volatile("s_waitcnt vmcnt(" #n ")" ::: "memory")
; #define PG8_WAIT_L(n) asm volatile("s_waitcnt lgkmcnt(" #n ")" ::: "memory")
; #define PG8_BAR __builtin_amdgcn_s_barrier()
; #define PG8_SCHED __builtin_amdgcn_sched_barrier(0)
; template <class Epi, class Sched, bool ALIGN_EPI = false, bool SP2 = false>
; __device__ __forceinline__ void gemm_phase(PG8_LAS unsigned char* lds, const Gemm g, const Sched& S, const Epi& E) {
;     ...
;             PG8_LDB(B0, 1, 0); PG8_LDB(B1, 1, 1); PG8_SCHED; PG8_LDA(At, 1, 0); PG8_STAGE(PG8_SA(0, 1), a2 + hstep, voffA);
;             PG8_WAIT_V(8); PG8_WAIT_L(0); PG8_BAR; PG8_MMA(0, 0, At, B0); PG8_MMA(0, 1, At, B1); PG8_BAR; PG8_SCHED;
;             PG8_LDA(At, 1, 1); PG8_STAGE(PG8_SB(1, 0), b3, voffB); PG8_STAGE(PG8_SB(1, 1), b3 + hstep, voffB); PG8_STAGE(PG8_SA(1, 0), a3, voffA);
;             PG8_WAIT_V(8); PG8_WAIT_L(0); PG8_BAR; PG8_MMA(1, 0, At, B0); PG8_MMA(1, 1, At, B1); PG8_BAR; PG8_SCHED;
	s_add_i32 s14, 0, 0x18000
	s_add_i32 s15, 0, 0x1c000
	v_add_u32_e32 v140, s14, v167
	v_add_u32_e32 v183, s15, v167
	ds_read_b128 v[128:131], v140
	ds_read_b128 v[132:135], v140 offset:1024
	ds_read_b128 v[136:139], v140 offset:2048
	ds_read_b128 v[140:143], v140 offset:3072
	ds_read_b128 v[162:165], v183
	ds_read_b128 v[172:175], v183 offset:1024
	ds_read_b128 v[176:179], v183 offset:2048
	ds_read_b128 v[184:187], v183 offset:3072
	s_add_u32 s34, s58, 0x40000
	s_addc_u32 s35, s59, 0
	s_mov_b32 m0, s66
	ds_read_b128 v[188:191], v171 offset:32768
	ds_read_b128 v[192:195], v171 offset:33792
	ds_read_b128 v[196:199], v171 offset:34816
	ds_read_b128 v[200:203], v171 offset:35840
	ds_read_b128 v[204:207], v171 offset:36864
	ds_read_b128 v[208:211], v171 offset:37888
	ds_read_b128 v[212:215], v171 offset:38912
	ds_read_b128 v[216:219], v171 offset:39936
	global_load_lds_dwordx4 v144, s[34:35]
	s_mov_b32 m0, s67
	s_nop 0
	global_load_lds_dwordx4 v148, s[34:35]
	s_waitcnt vmcnt(8)
	s_waitcnt lgkmcnt(0)
	s_barrier
	s_setprio 1
	s_waitcnt lgkmcnt(0)
	v_mfma_f32_16x16x32_bf16 v[124:127], v[128:131], v[188:191], v[124:127]
	v_mfma_f32_16x16x32_bf16 v[124:127], v[132:135], v[192:195], v[124:127]
	v_mfma_f32_16x16x32_bf16 v[120:123], v[136:139], v[188:191], v[120:123]
	v_mfma_f32_16x16x32_bf16 v[120:123], v[140:143], v[192:195], v[120:123]
	v_mfma_f32_16x16x32_bf16 v[108:111], v[136:139], v[196:199], v[108:111]
	v_mfma_f32_16x16x32_bf16 v[108:111], v[140:143], v[200:203], v[108:111]
	v_mfma_f32_16x16x32_bf16 v[116:119], v[128:131], v[196:199], v[116:119]
	v_mfma_f32_16x16x32_bf16 v[116:119], v[132:135], v[200:203], v[116:119]
	v_mfma_f32_16x16x32_bf16 v[100:103], v[128:131], v[204:207], v[100:103]
	v_mfma_f32_16x16x32_bf16 v[100:103], v[132:135], v[208:211], v[100:103]
	v_mfma_f32_16x16x32_bf16 v[92:95], v[136:139], v[204:207], v[92:95]
	v_mfma_f32_16x16x32_bf16 v[92:95], v[140:143], v[208:211], v[92:95]
	v_mfma_f32_16x16x32_bf16 v[76:79], v[136:139], v[212:215], v[76:79]
	v_mfma_f32_16x16x32_bf16 v[76:79], v[140:143], v[216:219], v[76:79]
	v_mfma_f32_16x16x32_bf16 v[84:87], v[128:131], v[212:215], v[84:87]
	v_mfma_f32_16x16x32_bf16 v[84:87], v[132:135], v[216:219], v[84:87]
	v_mfma_f32_16x16x32_bf16 v[112:115], v[162:165], v[188:191], v[112:115]
	v_mfma_f32_16x16x32_bf16 v[112:115], v[172:175], v[192:195], v[112:115]
	v_mfma_f32_16x16x32_bf16 v[104:107], v[176:179], v[188:191], v[104:107]
	v_mfma_f32_16x16x32_bf16 v[104:107], v[184:187], v[192:195], v[104:107]
	v_mfma_f32_16x16x32_bf16 v[88:91], v[176:179], v[196:199], v[88:91]
	v_mfma_f32_16x16x32_bf16 v[88:91], v[184:187], v[200:203], v[88:91]
	v_mfma_f32_16x16x32_bf16 v[96:99], v[162:165], v[196:199], v[96:99]
	v_mfma_f32_16x16x32_bf16 v[96:99], v[172:175], v[200:203], v[96:99]
	v_mfma_f32_16x16x32_bf16 v[80:83], v[162:165], v[204:207], v[80:83]
	v_mfma_f32_16x16x32_bf16 v[80:83], v[172:175], v[208:211], v[80:83]
	v_mfma_f32_16x16x32_bf16 v[72:75], v[176:179], v[204:207], v[72:75]
	v_mfma_f32_16x16x32_bf16 v[72:75], v[184:187], v[208:211], v[72:75]
	v_mfma_f32_16x16x32_bf16 v[64:67], v[176:179], v[212:215], v[64:67]
	v_mfma_f32_16x16x32_bf16 v[64:67], v[184:187], v[216:219], v[64:67]
	v_mfma_f32_16x16x32_bf16 v[68:71], v[162:165], v[212:215], v[68:71]
	v_mfma_f32_16x16x32_bf16 v[68:71], v[172:175], v[216:219], v[68:71]
	s_setprio 0
	s_barrier
	s_add_i32 s14, s14, s63
	s_add_u32 s98, s56, s36
	s_addc_u32 s99, s57, s37
	s_add_u32 s100, s58, s36
	s_addc_u32 s101, s59, s37
	s_mov_b32 m0, s14
	ds_read_b128 v[188:191], v171 offset:49152
	ds_read_b128 v[192:195], v171 offset:50176
	ds_read_b128 v[196:199], v171 offset:51200
	ds_read_b128 v[200:203], v171 offset:52224
	ds_read_b128 v[204:207], v171 offset:53248
	ds_read_b128 v[208:211], v171 offset:54272
	ds_read_b128 v[212:215], v171 offset:55296
	ds_read_b128 v[216:219], v171 offset:56320
	global_load_lds_dwordx4 v146, s[98:99]
	s_add_i32 m0, s14, 0x2000
	s_add_u32 s34, s56, 0x40080
	s_addc_u32 s35, s57, 0
	s_add_i32 s14, s15, s63
	global_load_lds_dwordx4 v150, s[98:99]
	s_mov_b32 m0, s14
	s_nop 0
	global_load_lds_dwordx4 v146, s[34:35]
	s_add_i32 m0, s14, 0x2000
	s_nop 0
	global_load_lds_dwordx4 v150, s[34:35]
	s_mov_b32 m0, s74
	s_nop 0
	global_load_lds_dwordx4 v144, s[100:101]
	s_mov_b32 m0, s75
	s_nop 0
	global_load_lds_dwordx4 v148, s[100:101]
	s_waitcnt vmcnt(8)
	s_waitcnt lgkmcnt(0)
	s_barrier
	s_setprio 1
	s_waitcnt lgkmcnt(0)
	v_mfma_f32_16x16x32_bf16 v[60:63], v[128:131], v[188:191], v[60:63]
	v_mfma_f32_16x16x32_bf16 v[60:63], v[132:135], v[192:195], v[60:63]
	v_mfma_f32_16x16x32_bf16 v[56:59], v[136:139], v[188:191], v[56:59]
	v_mfma_f32_16x16x32_bf16 v[56:59], v[140:143], v[192:195], v[56:59]
	v_mfma_f32_16x16x32_bf16 v[44:47], v[136:139], v[196:199], v[44:47]
	v_mfma_f32_16x16x32_bf16 v[44:47], v[140:143], v[200:203], v[44:47]
	v_mfma_f32_16x16x32_bf16 v[48:51], v[128:131], v[196:199], v[48:51]
	v_mfma_f32_16x16x32_bf16 v[48:51], v[132:135], v[200:203], v[48:51]
	v_mfma_f32_16x16x32_bf16 v[36:39], v[128:131], v[204:207], v[36:39]
	v_mfma_f32_16x16x32_bf16 v[36:39], v[132:135], v[208:211], v[36:39]
	v_mfma_f32_16x16x32_bf16 v[28:31], v[136:139], v[204:207], v[28:31]
	v_mfma_f32_16x16x32_bf16 v[28:31], v[140:143], v[208:211], v[28:31]
	v_mfma_f32_16x16x32_bf16 v[12:15], v[136:139], v[212:215], v[12:15]
	v_mfma_f32_16x16x32_bf16 v[12:15], v[140:143], v[216:219], v[12:15]
	v_mfma_f32_16x16x32_bf16 v[20:23], v[128:131], v[212:215], v[20:23]
	v_mfma_f32_16x16x32_bf16 v[20:23], v[132:135], v[216:219], v[20:23]
	v_mfma_f32_16x16x32_bf16 v[52:55], v[162:165], v[188:191], v[52:55]
	v_mfma_f32_16x16x32_bf16 v[52:55], v[172:175], v[192:195], v[52:55]
	v_mfma_f32_16x16x32_bf16 v[40:43], v[176:179], v[188:191], v[40:43]
	v_mfma_f32_16x16x32_bf16 v[40:43], v[184:187], v[192:195], v[40:43]
	v_mfma_f32_16x16x32_bf16 v[24:27], v[176:179], v[196:199], v[24:27]
	v_mfma_f32_16x16x32_bf16 v[24:27], v[184:187], v[200:203], v[24:27]
	v_mfma_f32_16x16x32_bf16 v[32:35], v[162:165], v[196:199], v[32:35]
	v_mfma_f32_16x16x32_bf16 v[32:35], v[172:175], v[200:203], v[32:35]
	v_mfma_f32_16x16x32_bf16 v[16:19], v[162:165], v[204:207], v[16:19]
	v_mfma_f32_16x16x32_bf16 v[16:19], v[172:175], v[208:211], v[16:19]
	v_mfma_f32_16x16x32_bf16 v[8:11], v[176:179], v[204:207], v[8:11]
	v_mfma_f32_16x16x32_bf16 v[8:11], v[184:187], v[208:211], v[8:11]
	v_mfma_f32_16x16x32_bf16 v[0:3], v[176:179], v[212:215], v[0:3]
	v_mfma_f32_16x16x32_bf16 v[0:3], v[184:187], v[216:219], v[0:3]
	v_mfma_f32_16x16x32_bf16 v[4:7], v[162:165], v[212:215], v[4:7]
	v_mfma_f32_16x16x32_bf16 v[4:7], v[172:175], v[216:219], v[4:7]
	s_setprio 0
	s_barrier
	s_add_i32 s84, s84, 2
	s_add_u32 s82, s82, 0x100
	s_addc_u32 s83, s83, 0
	s_add_u32 s54, s54, 0x100
	s_addc_u32 s55, s55, 0
	s_cmp_gt_u32 s84, 13
	s_cbranch_scc0 .LBB0_710
	s_and_b64 vcc, exec, s[40:41]
	s_cbranch_vccz .LBB0_713
	s_barrier

; #define PG8_STAGE(bufoff, gbase, voff) do { _Pragma("unroll") for (int _i = 0; _i < 2; ++_i) \
;         __builtin_amdgcn_global_load_lds((const unsigned*)((const char*)(gbase) + (voff)[_i]), (PG8_LAS unsigned*)(lds + (bufoff) + ldsw + _i * 8192), 16, 0, 0); } while (0)
; #define PG8_LDA(dst, b, h) do { _Pragma("unroll") for (int m = 0; m < 4; ++m) _Pragma("unroll") for (int k = 0; k < 2; ++k) dst[m][k] = *(const PG8_LAS bf16x8*)(lds + PG8_SA(b, h) + aoff + m * 2048 + k * 1024); } while (0)
; #define PG8_LDB(dst, b, h) do { _Pragma("unroll") for (int n = 0; n < 2; ++n) _Pragma("unroll") for (int k = 0; k < 2; ++k) dst[n][k] = *(const PG8_LAS bf16x8*)(lds + PG8_SB(b, h) + boff + n * 2048 + k * 1024); } while (0)
; #define PG8_MMA(ai, bj, At, Bt) do { __builtin_amdgcn_s_setprio(1); _Pragma("unroll") for (int m = 0; m < 4; ++m) _Pragma("unroll") for (int n = 0; n < 2; ++n) _Pragma("unroll") for (int k = 0; k < 2; ++k) \
;         acc[ai][bj][m][n] = __builtin_amdgcn_mfma_f32_16x16x32_bf16(Bt[n][k], At[m][k], acc[ai][bj][m][n], 0, 0, 0); __builtin_amdgcn_s_setprio(0); } while (0)
; #define PG8_WAIT_V(n) asm volatile("s_waitcnt vmcnt(" #n ")" ::: "memory")
; #define PG8_WAIT_L(n) asm volatile("s_waitcnt lgkmcnt(" #n ")" ::: "memory")
; #define PG8_BAR __builtin_amdgcn_s_barrier()
; #define PG8_SCHED __builtin_amdgcn_sched_barrier(0)
; template <class Epi, class Sched, bool ALIGN_EPI = false, bool SP2 = false>
; __device__ __forceinline__ void gemm_phase(PG8_LAS unsigned char* lds, const Gemm g, const Sched& S, const Epi& E) {
;     ...
;             PG8_LDB(B0, 0, 0); PG8_LDB(B1, 0, 1); PG8_SCHED; PG8_LDA(At, 0, 0); PG8_STAGE(PG8_SA(1, 1), a1 + hstep, voffA);
;             PG8_WAIT_V(8); PG8_WAIT_L(0); PG8_BAR; PG8_MMA(0, 0, At, B0); PG8_MMA(0, 1, At, B1); PG8_BAR; PG8_SCHED;
;             PG8_LDA(At, 0, 1); PG8_STAGE(PG8_SB(0, 0), b2, voffB); PG8_STAGE(PG8_SB(0, 1), b2 + hstep, voffB); PG8_STAGE(PG8_SA(0, 0), a2, voffA);
;             PG8_WAIT_V(8); PG8_WAIT_L(0); PG8_BAR; PG8_MMA(1, 0, At, B0); PG8_MMA(1, 1, At, B1); PG8_BAR; PG8_SCHED;
.LBB0_796:
	v_add_u32_e32 v130, s76, v165
	ds_read_b128 v[118:121], v130
	ds_read_b128 v[122:125], v130 offset:1024
	ds_read_b128 v[126:129], v130 offset:2048
	ds_read_b128 v[172:175], v130 offset:3072
	v_add_u32_e32 v130, s77, v165
	ds_read_b128 v[176:179], v130
	ds_read_b128 v[184:187], v130 offset:1024
	ds_read_b128 v[188:191], v130 offset:2048
	ds_read_b128 v[192:195], v130 offset:3072
	s_add_u32 s12, s52, 0xfffc0080
	s_addc_u32 s13, s53, -1
	s_and_b64 s[34:35], s[54:55], exec
	s_cselect_b32 s57, s43, s13
	s_cselect_b32 s56, s78, s12
	s_cselect_b32 s55, s41, s51
	s_cselect_b32 s54, s79, s49
	s_add_i32 m0, s62, 0xc000
	ds_read_b128 v[196:199], v170
	ds_read_b128 v[200:203], v170 offset:1024
	ds_read_b128 v[204:207], v170 offset:2048
	ds_read_b128 v[208:211], v170 offset:3072
	ds_read_b128 v[212:215], v170 offset:4096
	ds_read_b128 v[216:219], v170 offset:5120
	ds_read_b128 v[220:223], v170 offset:6144
	ds_read_b128 v[224:227], v170 offset:7168
	global_load_lds_dwordx4 v154, s[52:53]
	s_add_i32 m0, s62, 0xe000
	s_nop 0
	global_load_lds_dwordx4 v152, s[52:53]
	s_waitcnt vmcnt(8)
	s_waitcnt lgkmcnt(0)
	s_barrier
	s_setprio 1
	s_waitcnt lgkmcnt(0)
	v_mfma_f32_16x16x32_bf16 v[140:143], v[118:121], v[196:199], v[140:143]
	v_mfma_f32_16x16x32_bf16 v[140:143], v[122:125], v[200:203], v[140:143]
	v_mfma_f32_16x16x32_bf16 v[136:139], v[126:129], v[196:199], v[136:139]
	v_mfma_f32_16x16x32_bf16 v[136:139], v[172:175], v[200:203], v[136:139]
	v_mfma_f32_16x16x32_bf16 v[104:107], v[126:129], v[204:207], v[104:107]
	v_mfma_f32_16x16x32_bf16 v[104:107], v[172:175], v[208:211], v[104:107]
	v_mfma_f32_16x16x32_bf16 v[108:111], v[118:121], v[204:207], v[108:111]
	v_mfma_f32_16x16x32_bf16 v[108:111], v[122:125], v[208:211], v[108:111]
	v_mfma_f32_16x16x32_bf16 v[92:95], v[118:121], v[212:215], v[92:95]
	v_mfma_f32_16x16x32_bf16 v[92:95], v[122:125], v[216:219], v[92:95]
	v_mfma_f32_16x16x32_bf16 v[88:91], v[126:129], v[212:215], v[88:91]
	v_mfma_f32_16x16x32_bf16 v[88:91], v[172:175], v[216:219], v[88:91]
	v_mfma_f32_16x16x32_bf16 v[72:75], v[126:129], v[220:223], v[72:75]
	v_mfma_f32_16x16x32_bf16 v[72:75], v[172:175], v[224:227], v[72:75]
	v_mfma_f32_16x16x32_bf16 v[76:79], v[118:121], v[220:223], v[76:79]
	v_mfma_f32_16x16x32_bf16 v[76:79], v[122:125], v[224:227], v[76:79]
	v_mfma_f32_16x16x32_bf16 v[130:133], v[176:179], v[196:199], v[132:135]
	v_mfma_f32_16x16x32_bf16 v[130:133], v[184:187], v[200:203], v[130:133]
	v_mfma_f32_16x16x32_bf16 v[112:115], v[188:191], v[196:199], v[112:115]
	v_mfma_f32_16x16x32_bf16 v[112:115], v[192:195], v[200:203], v[112:115]
	v_mfma_f32_16x16x32_bf16 v[96:99], v[188:191], v[204:207], v[96:99]
	v_mfma_f32_16x16x32_bf16 v[96:99], v[192:195], v[208:211], v[96:99]
	v_mfma_f32_16x16x32_bf16 v[100:103], v[176:179], v[204:207], v[100:103]
	v_mfma_f32_16x16x32_bf16 v[100:103], v[184:187], v[208:211], v[100:103]
	v_mfma_f32_16x16x32_bf16 v[84:87], v[176:179], v[212:215], v[84:87]
	v_mfma_f32_16x16x32_bf16 v[84:87], v[184:187], v[216:219], v[84:87]
	v_mfma_f32_16x16x32_bf16 v[80:83], v[188:191], v[212:215], v[80:83]
	v_mfma_f32_16x16x32_bf16 v[80:83], v[192:195], v[216:219], v[80:83]
	v_mfma_f32_16x16x32_bf16 v[64:67], v[188:191], v[220:223], v[64:67]
	v_mfma_f32_16x16x32_bf16 v[64:67], v[192:195], v[224:227], v[64:67]
	v_mfma_f32_16x16x32_bf16 v[68:71], v[176:179], v[220:223], v[68:71]
	v_mfma_f32_16x16x32_bf16 v[68:71], v[184:187], v[224:227], v[68:71]
	s_setprio 0
	s_barrier
	s_add_i32 s12, s76, s59
	s_mov_b32 m0, s12
	ds_read_b128 v[196:199], v170 offset:16384
	ds_read_b128 v[200:203], v170 offset:17408
	ds_read_b128 v[204:207], v170 offset:18432
	ds_read_b128 v[208:211], v170 offset:19456
	ds_read_b128 v[212:215], v170 offset:20480
	ds_read_b128 v[216:219], v170 offset:21504
	ds_read_b128 v[220:223], v170 offset:22528
	ds_read_b128 v[224:227], v170 offset:23552
	global_load_lds_dwordx4 v148, s[54:55]
	s_add_i32 m0, s12, 0x2000
	s_add_u32 s34, s54, 0x40000
	s_addc_u32 s35, s55, 0
	s_add_i32 s12, s77, s59
	global_load_lds_dwordx4 v144, s[54:55]
	s_mov_b32 m0, s12
	s_nop 0
	global_load_lds_dwordx4 v148, s[34:35]
	s_add_i32 m0, s12, 0x2000
	s_nop 0
	global_load_lds_dwordx4 v144, s[34:35]
	s_mov_b32 m0, s62
	s_nop 0
	global_load_lds_dwordx4 v150, s[56:57]
	s_mov_b32 m0, s63
	s_nop 0
	global_load_lds_dwordx4 v146, s[56:57]
	s_waitcnt vmcnt(8)
	s_waitcnt lgkmcnt(0)
	s_barrier
	s_setprio 1
	s_waitcnt lgkmcnt(0)
	v_mfma_f32_16x16x32_bf16 v[60:63], v[118:121], v[196:199], v[60:63]
	v_mfma_f32_16x16x32_bf16 v[60:63], v[122:125], v[200:203], v[60:63]
	v_mfma_f32_16x16x32_bf16 v[56:59], v[126:129], v[196:199], v[56:59]
	v_mfma_f32_16x16x32_bf16 v[56:59], v[172:175], v[200:203], v[56:59]
	v_mfma_f32_16x16x32_bf16 v[40:43], v[126:129], v[204:207], v[40:43]
	v_mfma_f32_16x16x32_bf16 v[40:43], v[172:175], v[208:211], v[40:43]
	v_mfma_f32_16x16x32_bf16 v[44:47], v[118:121], v[204:207], v[44:47]
	v_mfma_f32_16x16x32_bf16 v[44:47], v[122:125], v[208:211], v[44:47]
	v_mfma_f32_16x16x32_bf16 v[28:31], v[118:121], v[212:215], v[28:31]
	v_mfma_f32_16x16x32_bf16 v[28:31], v[122:125], v[216:219], v[28:31]
	v_mfma_f32_16x16x32_bf16 v[24:27], v[126:129], v[212:215], v[24:27]
	v_mfma_f32_16x16x32_bf16 v[24:27], v[172:175], v[216:219], v[24:27]
	v_mfma_f32_16x16x32_bf16 v[8:11], v[126:129], v[220:223], v[8:11]
	v_mfma_f32_16x16x32_bf16 v[8:11], v[172:175], v[224:227], v[8:11]
	v_mfma_f32_16x16x32_bf16 v[12:15], v[118:121], v[220:223], v[12:15]
	v_mfma_f32_16x16x32_bf16 v[12:15], v[122:125], v[224:227], v[12:15]
	v_mfma_f32_16x16x32_bf16 v[52:55], v[176:179], v[196:199], v[52:55]
	v_mfma_f32_16x16x32_bf16 v[52:55], v[184:187], v[200:203], v[52:55]
	v_mfma_f32_16x16x32_bf16 v[48:51], v[188:191], v[196:199], v[48:51]
	v_mfma_f32_16x16x32_bf16 v[48:51], v[192:195], v[200:203], v[48:51]
	v_mfma_f32_16x16x32_bf16 v[32:35], v[188:191], v[204:207], v[32:35]
	v_mfma_f32_16x16x32_bf16 v[32:35], v[192:195], v[208:211], v[32:35]
	v_mfma_f32_16x16x32_bf16 v[36:39], v[176:179], v[204:207], v[36:39]
	v_mfma_f32_16x16x32_bf16 v[36:39], v[184:187], v[208:211], v[36:39]
	v_mfma_f32_16x16x32_bf16 v[20:23], v[176:179], v[212:215], v[20:23]
	v_mfma_f32_16x16x32_bf16 v[20:23], v[184:187], v[216:219], v[20:23]
	v_mfma_f32_16x16x32_bf16 v[16:19], v[188:191], v[212:215], v[16:19]
	v_mfma_f32_16x16x32_bf16 v[16:19], v[192:195], v[216:219], v[16:19]
	v_mfma_f32_16x16x32_bf16 v[0:3], v[188:191], v[220:223], v[0:3]
	v_mfma_f32_16x16x32_bf16 v[0:3], v[192:195], v[224:227], v[0:3]
	v_mfma_f32_16x16x32_bf16 v[4:7], v[176:179], v[220:223], v[4:7]
	v_mfma_f32_16x16x32_bf16 v[4:7], v[184:187], v[224:227], v[4:7]
	s_setprio 0
	s_barrier
; #define PG8_STAGE(bufoff, gbase, voff) do { _Pragma("unroll") for (int _i = 0; _i < 2; ++_i) \
;         __builtin_amdgcn_global_load_lds((const unsigned*)((const char*)(gbase) + (voff)[_i]), (PG8_LAS unsigned*)(lds + (bufoff) + ldsw + _i * 8192), 16, 0, 0); } while (0)
; #define PG8_LDA(dst, b, h) do { _Pragma("unroll") for (int m = 0; m < 4; ++m) _Pragma("unroll") for (int k = 0; k < 2; ++k) dst[m][k] = *(const PG8_LAS bf16x8*)(lds + PG8_SA(b, h) + aoff + m * 2048 + k * 1024); } while (0)
; #define PG8_LDB(dst, b, h) do { _Pragma("unroll") for (int n = 0; n < 2; ++n) _Pragma("unroll") for (int k = 0; k < 2; ++k) dst[n][k] = *(const PG8_LAS bf16x8*)(lds + PG8_SB(b, h) + boff + n * 2048 + k * 1024); } while (0)
; #define PG8_MMA(ai, bj, At, Bt) do { __builtin_amdgcn_s_setprio(1); _Pragma("unroll") for (int m = 0; m < 4; ++m) _Pragma("unroll") for (int n = 0; n < 2; ++n) _Pragma("unroll") for (int k = 0; k < 2; ++k) \
;         acc[ai][bj][m][n] = __builtin_amdgcn_mfma_f32_16x16x32_bf16(Bt[n][k], At[m][k], acc[ai][bj][m][n], 0, 0, 0); __builtin_amdgcn_s_setprio(0); } while (0)
; #define PG8_WAIT_V(n) asm volatile("s_waitcnt vmcnt(" #n ")" ::: "memory")
; #define PG8_WAIT_L(n) asm volatile("s_waitcnt lgkmcnt(" #n ")" ::: "memory")
; #define PG8_BAR __builtin_amdgcn_s_barrier()
; #define PG8_SCHED __builtin_amdgcn_sched_barrier(0)
; template <class Epi, class Sched, bool ALIGN_EPI = false, bool SP2 = false>
; __device__ __forceinline__ void gemm_phase(PG8_LAS unsigned char* lds, const Gemm g, const Sched& S, const Epi& E) {
;     ...
;             PG8_LDB(B0, 1, 0); PG8_LDB(B1, 1, 1); PG8_SCHED; PG8_LDA(At, 1, 0); PG8_STAGE(PG8_SA(0, 1), a2 + hstep, voffA);
;             PG8_WAIT_V(8); PG8_WAIT_L(0); PG8_BAR; PG8_MMA(0, 0, At, B0); PG8_MMA(0, 1, At, B1); PG8_BAR; PG8_SCHED;
;             PG8_LDA(At, 1, 1); PG8_STAGE(PG8_SB(1, 0), b3, voffB); PG8_STAGE(PG8_SB(1, 1), b3 + hstep, voffB); PG8_STAGE(PG8_SA(1, 0), a3, voffA);
;             PG8_WAIT_V(8); PG8_WAIT_L(0); PG8_BAR; PG8_MMA(1, 0, At, B0); PG8_MMA(1, 1, At, B1); PG8_BAR; PG8_SCHED;
	s_add_i32 s12, 0, 0x18000
	v_add_u32_e32 v134, s12, v165
	s_add_i32 s13, 0, 0x1c000
	ds_read_b128 v[118:121], v134
	ds_read_b128 v[122:125], v134 offset:1024
	ds_read_b128 v[126:129], v134 offset:2048
	ds_read_b128 v[172:175], v134 offset:3072
	v_add_u32_e32 v134, s13, v165
	ds_read_b128 v[176:179], v134
	ds_read_b128 v[184:187], v134 offset:1024
	ds_read_b128 v[188:191], v134 offset:2048
	ds_read_b128 v[192:195], v134 offset:3072
	s_add_u32 s34, s56, 0x40000
	s_addc_u32 s35, s57, 0
	s_mov_b32 m0, s64
	ds_read_b128 v[196:199], v170 offset:32768
	ds_read_b128 v[200:203], v170 offset:33792
	ds_read_b128 v[204:207], v170 offset:34816
	ds_read_b128 v[208:211], v170 offset:35840
	ds_read_b128 v[212:215], v170 offset:36864
	ds_read_b128 v[216:219], v170 offset:37888
	ds_read_b128 v[220:223], v170 offset:38912
	ds_read_b128 v[224:227], v170 offset:39936
	global_load_lds_dwordx4 v150, s[34:35]
	s_mov_b32 m0, s65
	s_nop 0
	global_load_lds_dwordx4 v146, s[34:35]
	s_waitcnt vmcnt(8)
	s_waitcnt lgkmcnt(0)
	s_barrier
	s_setprio 1
	s_waitcnt lgkmcnt(0)
	v_mfma_f32_16x16x32_bf16 v[140:143], v[118:121], v[196:199], v[140:143]
	v_mfma_f32_16x16x32_bf16 v[140:143], v[122:125], v[200:203], v[140:143]
	v_mfma_f32_16x16x32_bf16 v[134:137], v[126:129], v[196:199], v[136:139]
	v_mfma_f32_16x16x32_bf16 v[136:139], v[172:175], v[200:203], v[134:137]
	v_mfma_f32_16x16x32_bf16 v[104:107], v[126:129], v[204:207], v[104:107]
	v_mfma_f32_16x16x32_bf16 v[104:107], v[172:175], v[208:211], v[104:107]
	v_mfma_f32_16x16x32_bf16 v[108:111], v[118:121], v[204:207], v[108:111]
	v_mfma_f32_16x16x32_bf16 v[108:111], v[122:125], v[208:211], v[108:111]
	v_mfma_f32_16x16x32_bf16 v[92:95], v[118:121], v[212:215], v[92:95]
	v_mfma_f32_16x16x32_bf16 v[92:95], v[122:125], v[216:219], v[92:95]
	v_mfma_f32_16x16x32_bf16 v[88:91], v[126:129], v[212:215], v[88:91]
	v_mfma_f32_16x16x32_bf16 v[88:91], v[172:175], v[216:219], v[88:91]
	v_mfma_f32_16x16x32_bf16 v[72:75], v[126:129], v[220:223], v[72:75]
	v_mfma_f32_16x16x32_bf16 v[72:75], v[172:175], v[224:227], v[72:75]
	v_mfma_f32_16x16x32_bf16 v[76:79], v[118:121], v[220:223], v[76:79]
	v_mfma_f32_16x16x32_bf16 v[76:79], v[122:125], v[224:227], v[76:79]
	v_mfma_f32_16x16x32_bf16 v[130:133], v[176:179], v[196:199], v[130:133]
	v_mfma_f32_16x16x32_bf16 v[132:135], v[184:187], v[200:203], v[130:133]
	v_mfma_f32_16x16x32_bf16 v[112:115], v[188:191], v[196:199], v[112:115]
	v_mfma_f32_16x16x32_bf16 v[112:115], v[192:195], v[200:203], v[112:115]
	v_mfma_f32_16x16x32_bf16 v[96:99], v[188:191], v[204:207], v[96:99]
	v_mfma_f32_16x16x32_bf16 v[96:99], v[192:195], v[208:211], v[96:99]
	v_mfma_f32_16x16x32_bf16 v[100:103], v[176:179], v[204:207], v[100:103]
	v_mfma_f32_16x16x32_bf16 v[100:103], v[184:187], v[208:211], v[100:103]
	v_mfma_f32_16x16x32_bf16 v[84:87], v[176:179], v[212:215], v[84:87]
	v_mfma_f32_16x16x32_bf16 v[84:87], v[184:187], v[216:219], v[84:87]
	v_mfma_f32_16x16x32_bf16 v[80:83], v[188:191], v[212:215], v[80:83]
	v_mfma_f32_16x16x32_bf16 v[80:83], v[192:195], v[216:219], v[80:83]
	v_mfma_f32_16x16x32_bf16 v[64:67], v[188:191], v[220:223], v[64:67]
	v_mfma_f32_16x16x32_bf16 v[64:67], v[192:195], v[224:227], v[64:67]
	v_mfma_f32_16x16x32_bf16 v[68:71], v[176:179], v[220:223], v[68:71]
	v_mfma_f32_16x16x32_bf16 v[68:71], v[184:187], v[224:227], v[68:71]
	s_setprio 0
	s_barrier
	s_add_i32 s12, s12, s59
	s_add_u32 s98, s54, s18
	s_addc_u32 s99, s55, s19
	s_add_u32 s100, s56, s18
	s_addc_u32 s101, s57, s19
	s_mov_b32 m0, s12
	ds_read_b128 v[196:199], v170 offset:49152
	ds_read_b128 v[200:203], v170 offset:50176
	ds_read_b128 v[204:207], v170 offset:51200
	ds_read_b128 v[208:211], v170 offset:52224
	ds_read_b128 v[212:215], v170 offset:53248
	ds_read_b128 v[216:219], v170 offset:54272
	ds_read_b128 v[220:223], v170 offset:55296
	ds_read_b128 v[224:227], v170 offset:56320
	global_load_lds_dwordx4 v148, s[98:99]
	s_add_i32 m0, s12, 0x2000
	s_add_u32 s34, s54, 0x40080
	s_addc_u32 s35, s55, 0
	s_add_i32 s12, s13, s59
	global_load_lds_dwordx4 v144, s[98:99]
	s_mov_b32 m0, s12
	s_nop 0
	global_load_lds_dwordx4 v148, s[34:35]
	s_add_i32 m0, s12, 0x2000
	s_nop 0
	global_load_lds_dwordx4 v144, s[34:35]
	s_mov_b32 m0, s68
	s_nop 0
	global_load_lds_dwordx4 v150, s[100:101]
	s_mov_b32 m0, s69
	s_nop 0
	global_load_lds_dwordx4 v146, s[100:101]
	s_waitcnt vmcnt(8)
	s_waitcnt lgkmcnt(0)
	s_barrier
	s_setprio 1
	s_waitcnt lgkmcnt(0)
	v_mfma_f32_16x16x32_bf16 v[60:63], v[118:121], v[196:199], v[60:63]
	v_mfma_f32_16x16x32_bf16 v[60:63], v[122:125], v[200:203], v[60:63]
	v_mfma_f32_16x16x32_bf16 v[56:59], v[126:129], v[196:199], v[56:59]
	v_mfma_f32_16x16x32_bf16 v[56:59], v[172:175], v[200:203], v[56:59]
	v_mfma_f32_16x16x32_bf16 v[40:43], v[126:129], v[204:207], v[40:43]
	v_mfma_f32_16x16x32_bf16 v[40:43], v[172:175], v[208:211], v[40:43]
	v_mfma_f32_16x16x32_bf16 v[44:47], v[118:121], v[204:207], v[44:47]
	v_mfma_f32_16x16x32_bf16 v[44:47], v[122:125], v[208:211], v[44:47]
	v_mfma_f32_16x16x32_bf16 v[28:31], v[118:121], v[212:215], v[28:31]
	v_mfma_f32_16x16x32_bf16 v[28:31], v[122:125], v[216:219], v[28:31]
	v_mfma_f32_16x16x32_bf16 v[24:27], v[126:129], v[212:215], v[24:27]
	v_mfma_f32_16x16x32_bf16 v[24:27], v[172:175], v[216:219], v[24:27]
	v_mfma_f32_16x16x32_bf16 v[8:11], v[126:129], v[220:223], v[8:11]
	v_mfma_f32_16x16x32_bf16 v[8:11], v[172:175], v[224:227], v[8:11]
	v_mfma_f32_16x16x32_bf16 v[12:15], v[118:121], v[220:223], v[12:15]
	v_mfma_f32_16x16x32_bf16 v[12:15], v[122:125], v[224:227], v[12:15]
	v_mfma_f32_16x16x32_bf16 v[52:55], v[176:179], v[196:199], v[52:55]
	v_mfma_f32_16x16x32_bf16 v[52:55], v[184:187], v[200:203], v[52:55]
	v_mfma_f32_16x16x32_bf16 v[48:51], v[188:191], v[196:199], v[48:51]
	v_mfma_f32_16x16x32_bf16 v[48:51], v[192:195], v[200:203], v[48:51]
	v_mfma_f32_16x16x32_bf16 v[32:35], v[188:191], v[204:207], v[32:35]
	v_mfma_f32_16x16x32_bf16 v[32:35], v[192:195], v[208:211], v[32:35]
	v_mfma_f32_16x16x32_bf16 v[36:39], v[176:179], v[204:207], v[36:39]
	v_mfma_f32_16x16x32_bf16 v[36:39], v[184:187], v[208:211], v[36:39]
	v_mfma_f32_16x16x32_bf16 v[20:23], v[176:179], v[212:215], v[20:23]
	v_mfma_f32_16x16x32_bf16 v[20:23], v[184:187], v[216:219], v[20:23]
	v_mfma_f32_16x16x32_bf16 v[16:19], v[188:191], v[212:215], v[16:19]
	v_mfma_f32_16x16x32_bf16 v[16:19], v[192:195], v[216:219], v[16:19]
	v_mfma_f32_16x16x32_bf16 v[0:3], v[188:191], v[220:223], v[0:3]
	v_mfma_f32_16x16x32_bf16 v[0:3], v[192:195], v[224:227], v[0:3]
	v_mfma_f32_16x16x32_bf16 v[4:7], v[176:179], v[220:223], v[4:7]
	v_mfma_f32_16x16x32_bf16 v[4:7], v[184:187], v[224:227], v[4:7]
	s_setprio 0
	s_barrier
	s_add_i32 s80, s80, 2
	s_add_u32 s49, s49, 0x100
	s_addc_u32 s51, s51, 0
	s_add_u32 s52, s52, 0x100
	s_addc_u32 s53, s53, 0
	s_cmp_gt_u32 s80, 13
	s_cbranch_scc1 .LBB0_799

; #define PG8_STAGE(bufoff, gbase, voff) do { _Pragma("unroll") for (int _i = 0; _i < 2; ++_i) \
;         __builtin_amdgcn_global_load_lds((const unsigned*)((const char*)(gbase) + (voff)[_i]), (PG8_LAS unsigned*)(lds + (bufoff) + ldsw + _i * 8192), 16, 0, 0); } while (0)
; #define PG8_LDA(dst, b, h) do { _Pragma("unroll") for (int m = 0; m < 4; ++m) _Pragma("unroll") for (int k = 0; k < 2; ++k) dst[m][k] = *(const PG8_LAS bf16x8*)(lds + PG8_SA(b, h) + aoff + m * 2048 + k * 1024); } while (0)
; #define PG8_LDB(dst, b, h) do { _Pragma("unroll") for (int n = 0; n < 2; ++n) _Pragma("unroll") for (int k = 0; k < 2; ++k) dst[n][k] = *(const PG8_LAS bf16x8*)(lds + PG8_SB(b, h) + boff + n * 2048 + k * 1024); } while (0)
; #define PG8_MMA(ai, bj, At, Bt) do { __builtin_amdgcn_s_setprio(1); _Pragma("unroll") for (int m = 0; m < 4; ++m) _Pragma("unroll") for (int n = 0; n < 2; ++n) _Pragma("unroll") for (int k = 0; k < 2; ++k) \
;         acc[ai][bj][m][n] = __builtin_amdgcn_mfma_f32_16x16x32_bf16(Bt[n][k], At[m][k], acc[ai][bj][m][n], 0, 0, 0); __builtin_amdgcn_s_setprio(0); } while (0)
; #define PG8_WAIT_V(n) asm volatile("s_waitcnt vmcnt(" #n ")" ::: "memory")
; #define PG8_WAIT_L(n) asm volatile("s_waitcnt lgkmcnt(" #n ")" ::: "memory")
; #define PG8_BAR __builtin_amdgcn_s_barrier()
; #define PG8_SCHED __builtin_amdgcn_sched_barrier(0)
; template <class Epi, class Sched, bool ALIGN_EPI = false, bool SP2 = false>
; __device__ __forceinline__ void gemm_phase(PG8_LAS unsigned char* lds, const Gemm g, const Sched& S, const Epi& E) {
;     ...
;             PG8_LDB(B0, 0, 0); PG8_LDB(B1, 0, 1); PG8_SCHED; PG8_LDA(At, 0, 0); PG8_STAGE(PG8_SA(1, 1), a1 + hstep, voffA);
;             PG8_WAIT_V(8); PG8_WAIT_L(0); PG8_BAR; PG8_MMA(0, 0, At, B0); PG8_MMA(0, 1, At, B1); PG8_BAR; PG8_SCHED;
;             PG8_LDA(At, 0, 1); PG8_STAGE(PG8_SB(0, 0), b2, voffB); PG8_STAGE(PG8_SB(0, 1), b2 + hstep, voffB); PG8_STAGE(PG8_SA(0, 0), a2, voffA);
;             PG8_WAIT_V(8); PG8_WAIT_L(0); PG8_BAR; PG8_MMA(1, 0, At, B0); PG8_MMA(1, 1, At, B1); PG8_BAR; PG8_SCHED;
.LBB0_872:
	ds_read_b128 v[128:131], v169
	ds_read_b128 v[132:135], v169 offset:1024
	ds_read_b128 v[136:139], v169 offset:2048
	ds_read_b128 v[140:143], v169 offset:3072
	ds_read_b128 v[162:165], v170
	ds_read_b128 v[172:175], v170 offset:1024
	ds_read_b128 v[176:179], v170 offset:2048
	ds_read_b128 v[184:187], v170 offset:3072
	s_add_u32 s42, s40, 0x100
	s_addc_u32 s43, s41, 0
	s_cmp_eq_u32 s74, 40
	s_cselect_b32 s47, s11, s43
	s_cselect_b32 s46, s10, s42
	s_cselect_b32 s45, s37, s73
	s_cselect_b32 s44, s36, s71
	v_lshl_add_u64 v[180:181], s[40:41], 0, v[154:155]
	s_add_i32 m0, s50, 0xc000
	ds_read_b128 v[188:191], v171
	ds_read_b128 v[192:195], v171 offset:1024
	ds_read_b128 v[196:199], v171 offset:2048
	ds_read_b128 v[200:203], v171 offset:3072
	ds_read_b128 v[204:207], v171 offset:4096
	ds_read_b128 v[208:211], v171 offset:5120
	ds_read_b128 v[212:215], v171 offset:6144
	ds_read_b128 v[216:219], v171 offset:7168
	global_load_lds_dwordx4 v[180:181], off
	v_lshl_add_u64 v[180:181], s[40:41], 0, v[152:153]
	s_add_i32 m0, s50, 0xe000
	s_nop 0
	global_load_lds_dwordx4 v[180:181], off
	s_waitcnt vmcnt(8)
	s_waitcnt lgkmcnt(0)
	s_barrier
	s_setprio 1
	s_waitcnt lgkmcnt(0)
	v_mfma_f32_16x16x32_bf16 v[124:127], v[128:131], v[188:191], v[124:127]
	v_mfma_f32_16x16x32_bf16 v[124:127], v[132:135], v[192:195], v[124:127]
	v_mfma_f32_16x16x32_bf16 v[120:123], v[136:139], v[188:191], v[120:123]
	v_mfma_f32_16x16x32_bf16 v[120:123], v[140:143], v[192:195], v[120:123]
	v_mfma_f32_16x16x32_bf16 v[108:111], v[136:139], v[196:199], v[108:111]
	v_mfma_f32_16x16x32_bf16 v[108:111], v[140:143], v[200:203], v[108:111]
	v_mfma_f32_16x16x32_bf16 v[116:119], v[128:131], v[196:199], v[116:119]
	v_mfma_f32_16x16x32_bf16 v[116:119], v[132:135], v[200:203], v[116:119]
	v_mfma_f32_16x16x32_bf16 v[100:103], v[128:131], v[204:207], v[100:103]
	v_mfma_f32_16x16x32_bf16 v[100:103], v[132:135], v[208:211], v[100:103]
	v_mfma_f32_16x16x32_bf16 v[92:95], v[136:139], v[204:207], v[92:95]
	v_mfma_f32_16x16x32_bf16 v[92:95], v[140:143], v[208:211], v[92:95]
	v_mfma_f32_16x16x32_bf16 v[76:79], v[136:139], v[212:215], v[76:79]
	v_mfma_f32_16x16x32_bf16 v[76:79], v[140:143], v[216:219], v[76:79]
	v_mfma_f32_16x16x32_bf16 v[84:87], v[128:131], v[212:215], v[84:87]
	v_mfma_f32_16x16x32_bf16 v[84:87], v[132:135], v[216:219], v[84:87]
	v_mfma_f32_16x16x32_bf16 v[112:115], v[162:165], v[188:191], v[112:115]
	v_mfma_f32_16x16x32_bf16 v[112:115], v[172:175], v[192:195], v[112:115]
	v_mfma_f32_16x16x32_bf16 v[104:107], v[176:179], v[188:191], v[104:107]
	v_mfma_f32_16x16x32_bf16 v[104:107], v[184:187], v[192:195], v[104:107]
	v_mfma_f32_16x16x32_bf16 v[88:91], v[176:179], v[196:199], v[88:91]
	v_mfma_f32_16x16x32_bf16 v[88:91], v[184:187], v[200:203], v[88:91]
	v_mfma_f32_16x16x32_bf16 v[96:99], v[162:165], v[196:199], v[96:99]
	v_mfma_f32_16x16x32_bf16 v[96:99], v[172:175], v[200:203], v[96:99]
	v_mfma_f32_16x16x32_bf16 v[80:83], v[162:165], v[204:207], v[80:83]
	v_mfma_f32_16x16x32_bf16 v[80:83], v[172:175], v[208:211], v[80:83]
	v_mfma_f32_16x16x32_bf16 v[72:75], v[176:179], v[204:207], v[72:75]
	v_mfma_f32_16x16x32_bf16 v[72:75], v[184:187], v[208:211], v[72:75]
	v_mfma_f32_16x16x32_bf16 v[64:67], v[176:179], v[212:215], v[64:67]
	v_mfma_f32_16x16x32_bf16 v[64:67], v[184:187], v[216:219], v[64:67]
	v_mfma_f32_16x16x32_bf16 v[68:71], v[162:165], v[212:215], v[68:71]
	v_mfma_f32_16x16x32_bf16 v[68:71], v[172:175], v[216:219], v[68:71]
	s_setprio 0
	s_barrier
	s_add_i32 s12, s65, s49
	s_mov_b32 m0, s12
	ds_read_b128 v[188:191], v171 offset:16384
	ds_read_b128 v[192:195], v171 offset:17408
	ds_read_b128 v[196:199], v171 offset:18432
	ds_read_b128 v[200:203], v171 offset:19456
	ds_read_b128 v[204:207], v171 offset:20480
	ds_read_b128 v[208:211], v171 offset:21504
	ds_read_b128 v[212:215], v171 offset:22528
	ds_read_b128 v[216:219], v171 offset:23552
	global_load_lds_dwordx4 v146, s[44:45]
	s_add_i32 m0, s12, 0x2000
	s_add_u32 s40, s44, 0xb0000
	s_addc_u32 s41, s45, 0
	s_add_i32 s12, s66, s49
	global_load_lds_dwordx4 v150, s[44:45]
	s_mov_b32 m0, s12
	s_nop 0
	global_load_lds_dwordx4 v146, s[40:41]
	s_add_i32 m0, s12, 0x2000
	s_nop 0
	global_load_lds_dwordx4 v150, s[40:41]
	s_mov_b32 m0, s50
	s_nop 0
	global_load_lds_dwordx4 v144, s[46:47]
	s_mov_b32 m0, s51
	s_nop 0
	global_load_lds_dwordx4 v148, s[46:47]
	s_waitcnt vmcnt(8)
	s_waitcnt lgkmcnt(0)
	s_barrier
	s_setprio 1
	s_waitcnt lgkmcnt(0)
	v_mfma_f32_16x16x32_bf16 v[60:63], v[128:131], v[188:191], v[60:63]
	v_mfma_f32_16x16x32_bf16 v[60:63], v[132:135], v[192:195], v[60:63]
	v_mfma_f32_16x16x32_bf16 v[56:59], v[136:139], v[188:191], v[56:59]
	v_mfma_f32_16x16x32_bf16 v[56:59], v[140:143], v[192:195], v[56:59]
	v_mfma_f32_16x16x32_bf16 v[44:47], v[136:139], v[196:199], v[44:47]
	v_mfma_f32_16x16x32_bf16 v[44:47], v[140:143], v[200:203], v[44:47]
	v_mfma_f32_16x16x32_bf16 v[48:51], v[128:131], v[196:199], v[48:51]
	v_mfma_f32_16x16x32_bf16 v[48:51], v[132:135], v[200:203], v[48:51]
	v_mfma_f32_16x16x32_bf16 v[36:39], v[128:131], v[204:207], v[36:39]
	v_mfma_f32_16x16x32_bf16 v[36:39], v[132:135], v[208:211], v[36:39]
	v_mfma_f32_16x16x32_bf16 v[28:31], v[136:139], v[204:207], v[28:31]
	v_mfma_f32_16x16x32_bf16 v[28:31], v[140:143], v[208:211], v[28:31]
	v_mfma_f32_16x16x32_bf16 v[12:15], v[136:139], v[212:215], v[12:15]
	v_mfma_f32_16x16x32_bf16 v[12:15], v[140:143], v[216:219], v[12:15]
	v_mfma_f32_16x16x32_bf16 v[20:23], v[128:131], v[212:215], v[20:23]
	v_mfma_f32_16x16x32_bf16 v[20:23], v[132:135], v[216:219], v[20:23]
	v_mfma_f32_16x16x32_bf16 v[52:55], v[162:165], v[188:191], v[52:55]
	v_mfma_f32_16x16x32_bf16 v[52:55], v[172:175], v[192:195], v[52:55]
	v_mfma_f32_16x16x32_bf16 v[40:43], v[176:179], v[188:191], v[40:43]
	v_mfma_f32_16x16x32_bf16 v[40:43], v[184:187], v[192:195], v[40:43]
	v_mfma_f32_16x16x32_bf16 v[24:27], v[176:179], v[196:199], v[24:27]
	v_mfma_f32_16x16x32_bf16 v[24:27], v[184:187], v[200:203], v[24:27]
	v_mfma_f32_16x16x32_bf16 v[32:35], v[162:165], v[196:199], v[32:35]
	v_mfma_f32_16x16x32_bf16 v[32:35], v[172:175], v[200:203], v[32:35]
	v_mfma_f32_16x16x32_bf16 v[16:19], v[162:165], v[204:207], v[16:19]
	v_mfma_f32_16x16x32_bf16 v[16:19], v[172:175], v[208:211], v[16:19]
	v_mfma_f32_16x16x32_bf16 v[8:11], v[176:179], v[204:207], v[8:11]
	v_mfma_f32_16x16x32_bf16 v[8:11], v[184:187], v[208:211], v[8:11]
	v_mfma_f32_16x16x32_bf16 v[0:3], v[176:179], v[212:215], v[0:3]
	v_mfma_f32_16x16x32_bf16 v[0:3], v[184:187], v[216:219], v[0:3]
	v_mfma_f32_16x16x32_bf16 v[4:7], v[162:165], v[212:215], v[4:7]
	v_mfma_f32_16x16x32_bf16 v[4:7], v[172:175], v[216:219], v[4:7]
	s_setprio 0
	s_barrier
; #define PG8_STAGE(bufoff, gbase, voff) do { _Pragma("unroll") for (int _i = 0; _i < 2; ++_i) \
;         __builtin_amdgcn_global_load_lds((const unsigned*)((const char*)(gbase) + (voff)[_i]), (PG8_LAS unsigned*)(lds + (bufoff) + ldsw + _i * 8192), 16, 0, 0); } while (0)
; #define PG8_LDA(dst, b, h) do { _Pragma("unroll") for (int m = 0; m < 4; ++m) _Pragma("unroll") for (int k = 0; k < 2; ++k) dst[m][k] = *(const PG8_LAS bf16x8*)(lds + PG8_SA(b, h) + aoff + m * 2048 + k * 1024); } while (0)
; #define PG8_LDB(dst, b, h) do { _Pragma("unroll") for (int n = 0; n < 2; ++n) _Pragma("unroll") for (int k = 0; k < 2; ++k) dst[n][k] = *(const PG8_LAS bf16x8*)(lds + PG8_SB(b, h) + boff + n * 2048 + k * 1024); } while (0)
; #define PG8_MMA(ai, bj, At, Bt) do { __builtin_amdgcn_s_setprio(1); _Pragma("unroll") for (int m = 0; m < 4; ++m) _Pragma("unroll") for (int n = 0; n < 2; ++n) _Pragma("unroll") for (int k = 0; k < 2; ++k) \
;         acc[ai][bj][m][n] = __builtin_amdgcn_mfma_f32_16x16x32_bf16(Bt[n][k], At[m][k], acc[ai][bj][m][n], 0, 0, 0); __builtin_amdgcn_s_setprio(0); } while (0)
; #define PG8_WAIT_V(n) asm volatile("s_waitcnt vmcnt(" #n ")" ::: "memory")
; #define PG8_WAIT_L(n) asm volatile("s_waitcnt lgkmcnt(" #n ")" ::: "memory")
; #define PG8_BAR __builtin_amdgcn_s_barrier()
; #define PG8_SCHED __builtin_amdgcn_sched_barrier(0)
; template <class Epi, class Sched, bool ALIGN_EPI = false, bool SP2 = false>
; __device__ __forceinline__ void gemm_phase(PG8_LAS unsigned char* lds, const Gemm g, const Sched& S, const Epi& E) {
;     ...
;             PG8_LDB(B0, 1, 0); PG8_LDB(B1, 1, 1); PG8_SCHED; PG8_LDA(At, 1, 0); PG8_STAGE(PG8_SA(0, 1), a2 + hstep, voffA);
;             PG8_WAIT_V(8); PG8_WAIT_L(0); PG8_BAR; PG8_MMA(0, 0, At, B0); PG8_MMA(0, 1, At, B1); PG8_BAR; PG8_SCHED;
;             PG8_LDA(At, 1, 1); PG8_STAGE(PG8_SB(1, 0), b3, voffB); PG8_STAGE(PG8_SB(1, 1), b3 + hstep, voffB); PG8_STAGE(PG8_SA(1, 0), a3, voffA);
;             PG8_WAIT_V(8); PG8_WAIT_L(0); PG8_BAR; PG8_MMA(1, 0, At, B0); PG8_MMA(1, 1, At, B1); PG8_BAR; PG8_SCHED;
	s_add_i32 s12, 0, 0x18000
	s_add_i32 s13, 0, 0x1c000
	v_add_u32_e32 v140, s12, v167
	v_add_u32_e32 v183, s13, v167
	ds_read_b128 v[128:131], v140
	ds_read_b128 v[132:135], v140 offset:1024
	ds_read_b128 v[136:139], v140 offset:2048
	ds_read_b128 v[140:143], v140 offset:3072
	ds_read_b128 v[162:165], v183
	ds_read_b128 v[172:175], v183 offset:1024
	ds_read_b128 v[176:179], v183 offset:2048
	ds_read_b128 v[184:187], v183 offset:3072
	s_add_u32 s40, s46, 0xb0000
	s_addc_u32 s41, s47, 0
	s_mov_b32 m0, s52
	ds_read_b128 v[188:191], v171 offset:32768
	ds_read_b128 v[192:195], v171 offset:33792
	ds_read_b128 v[196:199], v171 offset:34816
	ds_read_b128 v[200:203], v171 offset:35840
	ds_read_b128 v[204:207], v171 offset:36864
	ds_read_b128 v[208:211], v171 offset:37888
	ds_read_b128 v[212:215], v171 offset:38912
	ds_read_b128 v[216:219], v171 offset:39936
	global_load_lds_dwordx4 v144, s[40:41]
	s_mov_b32 m0, s53
	s_nop 0
	global_load_lds_dwordx4 v148, s[40:41]
	s_waitcnt vmcnt(8)
	s_waitcnt lgkmcnt(0)
	s_barrier
	s_setprio 1
	s_waitcnt lgkmcnt(0)
	v_mfma_f32_16x16x32_bf16 v[124:127], v[128:131], v[188:191], v[124:127]
	v_mfma_f32_16x16x32_bf16 v[124:127], v[132:135], v[192:195], v[124:127]
	v_mfma_f32_16x16x32_bf16 v[120:123], v[136:139], v[188:191], v[120:123]
	v_mfma_f32_16x16x32_bf16 v[120:123], v[140:143], v[192:195], v[120:123]
	v_mfma_f32_16x16x32_bf16 v[108:111], v[136:139], v[196:199], v[108:111]
	v_mfma_f32_16x16x32_bf16 v[108:111], v[140:143], v[200:203], v[108:111]
	v_mfma_f32_16x16x32_bf16 v[116:119], v[128:131], v[196:199], v[116:119]
	v_mfma_f32_16x16x32_bf16 v[116:119], v[132:135], v[200:203], v[116:119]
	v_mfma_f32_16x16x32_bf16 v[100:103], v[128:131], v[204:207], v[100:103]
	v_mfma_f32_16x16x32_bf16 v[100:103], v[132:135], v[208:211], v[100:103]
	v_mfma_f32_16x16x32_bf16 v[92:95], v[136:139], v[204:207], v[92:95]
	v_mfma_f32_16x16x32_bf16 v[92:95], v[140:143], v[208:211], v[92:95]
	v_mfma_f32_16x16x32_bf16 v[76:79], v[136:139], v[212:215], v[76:79]
	v_mfma_f32_16x16x32_bf16 v[76:79], v[140:143], v[216:219], v[76:79]
	v_mfma_f32_16x16x32_bf16 v[84:87], v[128:131], v[212:215], v[84:87]
	v_mfma_f32_16x16x32_bf16 v[84:87], v[132:135], v[216:219], v[84:87]
	v_mfma_f32_16x16x32_bf16 v[112:115], v[162:165], v[188:191], v[112:115]
	v_mfma_f32_16x16x32_bf16 v[112:115], v[172:175], v[192:195], v[112:115]
	v_mfma_f32_16x16x32_bf16 v[104:107], v[176:179], v[188:191], v[104:107]
	v_mfma_f32_16x16x32_bf16 v[104:107], v[184:187], v[192:195], v[104:107]
	v_mfma_f32_16x16x32_bf16 v[88:91], v[176:179], v[196:199], v[88:91]
	v_mfma_f32_16x16x32_bf16 v[88:91], v[184:187], v[200:203], v[88:91]
	v_mfma_f32_16x16x32_bf16 v[96:99], v[162:165], v[196:199], v[96:99]
	v_mfma_f32_16x16x32_bf16 v[96:99], v[172:175], v[200:203], v[96:99]
	v_mfma_f32_16x16x32_bf16 v[80:83], v[162:165], v[204:207], v[80:83]
	v_mfma_f32_16x16x32_bf16 v[80:83], v[172:175], v[208:211], v[80:83]
	v_mfma_f32_16x16x32_bf16 v[72:75], v[176:179], v[204:207], v[72:75]
	v_mfma_f32_16x16x32_bf16 v[72:75], v[184:187], v[208:211], v[72:75]
	v_mfma_f32_16x16x32_bf16 v[64:67], v[176:179], v[212:215], v[64:67]
	v_mfma_f32_16x16x32_bf16 v[64:67], v[184:187], v[216:219], v[64:67]
	v_mfma_f32_16x16x32_bf16 v[68:71], v[162:165], v[212:215], v[68:71]
	v_mfma_f32_16x16x32_bf16 v[68:71], v[172:175], v[216:219], v[68:71]
	s_setprio 0
	s_barrier
	s_add_i32 s12, s12, s49
	s_add_u32 s98, s44, s30
	s_addc_u32 s99, s45, s31
	s_add_u32 s100, s46, s30
	s_addc_u32 s101, s47, s31
	s_mov_b32 m0, s12
	ds_read_b128 v[188:191], v171 offset:49152
	ds_read_b128 v[192:195], v171 offset:50176
	ds_read_b128 v[196:199], v171 offset:51200
	ds_read_b128 v[200:203], v171 offset:52224
	ds_read_b128 v[204:207], v171 offset:53248
	ds_read_b128 v[208:211], v171 offset:54272
	ds_read_b128 v[212:215], v171 offset:55296
	ds_read_b128 v[216:219], v171 offset:56320
	global_load_lds_dwordx4 v146, s[98:99]
	s_add_i32 m0, s12, 0x2000
	s_add_u32 s40, s44, 0xb0080
	s_addc_u32 s41, s45, 0
	s_add_i32 s12, s13, s49
	global_load_lds_dwordx4 v150, s[98:99]
	s_mov_b32 m0, s12
	s_nop 0
	global_load_lds_dwordx4 v146, s[40:41]
	s_add_i32 m0, s12, 0x2000
	s_nop 0
	global_load_lds_dwordx4 v150, s[40:41]
	s_mov_b32 m0, s59
	s_nop 0
	global_load_lds_dwordx4 v144, s[100:101]
	s_mov_b32 m0, s60
	s_nop 0
	global_load_lds_dwordx4 v148, s[100:101]
	s_waitcnt vmcnt(8)
	s_waitcnt lgkmcnt(0)
	s_barrier
	s_setprio 1
	s_waitcnt lgkmcnt(0)
	v_mfma_f32_16x16x32_bf16 v[60:63], v[128:131], v[188:191], v[60:63]
	v_mfma_f32_16x16x32_bf16 v[60:63], v[132:135], v[192:195], v[60:63]
	v_mfma_f32_16x16x32_bf16 v[56:59], v[136:139], v[188:191], v[56:59]
	v_mfma_f32_16x16x32_bf16 v[56:59], v[140:143], v[192:195], v[56:59]
	v_mfma_f32_16x16x32_bf16 v[44:47], v[136:139], v[196:199], v[44:47]
	v_mfma_f32_16x16x32_bf16 v[44:47], v[140:143], v[200:203], v[44:47]
	v_mfma_f32_16x16x32_bf16 v[48:51], v[128:131], v[196:199], v[48:51]
	v_mfma_f32_16x16x32_bf16 v[48:51], v[132:135], v[200:203], v[48:51]
	v_mfma_f32_16x16x32_bf16 v[36:39], v[128:131], v[204:207], v[36:39]
	v_mfma_f32_16x16x32_bf16 v[36:39], v[132:135], v[208:211], v[36:39]
	v_mfma_f32_16x16x32_bf16 v[28:31], v[136:139], v[204:207], v[28:31]
	v_mfma_f32_16x16x32_bf16 v[28:31], v[140:143], v[208:211], v[28:31]
	v_mfma_f32_16x16x32_bf16 v[12:15], v[136:139], v[212:215], v[12:15]
	v_mfma_f32_16x16x32_bf16 v[12:15], v[140:143], v[216:219], v[12:15]
	v_mfma_f32_16x16x32_bf16 v[20:23], v[128:131], v[212:215], v[20:23]
	v_mfma_f32_16x16x32_bf16 v[20:23], v[132:135], v[216:219], v[20:23]
	v_mfma_f32_16x16x32_bf16 v[52:55], v[162:165], v[188:191], v[52:55]
	v_mfma_f32_16x16x32_bf16 v[52:55], v[172:175], v[192:195], v[52:55]
	v_mfma_f32_16x16x32_bf16 v[40:43], v[176:179], v[188:191], v[40:43]
	v_mfma_f32_16x16x32_bf16 v[40:43], v[184:187], v[192:195], v[40:43]
	v_mfma_f32_16x16x32_bf16 v[24:27], v[176:179], v[196:199], v[24:27]
	v_mfma_f32_16x16x32_bf16 v[24:27], v[184:187], v[200:203], v[24:27]
	v_mfma_f32_16x16x32_bf16 v[32:35], v[162:165], v[196:199], v[32:35]
	v_mfma_f32_16x16x32_bf16 v[32:35], v[172:175], v[200:203], v[32:35]
	v_mfma_f32_16x16x32_bf16 v[16:19], v[162:165], v[204:207], v[16:19]
	v_mfma_f32_16x16x32_bf16 v[16:19], v[172:175], v[208:211], v[16:19]
	v_mfma_f32_16x16x32_bf16 v[8:11], v[176:179], v[204:207], v[8:11]
	v_mfma_f32_16x16x32_bf16 v[8:11], v[184:187], v[208:211], v[8:11]
	v_mfma_f32_16x16x32_bf16 v[0:3], v[176:179], v[212:215], v[0:3]
	v_mfma_f32_16x16x32_bf16 v[0:3], v[184:187], v[216:219], v[0:3]
	v_mfma_f32_16x16x32_bf16 v[4:7], v[162:165], v[212:215], v[4:7]
	v_mfma_f32_16x16x32_bf16 v[4:7], v[172:175], v[216:219], v[4:7]
	s_setprio 0
	s_barrier
	s_add_i32 s74, s74, 2
	s_add_u32 s71, s71, 0x100
	s_addc_u32 s73, s73, 0
	s_cmp_gt_u32 s74, 41
	s_mov_b64 s[40:41], s[42:43]
	s_cbranch_scc0 .LBB0_872
	s_and_b64 vcc, exec, s[34:35]
	s_cbranch_vccz .LBB0_875
	s_barrier

; #define PG8_STAGE(bufoff, gbase, voff) do { _Pragma("unroll") for (int _i = 0; _i < 2; ++_i) \
;         __builtin_amdgcn_global_load_lds((const unsigned*)((const char*)(gbase) + (voff)[_i]), (PG8_LAS unsigned*)(lds + (bufoff) + ldsw + _i * 8192), 16, 0, 0); } while (0)
; #define PG8_LDA(dst, b, h) do { _Pragma("unroll") for (int m = 0; m < 4; ++m) _Pragma("unroll") for (int k = 0; k < 2; ++k) dst[m][k] = *(const PG8_LAS bf16x8*)(lds + PG8_SA(b, h) + aoff + m * 2048 + k * 1024); } while (0)
; #define PG8_LDB(dst, b, h) do { _Pragma("unroll") for (int n = 0; n < 2; ++n) _Pragma("unroll") for (int k = 0; k < 2; ++k) dst[n][k] = *(const PG8_LAS bf16x8*)(lds + PG8_SB(b, h) + boff + n * 2048 + k * 1024); } while (0)
; #define PG8_MMA(ai, bj, At, Bt) do { __builtin_amdgcn_s_setprio(1); _Pragma("unroll") for (int m = 0; m < 4; ++m) _Pragma("unroll") for (int n = 0; n < 2; ++n) _Pragma("unroll") for (int k = 0; k < 2; ++k) \
;         acc[ai][bj][m][n] = __builtin_amdgcn_mfma_f32_16x16x32_bf16(Bt[n][k], At[m][k], acc[ai][bj][m][n], 0, 0, 0); __builtin_amdgcn_s_setprio(0); } while (0)
; #define PG8_WAIT_V(n) asm volatile("s_waitcnt vmcnt(" #n ")" ::: "memory")
; #define PG8_WAIT_L(n) asm volatile("s_waitcnt lgkmcnt(" #n ")" ::: "memory")
; #define PG8_BAR __builtin_amdgcn_s_barrier()
; #define PG8_SCHED __builtin_amdgcn_sched_barrier(0)
; template <class Epi, class Sched, bool ALIGN_EPI = false, bool SP2 = false>
; __device__ __forceinline__ void gemm_phase(PG8_LAS unsigned char* lds, const Gemm g, const Sched& S, const Epi& E) {
;     ...
;             PG8_LDB(B0, 0, 0); PG8_LDB(B1, 0, 1); PG8_SCHED; PG8_LDA(At, 0, 0); PG8_STAGE(PG8_SA(1, 1), a1 + hstep, voffA);
;             PG8_WAIT_V(8); PG8_WAIT_L(0); PG8_BAR; PG8_MMA(0, 0, At, B0); PG8_MMA(0, 1, At, B1); PG8_BAR; PG8_SCHED;
;             PG8_LDA(At, 0, 1); PG8_STAGE(PG8_SB(0, 0), b2, voffB); PG8_STAGE(PG8_SB(0, 1), b2 + hstep, voffB); PG8_STAGE(PG8_SA(0, 0), a2, voffA);
;             PG8_WAIT_V(8); PG8_WAIT_L(0); PG8_BAR; PG8_MMA(1, 0, At, B0); PG8_MMA(1, 1, At, B1); PG8_BAR; PG8_SCHED;
.LBB0_960:
	v_add_u32_e32 v130, s89, v169
	ds_read_b128 v[150:153], v130
	ds_read_b128 v[158:161], v130 offset:1024
	ds_read_b128 v[162:165], v130 offset:2048
	ds_read_b128 v[196:199], v130 offset:3072
	v_add_u32_e32 v130, s90, v169
	ds_read_b128 v[200:203], v130
	ds_read_b128 v[204:207], v130 offset:1024
	ds_read_b128 v[208:211], v130 offset:2048
	ds_read_b128 v[212:215], v130 offset:3072
	s_add_u32 s12, s10, 0xfffc0080
	s_addc_u32 s13, s11, -1
	s_and_b64 s[66:67], s[66:67], exec
	s_cselect_b32 s69, s57, s13
	s_cselect_b32 s68, s63, s12
	s_cselect_b32 s67, s55, s71
	s_cselect_b32 s66, s70, s65
	s_add_i32 m0, s75, 0xc000
	ds_read_b128 v[216:219], v191
	ds_read_b128 v[220:223], v191 offset:1024
	ds_read_b128 v[224:227], v191 offset:2048
	ds_read_b128 v[228:231], v191 offset:3072
	ds_read_b128 v[232:235], v191 offset:4096
	ds_read_b128 v[236:239], v191 offset:5120
	ds_read_b128 v[240:243], v191 offset:6144
	ds_read_b128 v[244:247], v191 offset:7168
	global_load_lds_dwordx4 v142, s[10:11]
	s_add_i32 m0, s75, 0xe000
	s_nop 0
	global_load_lds_dwordx4 v140, s[10:11]
	s_waitcnt vmcnt(8)
	s_waitcnt lgkmcnt(0)
	s_barrier
	s_setprio 1
	s_waitcnt lgkmcnt(0)
	v_mfma_f32_16x16x32_bf16 v[124:127], v[150:153], v[216:219], v[124:127]
	v_mfma_f32_16x16x32_bf16 v[124:127], v[158:161], v[220:223], v[124:127]
	v_mfma_f32_16x16x32_bf16 v[120:123], v[162:165], v[216:219], v[120:123]
	v_mfma_f32_16x16x32_bf16 v[120:123], v[196:199], v[220:223], v[120:123]
	v_mfma_f32_16x16x32_bf16 v[104:107], v[162:165], v[224:227], v[104:107]
	v_mfma_f32_16x16x32_bf16 v[104:107], v[196:199], v[228:231], v[104:107]
	v_mfma_f32_16x16x32_bf16 v[112:115], v[150:153], v[224:227], v[112:115]
	v_mfma_f32_16x16x32_bf16 v[112:115], v[158:161], v[228:231], v[112:115]
	v_mfma_f32_16x16x32_bf16 v[100:103], v[150:153], v[232:235], v[100:103]
	v_mfma_f32_16x16x32_bf16 v[100:103], v[158:161], v[236:239], v[100:103]
	v_mfma_f32_16x16x32_bf16 v[96:99], v[162:165], v[232:235], v[96:99]
	v_mfma_f32_16x16x32_bf16 v[96:99], v[196:199], v[236:239], v[96:99]
	v_mfma_f32_16x16x32_bf16 v[72:75], v[162:165], v[240:243], v[72:75]
	v_mfma_f32_16x16x32_bf16 v[72:75], v[196:199], v[244:247], v[72:75]
	v_mfma_f32_16x16x32_bf16 v[80:83], v[150:153], v[240:243], v[80:83]
	v_mfma_f32_16x16x32_bf16 v[80:83], v[158:161], v[244:247], v[80:83]
	v_mfma_f32_16x16x32_bf16 v[116:119], v[200:203], v[216:219], v[116:119]
	v_mfma_f32_16x16x32_bf16 v[116:119], v[204:207], v[220:223], v[116:119]
	v_mfma_f32_16x16x32_bf16 v[108:111], v[208:211], v[216:219], v[108:111]
	v_mfma_f32_16x16x32_bf16 v[108:111], v[212:215], v[220:223], v[108:111]
	v_mfma_f32_16x16x32_bf16 v[88:91], v[208:211], v[224:227], v[88:91]
	v_mfma_f32_16x16x32_bf16 v[88:91], v[212:215], v[228:231], v[88:91]
	v_mfma_f32_16x16x32_bf16 v[92:95], v[200:203], v[224:227], v[92:95]
	v_mfma_f32_16x16x32_bf16 v[92:95], v[204:207], v[228:231], v[92:95]
	v_mfma_f32_16x16x32_bf16 v[84:87], v[200:203], v[232:235], v[84:87]
	v_mfma_f32_16x16x32_bf16 v[84:87], v[204:207], v[236:239], v[84:87]
	v_mfma_f32_16x16x32_bf16 v[76:79], v[208:211], v[232:235], v[76:79]
	v_mfma_f32_16x16x32_bf16 v[76:79], v[212:215], v[236:239], v[76:79]
	v_mfma_f32_16x16x32_bf16 v[64:67], v[208:211], v[240:243], v[64:67]
	v_mfma_f32_16x16x32_bf16 v[64:67], v[212:215], v[244:247], v[64:67]
	v_mfma_f32_16x16x32_bf16 v[68:71], v[200:203], v[240:243], v[68:71]
	v_mfma_f32_16x16x32_bf16 v[68:71], v[204:207], v[244:247], v[68:71]
	s_setprio 0
	s_barrier
	s_add_i32 s12, s89, s74
	s_mov_b32 m0, s12
	ds_read_b128 v[216:219], v191 offset:16384
	ds_read_b128 v[220:223], v191 offset:17408
	ds_read_b128 v[224:227], v191 offset:18432
	ds_read_b128 v[228:231], v191 offset:19456
	ds_read_b128 v[232:235], v191 offset:20480
	ds_read_b128 v[236:239], v191 offset:21504
	ds_read_b128 v[240:243], v191 offset:22528
	ds_read_b128 v[244:247], v191 offset:23552
	global_load_lds_dwordx4 v134, s[66:67]
	s_add_i32 m0, s12, 0x2000
	s_add_u32 vcc_lo, s66, 0x40000
	v_lshl_add_u64 v[154:155], s[66:67], 0, v[138:139]
	s_addc_u32 vcc_hi, s67, 0
	s_add_i32 s12, s90, s74
	global_load_lds_dwordx4 v138, s[66:67]
	v_lshl_add_u64 v[166:167], vcc, 0, v[134:135]
	s_mov_b32 m0, s12
	v_lshl_add_u64 v[248:249], s[68:69], 0, v[136:137]
	global_load_lds_dwordx4 v[166:167], off
	v_lshl_add_u64 v[166:167], vcc, 0, v[138:139]
	s_add_i32 m0, s12, 0x2000
	s_nop 0
	global_load_lds_dwordx4 v[166:167], off
	v_lshl_add_u64 v[166:167], s[68:69], 0, v[132:133]
	s_mov_b32 m0, s75
	s_nop 0
	global_load_lds_dwordx4 v132, s[68:69]
	s_mov_b32 m0, s76
	s_nop 0
	global_load_lds_dwordx4 v136, s[68:69]
	s_waitcnt vmcnt(8)
	s_waitcnt lgkmcnt(0)
	s_barrier
; #define PG8_STAGE(bufoff, gbase, voff) do { _Pragma("unroll") for (int _i = 0; _i < 2; ++_i) \
;         __builtin_amdgcn_global_load_lds((const unsigned*)((const char*)(gbase) + (voff)[_i]), (PG8_LAS unsigned*)(lds + (bufoff) + ldsw + _i * 8192), 16, 0, 0); } while (0)
; #define PG8_LDA(dst, b, h) do { _Pragma("unroll") for (int m = 0; m < 4; ++m) _Pragma("unroll") for (int k = 0; k < 2; ++k) dst[m][k] = *(const PG8_LAS bf16x8*)(lds + PG8_SA(b, h) + aoff + m * 2048 + k * 1024); } while (0)
; #define PG8_LDB(dst, b, h) do { _Pragma("unroll") for (int n = 0; n < 2; ++n) _Pragma("unroll") for (int k = 0; k < 2; ++k) dst[n][k] = *(const PG8_LAS bf16x8*)(lds + PG8_SB(b, h) + boff + n * 2048 + k * 1024); } while (0)
; #define PG8_MMA(ai, bj, At, Bt) do { __builtin_amdgcn_s_setprio(1); _Pragma("unroll") for (int m = 0; m < 4; ++m) _Pragma("unroll") for (int n = 0; n < 2; ++n) _Pragma("unroll") for (int k = 0; k < 2; ++k) \
;         acc[ai][bj][m][n] = __builtin_amdgcn_mfma_f32_16x16x32_bf16(Bt[n][k], At[m][k], acc[ai][bj][m][n], 0, 0, 0); __builtin_amdgcn_s_setprio(0); } while (0)
; #define PG8_WAIT_V(n) asm volatile("s_waitcnt vmcnt(" #n ")" ::: "memory")
; #define PG8_WAIT_L(n) asm volatile("s_waitcnt lgkmcnt(" #n ")" ::: "memory")
; #define PG8_BAR __builtin_amdgcn_s_barrier()
; #define PG8_SCHED __builtin_amdgcn_sched_barrier(0)
; template <class Epi, class Sched, bool ALIGN_EPI = false, bool SP2 = false>
; __device__ __forceinline__ void gemm_phase(PG8_LAS unsigned char* lds, const Gemm g, const Sched& S, const Epi& E) {
;     ...
;             PG8_WAIT_V(8); PG8_WAIT_L(0); PG8_BAR; PG8_MMA(1, 0, At, B0); PG8_MMA(1, 1, At, B1); PG8_BAR; PG8_SCHED;
;             PG8_LDB(B0, 1, 0); PG8_LDB(B1, 1, 1); PG8_SCHED; PG8_LDA(At, 1, 0); PG8_STAGE(PG8_SA(0, 1), a2 + hstep, voffA);
;             PG8_WAIT_V(8); PG8_WAIT_L(0); PG8_BAR; PG8_MMA(0, 0, At, B0); PG8_MMA(0, 1, At, B1); PG8_BAR; PG8_SCHED;
	s_setprio 1
	s_waitcnt lgkmcnt(0)
	v_mfma_f32_16x16x32_bf16 v[60:63], v[150:153], v[216:219], v[60:63]
	v_mfma_f32_16x16x32_bf16 v[60:63], v[158:161], v[220:223], v[60:63]
	v_mfma_f32_16x16x32_bf16 v[56:59], v[162:165], v[216:219], v[56:59]
	v_mfma_f32_16x16x32_bf16 v[56:59], v[196:199], v[220:223], v[56:59]
	v_mfma_f32_16x16x32_bf16 v[40:43], v[162:165], v[224:227], v[40:43]
	v_mfma_f32_16x16x32_bf16 v[40:43], v[196:199], v[228:231], v[40:43]
	v_mfma_f32_16x16x32_bf16 v[48:51], v[150:153], v[224:227], v[48:51]
	v_mfma_f32_16x16x32_bf16 v[48:51], v[158:161], v[228:231], v[48:51]
	v_mfma_f32_16x16x32_bf16 v[36:39], v[150:153], v[232:235], v[36:39]
	v_mfma_f32_16x16x32_bf16 v[36:39], v[158:161], v[236:239], v[36:39]
	v_mfma_f32_16x16x32_bf16 v[32:35], v[162:165], v[232:235], v[32:35]
	v_mfma_f32_16x16x32_bf16 v[32:35], v[196:199], v[236:239], v[32:35]
	v_mfma_f32_16x16x32_bf16 v[16:19], v[162:165], v[240:243], v[16:19]
	v_mfma_f32_16x16x32_bf16 v[16:19], v[196:199], v[244:247], v[16:19]
	v_mfma_f32_16x16x32_bf16 v[20:23], v[150:153], v[240:243], v[20:23]
	v_mfma_f32_16x16x32_bf16 v[20:23], v[158:161], v[244:247], v[20:23]
	v_mfma_f32_16x16x32_bf16 v[52:55], v[200:203], v[216:219], v[52:55]
	v_mfma_f32_16x16x32_bf16 v[52:55], v[204:207], v[220:223], v[52:55]
	v_mfma_f32_16x16x32_bf16 v[44:47], v[208:211], v[216:219], v[44:47]
	v_mfma_f32_16x16x32_bf16 v[44:47], v[212:215], v[220:223], v[44:47]
	v_mfma_f32_16x16x32_bf16 v[24:27], v[208:211], v[224:227], v[24:27]
	v_mfma_f32_16x16x32_bf16 v[24:27], v[212:215], v[228:231], v[24:27]
	v_mfma_f32_16x16x32_bf16 v[28:31], v[200:203], v[224:227], v[28:31]
	v_mfma_f32_16x16x32_bf16 v[28:31], v[204:207], v[228:231], v[28:31]
	v_mfma_f32_16x16x32_bf16 v[12:15], v[200:203], v[232:235], v[12:15]
	v_mfma_f32_16x16x32_bf16 v[12:15], v[204:207], v[236:239], v[12:15]
	v_mfma_f32_16x16x32_bf16 v[8:11], v[208:211], v[232:235], v[8:11]
	v_mfma_f32_16x16x32_bf16 v[8:11], v[212:215], v[236:239], v[8:11]
	v_mfma_f32_16x16x32_bf16 v[0:3], v[208:211], v[240:243], v[0:3]
	v_mfma_f32_16x16x32_bf16 v[0:3], v[212:215], v[244:247], v[0:3]
	v_mfma_f32_16x16x32_bf16 v[4:7], v[200:203], v[240:243], v[4:7]
	v_mfma_f32_16x16x32_bf16 v[4:7], v[204:207], v[244:247], v[4:7]
	s_setprio 0
	s_barrier
	s_add_i32 s12, 0, 0x18000
	v_add_u32_e32 v195, s12, v169
	s_add_i32 s13, 0, 0x1c000
	ds_read_b128 v[150:153], v195
	ds_read_b128 v[158:161], v195 offset:1024
	ds_read_b128 v[162:165], v195 offset:2048
	ds_read_b128 v[196:199], v195 offset:3072
	v_add_u32_e32 v195, s13, v169
	ds_read_b128 v[200:203], v195
	ds_read_b128 v[204:207], v195 offset:1024
	ds_read_b128 v[208:211], v195 offset:2048
	ds_read_b128 v[212:215], v195 offset:3072
	s_add_u32 s68, s68, 0x40000
	s_addc_u32 s69, s69, 0
	s_mov_b32 m0, s77
	ds_read_b128 v[216:219], v191 offset:32768
	ds_read_b128 v[220:223], v191 offset:33792
	ds_read_b128 v[224:227], v191 offset:34816
	ds_read_b128 v[228:231], v191 offset:35840
	ds_read_b128 v[232:235], v191 offset:36864
	ds_read_b128 v[236:239], v191 offset:37888
	ds_read_b128 v[240:243], v191 offset:38912
	ds_read_b128 v[244:247], v191 offset:39936
	global_load_lds_dwordx4 v132, s[68:69]
	s_mov_b32 m0, s78
	s_nop 0
	global_load_lds_dwordx4 v136, s[68:69]
	s_waitcnt vmcnt(8)
	s_waitcnt lgkmcnt(0)
	s_barrier
	s_setprio 1
	s_waitcnt lgkmcnt(0)
	v_mfma_f32_16x16x32_bf16 v[124:127], v[150:153], v[216:219], v[124:127]
	v_mfma_f32_16x16x32_bf16 v[124:127], v[158:161], v[220:223], v[124:127]
	v_mfma_f32_16x16x32_bf16 v[120:123], v[162:165], v[216:219], v[120:123]
	v_mfma_f32_16x16x32_bf16 v[120:123], v[196:199], v[220:223], v[120:123]
	v_mfma_f32_16x16x32_bf16 v[104:107], v[162:165], v[224:227], v[104:107]
	v_mfma_f32_16x16x32_bf16 v[104:107], v[196:199], v[228:231], v[104:107]
	v_mfma_f32_16x16x32_bf16 v[112:115], v[150:153], v[224:227], v[112:115]
	v_mfma_f32_16x16x32_bf16 v[112:115], v[158:161], v[228:231], v[112:115]
	v_mfma_f32_16x16x32_bf16 v[100:103], v[150:153], v[232:235], v[100:103]
	v_mfma_f32_16x16x32_bf16 v[100:103], v[158:161], v[236:239], v[100:103]
	v_mfma_f32_16x16x32_bf16 v[96:99], v[162:165], v[232:235], v[96:99]
	v_mfma_f32_16x16x32_bf16 v[96:99], v[196:199], v[236:239], v[96:99]
	v_mfma_f32_16x16x32_bf16 v[72:75], v[162:165], v[240:243], v[72:75]
	v_mfma_f32_16x16x32_bf16 v[72:75], v[196:199], v[244:247], v[72:75]
	v_mfma_f32_16x16x32_bf16 v[80:83], v[150:153], v[240:243], v[80:83]
	v_mfma_f32_16x16x32_bf16 v[80:83], v[158:161], v[244:247], v[80:83]
	v_mfma_f32_16x16x32_bf16 v[116:119], v[200:203], v[216:219], v[116:119]
	v_mfma_f32_16x16x32_bf16 v[116:119], v[204:207], v[220:223], v[116:119]
	v_mfma_f32_16x16x32_bf16 v[108:111], v[208:211], v[216:219], v[108:111]
	v_mfma_f32_16x16x32_bf16 v[108:111], v[212:215], v[220:223], v[108:111]
	v_mfma_f32_16x16x32_bf16 v[88:91], v[208:211], v[224:227], v[88:91]
	v_mfma_f32_16x16x32_bf16 v[88:91], v[212:215], v[228:231], v[88:91]
	v_mfma_f32_16x16x32_bf16 v[92:95], v[200:203], v[224:227], v[92:95]
	v_mfma_f32_16x16x32_bf16 v[92:95], v[204:207], v[228:231], v[92:95]
	v_mfma_f32_16x16x32_bf16 v[84:87], v[200:203], v[232:235], v[84:87]
	v_mfma_f32_16x16x32_bf16 v[84:87], v[204:207], v[236:239], v[84:87]
	v_mfma_f32_16x16x32_bf16 v[76:79], v[208:211], v[232:235], v[76:79]
	v_mfma_f32_16x16x32_bf16 v[76:79], v[212:215], v[236:239], v[76:79]
	v_mfma_f32_16x16x32_bf16 v[64:67], v[208:211], v[240:243], v[64:67]
	v_mfma_f32_16x16x32_bf16 v[64:67], v[212:215], v[244:247], v[64:67]
	v_mfma_f32_16x16x32_bf16 v[68:71], v[200:203], v[240:243], v[68:71]
	v_mfma_f32_16x16x32_bf16 v[68:71], v[204:207], v[244:247], v[68:71]
	s_setprio 0
	s_barrier
; #define PG8_STAGE(bufoff, gbase, voff) do { _Pragma("unroll") for (int _i = 0; _i < 2; ++_i) \
;         __builtin_amdgcn_global_load_lds((const unsigned*)((const char*)(gbase) + (voff)[_i]), (PG8_LAS unsigned*)(lds + (bufoff) + ldsw + _i * 8192), 16, 0, 0); } while (0)
; #define PG8_LDA(dst, b, h) do { _Pragma("unroll") for (int m = 0; m < 4; ++m) _Pragma("unroll") for (int k = 0; k < 2; ++k) dst[m][k] = *(const PG8_LAS bf16x8*)(lds + PG8_SA(b, h) + aoff + m * 2048 + k * 1024); } while (0)
; #define PG8_MMA(ai, bj, At, Bt) do { __builtin_amdgcn_s_setprio(1); _Pragma("unroll") for (int m = 0; m < 4; ++m) _Pragma("unroll") for (int n = 0; n < 2; ++n) _Pragma("unroll") for (int k = 0; k < 2; ++k) \
;         acc[ai][bj][m][n] = __builtin_amdgcn_mfma_f32_16x16x32_bf16(Bt[n][k], At[m][k], acc[ai][bj][m][n], 0, 0, 0); __builtin_amdgcn_s_setprio(0); } while (0)
; #define PG8_WAIT_V(n) asm volatile("s_waitcnt vmcnt(" #n ")" ::: "memory")
; #define PG8_WAIT_L(n) asm volatile("s_waitcnt lgkmcnt(" #n ")" ::: "memory")
; #define PG8_BAR __builtin_amdgcn_s_barrier()
; #define PG8_SCHED __builtin_amdgcn_sched_barrier(0)
; template <class Epi, class Sched, bool ALIGN_EPI = false, bool SP2 = false>
; __device__ __forceinline__ void gemm_phase(PG8_LAS unsigned char* lds, const Gemm g, const Sched& S, const Epi& E) {
;     ...
;             PG8_LDA(At, 1, 1); PG8_STAGE(PG8_SB(1, 0), b3, voffB); PG8_STAGE(PG8_SB(1, 1), b3 + hstep, voffB); PG8_STAGE(PG8_SA(1, 0), a3, voffA);
;             PG8_WAIT_V(8); PG8_WAIT_L(0); PG8_BAR; PG8_MMA(1, 0, At, B0); PG8_MMA(1, 1, At, B1); PG8_BAR; PG8_SCHED;
	s_add_i32 s12, s12, s74
	s_add_u32 s98, s66, s42
	s_addc_u32 s99, s67, s43
	s_mov_b32 m0, s12
	ds_read_b128 v[216:219], v191 offset:49152
	ds_read_b128 v[220:223], v191 offset:50176
	ds_read_b128 v[224:227], v191 offset:51200
	ds_read_b128 v[228:231], v191 offset:52224
	ds_read_b128 v[232:235], v191 offset:53248
	ds_read_b128 v[236:239], v191 offset:54272
	ds_read_b128 v[240:243], v191 offset:55296
	ds_read_b128 v[244:247], v191 offset:56320
	global_load_lds_dwordx4 v134, s[98:99]
	s_add_i32 m0, s12, 0x2000
	s_add_u32 s66, s66, 0x40080
	v_lshl_add_u64 v[130:131], v[154:155], 0, s[42:43]
	s_addc_u32 s67, s67, 0
	s_add_i32 s12, s13, s74
	global_load_lds_dwordx4 v[130:131], off
	s_mov_b32 m0, s12
	s_nop 0
	global_load_lds_dwordx4 v134, s[66:67]
	s_add_i32 m0, s12, 0x2000
	s_nop 0
	global_load_lds_dwordx4 v138, s[66:67]
	v_lshl_add_u64 v[130:131], v[166:167], 0, s[42:43]
	s_mov_b32 m0, s79
	s_nop 0
	global_load_lds_dwordx4 v[130:131], off
	v_lshl_add_u64 v[130:131], v[248:249], 0, s[42:43]
	s_mov_b32 m0, s80
	s_nop 0
	global_load_lds_dwordx4 v[130:131], off
	s_waitcnt vmcnt(8)
	s_waitcnt lgkmcnt(0)
	s_barrier
	s_setprio 1
	s_waitcnt lgkmcnt(0)
	v_mfma_f32_16x16x32_bf16 v[60:63], v[150:153], v[216:219], v[60:63]
	v_mfma_f32_16x16x32_bf16 v[60:63], v[158:161], v[220:223], v[60:63]
	v_mfma_f32_16x16x32_bf16 v[56:59], v[162:165], v[216:219], v[56:59]
	v_mfma_f32_16x16x32_bf16 v[56:59], v[196:199], v[220:223], v[56:59]
	v_mfma_f32_16x16x32_bf16 v[40:43], v[162:165], v[224:227], v[40:43]
	v_mfma_f32_16x16x32_bf16 v[40:43], v[196:199], v[228:231], v[40:43]
	v_mfma_f32_16x16x32_bf16 v[48:51], v[150:153], v[224:227], v[48:51]
	v_mfma_f32_16x16x32_bf16 v[48:51], v[158:161], v[228:231], v[48:51]
	v_mfma_f32_16x16x32_bf16 v[36:39], v[150:153], v[232:235], v[36:39]
	v_mfma_f32_16x16x32_bf16 v[36:39], v[158:161], v[236:239], v[36:39]
	v_mfma_f32_16x16x32_bf16 v[32:35], v[162:165], v[232:235], v[32:35]
	v_mfma_f32_16x16x32_bf16 v[32:35], v[196:199], v[236:239], v[32:35]
	v_mfma_f32_16x16x32_bf16 v[16:19], v[162:165], v[240:243], v[16:19]
	v_mfma_f32_16x16x32_bf16 v[16:19], v[196:199], v[244:247], v[16:19]
	v_mfma_f32_16x16x32_bf16 v[20:23], v[150:153], v[240:243], v[20:23]
	v_mfma_f32_16x16x32_bf16 v[20:23], v[158:161], v[244:247], v[20:23]
	v_mfma_f32_16x16x32_bf16 v[52:55], v[200:203], v[216:219], v[52:55]
	v_mfma_f32_16x16x32_bf16 v[52:55], v[204:207], v[220:223], v[52:55]
	v_mfma_f32_16x16x32_bf16 v[44:47], v[208:211], v[216:219], v[44:47]
	v_mfma_f32_16x16x32_bf16 v[44:47], v[212:215], v[220:223], v[44:47]
	v_mfma_f32_16x16x32_bf16 v[24:27], v[208:211], v[224:227], v[24:27]
	v_mfma_f32_16x16x32_bf16 v[24:27], v[212:215], v[228:231], v[24:27]
	v_mfma_f32_16x16x32_bf16 v[28:31], v[200:203], v[224:227], v[28:31]
	v_mfma_f32_16x16x32_bf16 v[28:31], v[204:207], v[228:231], v[28:31]
	v_mfma_f32_16x16x32_bf16 v[12:15], v[200:203], v[232:235], v[12:15]
	v_mfma_f32_16x16x32_bf16 v[12:15], v[204:207], v[236:239], v[12:15]
	v_mfma_f32_16x16x32_bf16 v[8:11], v[208:211], v[232:235], v[8:11]
	v_mfma_f32_16x16x32_bf16 v[8:11], v[212:215], v[236:239], v[8:11]
	v_mfma_f32_16x16x32_bf16 v[0:3], v[208:211], v[240:243], v[0:3]
	v_mfma_f32_16x16x32_bf16 v[0:3], v[212:215], v[244:247], v[0:3]
	v_mfma_f32_16x16x32_bf16 v[4:7], v[200:203], v[240:243], v[4:7]
	v_mfma_f32_16x16x32_bf16 v[4:7], v[204:207], v[244:247], v[4:7]
	s_setprio 0
	s_barrier
	s_add_i32 s96, s96, 2
	s_add_u32 s65, s65, 0x100
	s_addc_u32 s71, s71, 0
	s_add_u32 s10, s10, 0x100
	s_addc_u32 s11, s11, 0
	s_cmp_gt_u32 s96, 13
	s_cbranch_scc1 .LBB0_963

; #define PG8_STAGE(bufoff, gbase, voff) do { _Pragma("unroll") for (int _i = 0; _i < 2; ++_i) \
;         __builtin_amdgcn_global_load_lds((const unsigned*)((const char*)(gbase) + (voff)[_i]), (PG8_LAS unsigned*)(lds + (bufoff) + ldsw + _i * 8192), 16, 0, 0); } while (0)
; #define PG8_LDA(dst, b, h) do { _Pragma("unroll") for (int m = 0; m < 4; ++m) _Pragma("unroll") for (int k = 0; k < 2; ++k) dst[m][k] = *(const PG8_LAS bf16x8*)(lds + PG8_SA(b, h) + aoff + m * 2048 + k * 1024); } while (0)
; #define PG8_LDB(dst, b, h) do { _Pragma("unroll") for (int n = 0; n < 2; ++n) _Pragma("unroll") for (int k = 0; k < 2; ++k) dst[n][k] = *(const PG8_LAS bf16x8*)(lds + PG8_SB(b, h) + boff + n * 2048 + k * 1024); } while (0)
; #define PG8_MMA(ai, bj, At, Bt) do { __builtin_amdgcn_s_setprio(1); _Pragma("unroll") for (int m = 0; m < 4; ++m) _Pragma("unroll") for (int n = 0; n < 2; ++n) _Pragma("unroll") for (int k = 0; k < 2; ++k) \
;         acc[ai][bj][m][n] = __builtin_amdgcn_mfma_f32_16x16x32_bf16(Bt[n][k], At[m][k], acc[ai][bj][m][n], 0, 0, 0); __builtin_amdgcn_s_setprio(0); } while (0)
; #define PG8_WAIT_V(n) asm volatile("s_waitcnt vmcnt(" #n ")" ::: "memory")
; #define PG8_WAIT_L(n) asm volatile("s_waitcnt lgkmcnt(" #n ")" ::: "memory")
; #define PG8_BAR __builtin_amdgcn_s_barrier()
; #define PG8_SCHED __builtin_amdgcn_sched_barrier(0)
; template <class Epi, class Sched, bool ALIGN_EPI = false, bool SP2 = false>
; __device__ __forceinline__ void gemm_phase(PG8_LAS unsigned char* lds, const Gemm g, const Sched& S, const Epi& E) {
;     ...
;             PG8_LDB(B0, 0, 0); PG8_LDB(B1, 0, 1); PG8_SCHED; PG8_LDA(At, 0, 0); PG8_STAGE(PG8_SA(1, 1), a1 + hstep, voffA);
;             PG8_WAIT_V(8); PG8_WAIT_L(0); PG8_BAR; PG8_MMA(0, 0, At, B0); PG8_MMA(0, 1, At, B1); PG8_BAR; PG8_SCHED;
;             PG8_LDA(At, 0, 1); PG8_STAGE(PG8_SB(0, 0), b2, voffB); PG8_STAGE(PG8_SB(0, 1), b2 + hstep, voffB); PG8_STAGE(PG8_SA(0, 0), a2, voffA);
;             PG8_WAIT_V(8); PG8_WAIT_L(0); PG8_BAR; PG8_MMA(1, 0, At, B0); PG8_MMA(1, 1, At, B1); PG8_BAR; PG8_SCHED;
.LBB0_1272:
	ds_read_b128 v[128:131], v167
	ds_read_b128 v[132:135], v167 offset:1024
	ds_read_b128 v[136:139], v167 offset:2048
	ds_read_b128 v[140:143], v167 offset:3072
	ds_read_b128 v[160:163], v168
	ds_read_b128 v[170:173], v168 offset:1024
	ds_read_b128 v[174:177], v168 offset:2048
	ds_read_b128 v[178:181], v168 offset:3072
	s_add_u32 s12, s50, 0xfffc0080
	s_addc_u32 s13, s51, -1
	s_cmp_eq_u32 s79, 12
	s_cselect_b32 s55, s41, s13
	s_cselect_b32 s54, s47, s12
	s_cselect_b32 s53, s39, s78
	s_cselect_b32 s52, s49, s77
	s_add_i32 m0, s60, 0xc000
	ds_read_b128 v[188:191], v169
	ds_read_b128 v[192:195], v169 offset:1024
	ds_read_b128 v[196:199], v169 offset:2048
	ds_read_b128 v[200:203], v169 offset:3072
	ds_read_b128 v[204:207], v169 offset:4096
	ds_read_b128 v[208:211], v169 offset:5120
	ds_read_b128 v[212:215], v169 offset:6144
	ds_read_b128 v[216:219], v169 offset:7168
	global_load_lds_dwordx4 v154, s[50:51]
	s_add_i32 m0, s60, 0xe000
	s_nop 0
	global_load_lds_dwordx4 v152, s[50:51]
	s_waitcnt vmcnt(8)
	s_waitcnt lgkmcnt(0)
	s_barrier
	s_setprio 1
	s_waitcnt lgkmcnt(0)
	v_mfma_f32_16x16x32_bf16 v[124:127], v[128:131], v[188:191], v[124:127]
	v_mfma_f32_16x16x32_bf16 v[124:127], v[132:135], v[192:195], v[124:127]
	v_mfma_f32_16x16x32_bf16 v[120:123], v[136:139], v[188:191], v[120:123]
	v_mfma_f32_16x16x32_bf16 v[120:123], v[140:143], v[192:195], v[120:123]
	v_mfma_f32_16x16x32_bf16 v[108:111], v[136:139], v[196:199], v[108:111]
	v_mfma_f32_16x16x32_bf16 v[108:111], v[140:143], v[200:203], v[108:111]
	v_mfma_f32_16x16x32_bf16 v[116:119], v[128:131], v[196:199], v[116:119]
	v_mfma_f32_16x16x32_bf16 v[116:119], v[132:135], v[200:203], v[116:119]
	v_mfma_f32_16x16x32_bf16 v[100:103], v[128:131], v[204:207], v[100:103]
	v_mfma_f32_16x16x32_bf16 v[100:103], v[132:135], v[208:211], v[100:103]
	v_mfma_f32_16x16x32_bf16 v[92:95], v[136:139], v[204:207], v[92:95]
	v_mfma_f32_16x16x32_bf16 v[92:95], v[140:143], v[208:211], v[92:95]
	v_mfma_f32_16x16x32_bf16 v[76:79], v[136:139], v[212:215], v[76:79]
	v_mfma_f32_16x16x32_bf16 v[76:79], v[140:143], v[216:219], v[76:79]
	v_mfma_f32_16x16x32_bf16 v[84:87], v[128:131], v[212:215], v[84:87]
	v_mfma_f32_16x16x32_bf16 v[84:87], v[132:135], v[216:219], v[84:87]
	v_mfma_f32_16x16x32_bf16 v[112:115], v[160:163], v[188:191], v[112:115]
	v_mfma_f32_16x16x32_bf16 v[112:115], v[170:173], v[192:195], v[112:115]
	v_mfma_f32_16x16x32_bf16 v[104:107], v[174:177], v[188:191], v[104:107]
	v_mfma_f32_16x16x32_bf16 v[104:107], v[178:181], v[192:195], v[104:107]
	v_mfma_f32_16x16x32_bf16 v[88:91], v[174:177], v[196:199], v[88:91]
	v_mfma_f32_16x16x32_bf16 v[88:91], v[178:181], v[200:203], v[88:91]
	v_mfma_f32_16x16x32_bf16 v[96:99], v[160:163], v[196:199], v[96:99]
	v_mfma_f32_16x16x32_bf16 v[96:99], v[170:173], v[200:203], v[96:99]
	v_mfma_f32_16x16x32_bf16 v[80:83], v[160:163], v[204:207], v[80:83]
	v_mfma_f32_16x16x32_bf16 v[80:83], v[170:173], v[208:211], v[80:83]
	v_mfma_f32_16x16x32_bf16 v[72:75], v[174:177], v[204:207], v[72:75]
	v_mfma_f32_16x16x32_bf16 v[72:75], v[178:181], v[208:211], v[72:75]
	v_mfma_f32_16x16x32_bf16 v[64:67], v[174:177], v[212:215], v[64:67]
	v_mfma_f32_16x16x32_bf16 v[64:67], v[178:181], v[216:219], v[64:67]
	v_mfma_f32_16x16x32_bf16 v[68:71], v[160:163], v[212:215], v[68:71]
	v_mfma_f32_16x16x32_bf16 v[68:71], v[170:173], v[216:219], v[68:71]
	s_setprio 0
	s_barrier
	s_add_i32 s12, s75, s59
	s_mov_b32 m0, s12
	ds_read_b128 v[188:191], v169 offset:16384
	ds_read_b128 v[192:195], v169 offset:17408
	ds_read_b128 v[196:199], v169 offset:18432
	ds_read_b128 v[200:203], v169 offset:19456
	ds_read_b128 v[204:207], v169 offset:20480
	ds_read_b128 v[208:211], v169 offset:21504
	ds_read_b128 v[212:215], v169 offset:22528
	ds_read_b128 v[216:219], v169 offset:23552
	global_load_lds_dwordx4 v146, s[52:53]
	s_add_i32 m0, s12, 0x2000
	s_add_u32 s80, s52, 0x40000
	v_lshl_add_u64 v[220:221], s[52:53], 0, v[150:151]
	s_addc_u32 s81, s53, 0
	s_add_i32 s12, s76, s59
	global_load_lds_dwordx4 v150, s[52:53]
	s_mov_b32 m0, s12
	v_lshl_add_u64 v[224:225], s[54:55], 0, v[148:149]
	global_load_lds_dwordx4 v146, s[80:81]
	s_add_i32 m0, s12, 0x2000
	s_nop 0
	global_load_lds_dwordx4 v150, s[80:81]
	v_lshl_add_u64 v[222:223], s[54:55], 0, v[144:145]
	s_mov_b32 m0, s60
	s_nop 0
	global_load_lds_dwordx4 v144, s[54:55]
	s_mov_b32 m0, s61
	s_nop 0
	global_load_lds_dwordx4 v148, s[54:55]
	s_waitcnt vmcnt(8)
	s_waitcnt lgkmcnt(0)
	s_barrier
	s_setprio 1
	s_waitcnt lgkmcnt(0)
	v_mfma_f32_16x16x32_bf16 v[60:63], v[128:131], v[188:191], v[60:63]
	v_mfma_f32_16x16x32_bf16 v[60:63], v[132:135], v[192:195], v[60:63]
	v_mfma_f32_16x16x32_bf16 v[56:59], v[136:139], v[188:191], v[56:59]
	v_mfma_f32_16x16x32_bf16 v[56:59], v[140:143], v[192:195], v[56:59]
	v_mfma_f32_16x16x32_bf16 v[44:47], v[136:139], v[196:199], v[44:47]
	v_mfma_f32_16x16x32_bf16 v[44:47], v[140:143], v[200:203], v[44:47]
	v_mfma_f32_16x16x32_bf16 v[48:51], v[128:131], v[196:199], v[48:51]
	v_mfma_f32_16x16x32_bf16 v[48:51], v[132:135], v[200:203], v[48:51]
	v_mfma_f32_16x16x32_bf16 v[36:39], v[128:131], v[204:207], v[36:39]
	v_mfma_f32_16x16x32_bf16 v[36:39], v[132:135], v[208:211], v[36:39]
	v_mfma_f32_16x16x32_bf16 v[28:31], v[136:139], v[204:207], v[28:31]
	v_mfma_f32_16x16x32_bf16 v[28:31], v[140:143], v[208:211], v[28:31]
	v_mfma_f32_16x16x32_bf16 v[12:15], v[136:139], v[212:215], v[12:15]
	v_mfma_f32_16x16x32_bf16 v[12:15], v[140:143], v[216:219], v[12:15]
	v_mfma_f32_16x16x32_bf16 v[20:23], v[128:131], v[212:215], v[20:23]
	v_mfma_f32_16x16x32_bf16 v[20:23], v[132:135], v[216:219], v[20:23]
	v_mfma_f32_16x16x32_bf16 v[52:55], v[160:163], v[188:191], v[52:55]
	v_mfma_f32_16x16x32_bf16 v[52:55], v[170:173], v[192:195], v[52:55]
	v_mfma_f32_16x16x32_bf16 v[40:43], v[174:177], v[188:191], v[40:43]
	v_mfma_f32_16x16x32_bf16 v[40:43], v[178:181], v[192:195], v[40:43]
	v_mfma_f32_16x16x32_bf16 v[24:27], v[174:177], v[196:199], v[24:27]
	v_mfma_f32_16x16x32_bf16 v[24:27], v[178:181], v[200:203], v[24:27]
	v_mfma_f32_16x16x32_bf16 v[32:35], v[160:163], v[196:199], v[32:35]
	v_mfma_f32_16x16x32_bf16 v[32:35], v[170:173], v[200:203], v[32:35]
	v_mfma_f32_16x16x32_bf16 v[16:19], v[160:163], v[204:207], v[16:19]
	v_mfma_f32_16x16x32_bf16 v[16:19], v[170:173], v[208:211], v[16:19]
	v_mfma_f32_16x16x32_bf16 v[8:11], v[174:177], v[204:207], v[8:11]
	v_mfma_f32_16x16x32_bf16 v[8:11], v[178:181], v[208:211], v[8:11]
	v_mfma_f32_16x16x32_bf16 v[0:3], v[174:177], v[212:215], v[0:3]
	v_mfma_f32_16x16x32_bf16 v[0:3], v[178:181], v[216:219], v[0:3]
	v_mfma_f32_16x16x32_bf16 v[4:7], v[160:163], v[212:215], v[4:7]
	v_mfma_f32_16x16x32_bf16 v[4:7], v[170:173], v[216:219], v[4:7]
	s_setprio 0
	s_barrier
; #define PG8_STAGE(bufoff, gbase, voff) do { _Pragma("unroll") for (int _i = 0; _i < 2; ++_i) \
;         __builtin_amdgcn_global_load_lds((const unsigned*)((const char*)(gbase) + (voff)[_i]), (PG8_LAS unsigned*)(lds + (bufoff) + ldsw + _i * 8192), 16, 0, 0); } while (0)
; #define PG8_LDA(dst, b, h) do { _Pragma("unroll") for (int m = 0; m < 4; ++m) _Pragma("unroll") for (int k = 0; k < 2; ++k) dst[m][k] = *(const PG8_LAS bf16x8*)(lds + PG8_SA(b, h) + aoff + m * 2048 + k * 1024); } while (0)
; #define PG8_LDB(dst, b, h) do { _Pragma("unroll") for (int n = 0; n < 2; ++n) _Pragma("unroll") for (int k = 0; k < 2; ++k) dst[n][k] = *(const PG8_LAS bf16x8*)(lds + PG8_SB(b, h) + boff + n * 2048 + k * 1024); } while (0)
; #define PG8_MMA(ai, bj, At, Bt) do { __builtin_amdgcn_s_setprio(1); _Pragma("unroll") for (int m = 0; m < 4; ++m) _Pragma("unroll") for (int n = 0; n < 2; ++n) _Pragma("unroll") for (int k = 0; k < 2; ++k) \
;         acc[ai][bj][m][n] = __builtin_amdgcn_mfma_f32_16x16x32_bf16(Bt[n][k], At[m][k], acc[ai][bj][m][n], 0, 0, 0); __builtin_amdgcn_s_setprio(0); } while (0)
; #define PG8_WAIT_V(n) asm volatile("s_waitcnt vmcnt(" #n ")" ::: "memory")
; #define PG8_WAIT_L(n) asm volatile("s_waitcnt lgkmcnt(" #n ")" ::: "memory")
; #define PG8_BAR __builtin_amdgcn_s_barrier()
; #define PG8_SCHED __builtin_amdgcn_sched_barrier(0)
; template <class Epi, class Sched, bool ALIGN_EPI = false, bool SP2 = false>
; __device__ __forceinline__ void gemm_phase(PG8_LAS unsigned char* lds, const Gemm g, const Sched& S, const Epi& E) {
;     ...
;             PG8_LDB(B0, 1, 0); PG8_LDB(B1, 1, 1); PG8_SCHED; PG8_LDA(At, 1, 0); PG8_STAGE(PG8_SA(0, 1), a2 + hstep, voffA);
;             PG8_WAIT_V(8); PG8_WAIT_L(0); PG8_BAR; PG8_MMA(0, 0, At, B0); PG8_MMA(0, 1, At, B1); PG8_BAR; PG8_SCHED;
;             PG8_LDA(At, 1, 1); PG8_STAGE(PG8_SB(1, 0), b3, voffB); PG8_STAGE(PG8_SB(1, 1), b3 + hstep, voffB); PG8_STAGE(PG8_SA(1, 0), a3, voffA);
;             PG8_WAIT_V(8); PG8_WAIT_L(0); PG8_BAR; PG8_MMA(1, 0, At, B0); PG8_MMA(1, 1, At, B1); PG8_BAR; PG8_SCHED;
	s_add_i32 s12, 0, 0x18000
	s_add_i32 s13, 0, 0x1c000
	v_add_u32_e32 v140, s12, v165
	v_add_u32_e32 v178, s13, v165
	ds_read_b128 v[128:131], v140
	ds_read_b128 v[132:135], v140 offset:1024
	ds_read_b128 v[136:139], v140 offset:2048
	ds_read_b128 v[140:143], v140 offset:3072
	ds_read_b128 v[160:163], v178
	ds_read_b128 v[170:173], v178 offset:1024
	ds_read_b128 v[174:177], v178 offset:2048
	ds_read_b128 v[178:181], v178 offset:3072
	s_add_u32 s54, s54, 0x40000
	s_addc_u32 s55, s55, 0
	s_mov_b32 m0, s62
	ds_read_b128 v[188:191], v169 offset:32768
	ds_read_b128 v[192:195], v169 offset:33792
	ds_read_b128 v[196:199], v169 offset:34816
	ds_read_b128 v[200:203], v169 offset:35840
	ds_read_b128 v[204:207], v169 offset:36864
	ds_read_b128 v[208:211], v169 offset:37888
	ds_read_b128 v[212:215], v169 offset:38912
	ds_read_b128 v[216:219], v169 offset:39936
	global_load_lds_dwordx4 v144, s[54:55]
	s_mov_b32 m0, s63
	s_nop 0
	global_load_lds_dwordx4 v148, s[54:55]
	s_waitcnt vmcnt(8)
	s_waitcnt lgkmcnt(0)
	s_barrier
	s_setprio 1
	s_waitcnt lgkmcnt(0)
	v_mfma_f32_16x16x32_bf16 v[124:127], v[128:131], v[188:191], v[124:127]
	v_mfma_f32_16x16x32_bf16 v[124:127], v[132:135], v[192:195], v[124:127]
	v_mfma_f32_16x16x32_bf16 v[120:123], v[136:139], v[188:191], v[120:123]
	v_mfma_f32_16x16x32_bf16 v[120:123], v[140:143], v[192:195], v[120:123]
	v_mfma_f32_16x16x32_bf16 v[108:111], v[136:139], v[196:199], v[108:111]
	v_mfma_f32_16x16x32_bf16 v[108:111], v[140:143], v[200:203], v[108:111]
	v_mfma_f32_16x16x32_bf16 v[116:119], v[128:131], v[196:199], v[116:119]
	v_mfma_f32_16x16x32_bf16 v[116:119], v[132:135], v[200:203], v[116:119]
	v_mfma_f32_16x16x32_bf16 v[100:103], v[128:131], v[204:207], v[100:103]
	v_mfma_f32_16x16x32_bf16 v[100:103], v[132:135], v[208:211], v[100:103]
	v_mfma_f32_16x16x32_bf16 v[92:95], v[136:139], v[204:207], v[92:95]
	v_mfma_f32_16x16x32_bf16 v[92:95], v[140:143], v[208:211], v[92:95]
	v_mfma_f32_16x16x32_bf16 v[76:79], v[136:139], v[212:215], v[76:79]
	v_mfma_f32_16x16x32_bf16 v[76:79], v[140:143], v[216:219], v[76:79]
	v_mfma_f32_16x16x32_bf16 v[84:87], v[128:131], v[212:215], v[84:87]
	v_mfma_f32_16x16x32_bf16 v[84:87], v[132:135], v[216:219], v[84:87]
	v_mfma_f32_16x16x32_bf16 v[112:115], v[160:163], v[188:191], v[112:115]
	v_mfma_f32_16x16x32_bf16 v[112:115], v[170:173], v[192:195], v[112:115]
	v_mfma_f32_16x16x32_bf16 v[104:107], v[174:177], v[188:191], v[104:107]
	v_mfma_f32_16x16x32_bf16 v[104:107], v[178:181], v[192:195], v[104:107]
	v_mfma_f32_16x16x32_bf16 v[88:91], v[174:177], v[196:199], v[88:91]
	v_mfma_f32_16x16x32_bf16 v[88:91], v[178:181], v[200:203], v[88:91]
	v_mfma_f32_16x16x32_bf16 v[96:99], v[160:163], v[196:199], v[96:99]
	v_mfma_f32_16x16x32_bf16 v[96:99], v[170:173], v[200:203], v[96:99]
	v_mfma_f32_16x16x32_bf16 v[80:83], v[160:163], v[204:207], v[80:83]
	v_mfma_f32_16x16x32_bf16 v[80:83], v[170:173], v[208:211], v[80:83]
	v_mfma_f32_16x16x32_bf16 v[72:75], v[174:177], v[204:207], v[72:75]
	v_mfma_f32_16x16x32_bf16 v[72:75], v[178:181], v[208:211], v[72:75]
	v_mfma_f32_16x16x32_bf16 v[64:67], v[174:177], v[212:215], v[64:67]
	v_mfma_f32_16x16x32_bf16 v[64:67], v[178:181], v[216:219], v[64:67]
	v_mfma_f32_16x16x32_bf16 v[68:71], v[160:163], v[212:215], v[68:71]
	v_mfma_f32_16x16x32_bf16 v[68:71], v[170:173], v[216:219], v[68:71]
	s_setprio 0
	s_barrier
	s_add_i32 s12, s12, s59
	s_add_u32 s98, s52, s22
	s_addc_u32 s99, s53, s23
	s_mov_b32 m0, s12
	ds_read_b128 v[188:191], v169 offset:49152
	ds_read_b128 v[192:195], v169 offset:50176
	ds_read_b128 v[196:199], v169 offset:51200
	ds_read_b128 v[200:203], v169 offset:52224
	ds_read_b128 v[204:207], v169 offset:53248
	ds_read_b128 v[208:211], v169 offset:54272
	ds_read_b128 v[212:215], v169 offset:55296
	ds_read_b128 v[216:219], v169 offset:56320
	global_load_lds_dwordx4 v146, s[98:99]
	s_add_i32 m0, s12, 0x2000
	s_add_u32 s52, s52, 0x40080
	v_lshl_add_u64 v[184:185], v[220:221], 0, s[22:23]
	s_addc_u32 s53, s53, 0
	s_add_i32 s12, s13, s59
	global_load_lds_dwordx4 v[184:185], off
	s_mov_b32 m0, s12
	s_nop 0
	global_load_lds_dwordx4 v146, s[52:53]
	s_add_i32 m0, s12, 0x2000
	s_nop 0
	global_load_lds_dwordx4 v150, s[52:53]
	v_lshl_add_u64 v[184:185], v[222:223], 0, s[22:23]
	s_mov_b32 m0, s69
	s_nop 0
	global_load_lds_dwordx4 v[184:185], off
	v_lshl_add_u64 v[184:185], v[224:225], 0, s[22:23]
	s_mov_b32 m0, s70
	s_nop 0
	global_load_lds_dwordx4 v[184:185], off
	s_waitcnt vmcnt(8)
	s_waitcnt lgkmcnt(0)
	s_barrier
	s_setprio 1
	s_waitcnt lgkmcnt(0)
	v_mfma_f32_16x16x32_bf16 v[60:63], v[128:131], v[188:191], v[60:63]
	v_mfma_f32_16x16x32_bf16 v[60:63], v[132:135], v[192:195], v[60:63]
	v_mfma_f32_16x16x32_bf16 v[56:59], v[136:139], v[188:191], v[56:59]
	v_mfma_f32_16x16x32_bf16 v[56:59], v[140:143], v[192:195], v[56:59]
	v_mfma_f32_16x16x32_bf16 v[44:47], v[136:139], v[196:199], v[44:47]
	v_mfma_f32_16x16x32_bf16 v[44:47], v[140:143], v[200:203], v[44:47]
	v_mfma_f32_16x16x32_bf16 v[48:51], v[128:131], v[196:199], v[48:51]
	v_mfma_f32_16x16x32_bf16 v[48:51], v[132:135], v[200:203], v[48:51]
	v_mfma_f32_16x16x32_bf16 v[36:39], v[128:131], v[204:207], v[36:39]
	v_mfma_f32_16x16x32_bf16 v[36:39], v[132:135], v[208:211], v[36:39]
	v_mfma_f32_16x16x32_bf16 v[28:31], v[136:139], v[204:207], v[28:31]
	v_mfma_f32_16x16x32_bf16 v[28:31], v[140:143], v[208:211], v[28:31]
	v_mfma_f32_16x16x32_bf16 v[12:15], v[136:139], v[212:215], v[12:15]
	v_mfma_f32_16x16x32_bf16 v[12:15], v[140:143], v[216:219], v[12:15]
	v_mfma_f32_16x16x32_bf16 v[20:23], v[128:131], v[212:215], v[20:23]
	v_mfma_f32_16x16x32_bf16 v[20:23], v[132:135], v[216:219], v[20:23]
	v_mfma_f32_16x16x32_bf16 v[52:55], v[160:163], v[188:191], v[52:55]
	v_mfma_f32_16x16x32_bf16 v[52:55], v[170:173], v[192:195], v[52:55]
	v_mfma_f32_16x16x32_bf16 v[40:43], v[174:177], v[188:191], v[40:43]
	v_mfma_f32_16x16x32_bf16 v[40:43], v[178:181], v[192:195], v[40:43]
	v_mfma_f32_16x16x32_bf16 v[24:27], v[174:177], v[196:199], v[24:27]
	v_mfma_f32_16x16x32_bf16 v[24:27], v[178:181], v[200:203], v[24:27]
	v_mfma_f32_16x16x32_bf16 v[32:35], v[160:163], v[196:199], v[32:35]
	v_mfma_f32_16x16x32_bf16 v[32:35], v[170:173], v[200:203], v[32:35]
	v_mfma_f32_16x16x32_bf16 v[16:19], v[160:163], v[204:207], v[16:19]
	v_mfma_f32_16x16x32_bf16 v[16:19], v[170:173], v[208:211], v[16:19]
	v_mfma_f32_16x16x32_bf16 v[8:11], v[174:177], v[204:207], v[8:11]
	v_mfma_f32_16x16x32_bf16 v[8:11], v[178:181], v[208:211], v[8:11]
	v_mfma_f32_16x16x32_bf16 v[0:3], v[174:177], v[212:215], v[0:3]
	v_mfma_f32_16x16x32_bf16 v[0:3], v[178:181], v[216:219], v[0:3]
	v_mfma_f32_16x16x32_bf16 v[4:7], v[160:163], v[212:215], v[4:7]
	v_mfma_f32_16x16x32_bf16 v[4:7], v[170:173], v[216:219], v[4:7]
	s_setprio 0
	s_barrier
	s_add_i32 s79, s79, 2
	s_add_u32 s77, s77, 0x100
	s_addc_u32 s78, s78, 0
	s_add_u32 s50, s50, 0x100
	s_addc_u32 s51, s51, 0
	s_cmp_gt_u32 s79, 13
	s_cbranch_scc0 .LBB0_1272
	s_and_b64 vcc, exec, s[36:37]
	s_cbranch_vccz .LBB0_1275
	s_barrier

; #define PG8_STAGE(bufoff, gbase, voff) do { _Pragma("unroll") for (int _i = 0; _i < 2; ++_i) \
;         __builtin_amdgcn_global_load_lds((const unsigned*)((const char*)(gbase) + (voff)[_i]), (PG8_LAS unsigned*)(lds + (bufoff) + ldsw + _i * 8192), 16, 0, 0); } while (0)
; #define PG8_LDA(dst, b, h) do { _Pragma("unroll") for (int m = 0; m < 4; ++m) _Pragma("unroll") for (int k = 0; k < 2; ++k) dst[m][k] = *(const PG8_LAS bf16x8*)(lds + PG8_SA(b, h) + aoff + m * 2048 + k * 1024); } while (0)
; #define PG8_LDB(dst, b, h) do { _Pragma("unroll") for (int n = 0; n < 2; ++n) _Pragma("unroll") for (int k = 0; k < 2; ++k) dst[n][k] = *(const PG8_LAS bf16x8*)(lds + PG8_SB(b, h) + boff + n * 2048 + k * 1024); } while (0)
; #define PG8_MMA(ai, bj, At, Bt) do { __builtin_amdgcn_s_setprio(1); _Pragma("unroll") for (int m = 0; m < 4; ++m) _Pragma("unroll") for (int n = 0; n < 2; ++n) _Pragma("unroll") for (int k = 0; k < 2; ++k) \
;         acc[ai][bj][m][n] = __builtin_amdgcn_mfma_f32_16x16x32_bf16(Bt[n][k], At[m][k], acc[ai][bj][m][n], 0, 0, 0); __builtin_amdgcn_s_setprio(0); } while (0)
; #define PG8_WAIT_V(n) asm volatile("s_waitcnt vmcnt(" #n ")" ::: "memory")
; #define PG8_WAIT_L(n) asm volatile("s_waitcnt lgkmcnt(" #n ")" ::: "memory")
; #define PG8_BAR __builtin_amdgcn_s_barrier()
; #define PG8_SCHED __builtin_amdgcn_sched_barrier(0)
; template <class Epi, class Sched, bool ALIGN_EPI = false, bool SP2 = false>
; __device__ __forceinline__ void gemm_phase(PG8_LAS unsigned char* lds, const Gemm g, const Sched& S, const Epi& E) {
;     ...
;             PG8_LDB(B0, 0, 0); PG8_LDB(B1, 0, 1); PG8_SCHED; PG8_LDA(At, 0, 0); PG8_STAGE(PG8_SA(1, 1), a1 + hstep, voffA);
;             PG8_WAIT_V(8); PG8_WAIT_L(0); PG8_BAR; PG8_MMA(0, 0, At, B0); PG8_MMA(0, 1, At, B1); PG8_BAR; PG8_SCHED;
;             PG8_LDA(At, 0, 1); PG8_STAGE(PG8_SB(0, 0), b2, voffB); PG8_STAGE(PG8_SB(0, 1), b2 + hstep, voffB); PG8_STAGE(PG8_SA(0, 0), a2, voffA);
;             PG8_WAIT_V(8); PG8_WAIT_L(0); PG8_BAR; PG8_MMA(1, 0, At, B0); PG8_MMA(1, 1, At, B1); PG8_BAR; PG8_SCHED;
.LBB0_1358:
	v_add_u32_e32 v130, s71, v163
	ds_read_b128 v[118:121], v130
	ds_read_b128 v[122:125], v130 offset:1024
	ds_read_b128 v[126:129], v130 offset:2048
	ds_read_b128 v[170:173], v130 offset:3072
	v_add_u32_e32 v130, s72, v163
	ds_read_b128 v[174:177], v130
	ds_read_b128 v[178:181], v130 offset:1024
	ds_read_b128 v[184:187], v130 offset:2048
	ds_read_b128 v[188:191], v130 offset:3072
	s_add_u32 s14, s48, 0xfffc0080
	s_addc_u32 s15, s49, -1
	s_and_b64 s[50:51], s[50:51], exec
	s_cselect_b32 s53, s39, s15
	s_cselect_b32 s52, s73, s14
	s_cselect_b32 s51, s37, s47
	s_cselect_b32 s50, s74, s45
	s_add_i32 m0, s58, 0xc000
	ds_read_b128 v[192:195], v168
	ds_read_b128 v[196:199], v168 offset:1024
	ds_read_b128 v[200:203], v168 offset:2048
	ds_read_b128 v[204:207], v168 offset:3072
	ds_read_b128 v[208:211], v168 offset:4096
	ds_read_b128 v[212:215], v168 offset:5120
	ds_read_b128 v[216:219], v168 offset:6144
	ds_read_b128 v[220:223], v168 offset:7168
	global_load_lds_dwordx4 v154, s[48:49]
	s_add_i32 m0, s58, 0xe000
	s_nop 0
	global_load_lds_dwordx4 v152, s[48:49]
	s_waitcnt vmcnt(8)
	s_waitcnt lgkmcnt(0)
	s_barrier
	s_setprio 1
	s_waitcnt lgkmcnt(0)
	v_mfma_f32_16x16x32_bf16 v[140:143], v[118:121], v[192:195], v[140:143]
	v_mfma_f32_16x16x32_bf16 v[140:143], v[122:125], v[196:199], v[140:143]
	v_mfma_f32_16x16x32_bf16 v[136:139], v[126:129], v[192:195], v[136:139]
	v_mfma_f32_16x16x32_bf16 v[136:139], v[170:173], v[196:199], v[136:139]
	v_mfma_f32_16x16x32_bf16 v[104:107], v[126:129], v[200:203], v[104:107]
	v_mfma_f32_16x16x32_bf16 v[104:107], v[170:173], v[204:207], v[104:107]
	v_mfma_f32_16x16x32_bf16 v[108:111], v[118:121], v[200:203], v[108:111]
	v_mfma_f32_16x16x32_bf16 v[108:111], v[122:125], v[204:207], v[108:111]
	v_mfma_f32_16x16x32_bf16 v[92:95], v[118:121], v[208:211], v[92:95]
	v_mfma_f32_16x16x32_bf16 v[92:95], v[122:125], v[212:215], v[92:95]
	v_mfma_f32_16x16x32_bf16 v[88:91], v[126:129], v[208:211], v[88:91]
	v_mfma_f32_16x16x32_bf16 v[88:91], v[170:173], v[212:215], v[88:91]
	v_mfma_f32_16x16x32_bf16 v[72:75], v[126:129], v[216:219], v[72:75]
	v_mfma_f32_16x16x32_bf16 v[72:75], v[170:173], v[220:223], v[72:75]
	v_mfma_f32_16x16x32_bf16 v[76:79], v[118:121], v[216:219], v[76:79]
	v_mfma_f32_16x16x32_bf16 v[76:79], v[122:125], v[220:223], v[76:79]
	v_mfma_f32_16x16x32_bf16 v[130:133], v[174:177], v[192:195], v[132:135]
	v_mfma_f32_16x16x32_bf16 v[130:133], v[178:181], v[196:199], v[130:133]
	v_mfma_f32_16x16x32_bf16 v[112:115], v[184:187], v[192:195], v[112:115]
	v_mfma_f32_16x16x32_bf16 v[112:115], v[188:191], v[196:199], v[112:115]
	v_mfma_f32_16x16x32_bf16 v[96:99], v[184:187], v[200:203], v[96:99]
	v_mfma_f32_16x16x32_bf16 v[96:99], v[188:191], v[204:207], v[96:99]
	v_mfma_f32_16x16x32_bf16 v[100:103], v[174:177], v[200:203], v[100:103]
	v_mfma_f32_16x16x32_bf16 v[100:103], v[178:181], v[204:207], v[100:103]
	v_mfma_f32_16x16x32_bf16 v[84:87], v[174:177], v[208:211], v[84:87]
	v_mfma_f32_16x16x32_bf16 v[84:87], v[178:181], v[212:215], v[84:87]
	v_mfma_f32_16x16x32_bf16 v[80:83], v[184:187], v[208:211], v[80:83]
	v_mfma_f32_16x16x32_bf16 v[80:83], v[188:191], v[212:215], v[80:83]
	v_mfma_f32_16x16x32_bf16 v[64:67], v[184:187], v[216:219], v[64:67]
	v_mfma_f32_16x16x32_bf16 v[64:67], v[188:191], v[220:223], v[64:67]
	v_mfma_f32_16x16x32_bf16 v[68:71], v[174:177], v[216:219], v[68:71]
	v_mfma_f32_16x16x32_bf16 v[68:71], v[178:181], v[220:223], v[68:71]
	s_setprio 0
	s_barrier
	s_add_i32 s14, s71, s55
	s_mov_b32 m0, s14
	ds_read_b128 v[192:195], v168 offset:16384
	ds_read_b128 v[196:199], v168 offset:17408
	ds_read_b128 v[200:203], v168 offset:18432
	ds_read_b128 v[204:207], v168 offset:19456
	ds_read_b128 v[208:211], v168 offset:20480
	ds_read_b128 v[212:215], v168 offset:21504
	ds_read_b128 v[216:219], v168 offset:22528
	ds_read_b128 v[220:223], v168 offset:23552
	global_load_lds_dwordx4 v148, s[50:51]
	s_add_i32 m0, s14, 0x2000
	s_add_u32 s76, s50, 0x40000
	v_lshl_add_u64 v[226:227], s[50:51], 0, v[144:145]
	s_addc_u32 s77, s51, 0
	s_add_i32 s14, s72, s55
	global_load_lds_dwordx4 v144, s[50:51]
	s_mov_b32 m0, s14
	v_lshl_add_u64 v[228:229], s[52:53], 0, v[150:151]
	global_load_lds_dwordx4 v148, s[76:77]
	s_add_i32 m0, s14, 0x2000
	v_lshl_add_u64 v[230:231], s[52:53], 0, v[146:147]
	global_load_lds_dwordx4 v144, s[76:77]
	s_mov_b32 m0, s58
	s_nop 0
	global_load_lds_dwordx4 v150, s[52:53]
	s_mov_b32 m0, s59
	s_nop 0
	global_load_lds_dwordx4 v146, s[52:53]
	s_waitcnt vmcnt(8)
	s_waitcnt lgkmcnt(0)
	s_barrier
	s_setprio 1
	s_waitcnt lgkmcnt(0)
	v_mfma_f32_16x16x32_bf16 v[60:63], v[118:121], v[192:195], v[60:63]
	v_mfma_f32_16x16x32_bf16 v[60:63], v[122:125], v[196:199], v[60:63]
	v_mfma_f32_16x16x32_bf16 v[56:59], v[126:129], v[192:195], v[56:59]
	v_mfma_f32_16x16x32_bf16 v[56:59], v[170:173], v[196:199], v[56:59]
	v_mfma_f32_16x16x32_bf16 v[40:43], v[126:129], v[200:203], v[40:43]
	v_mfma_f32_16x16x32_bf16 v[40:43], v[170:173], v[204:207], v[40:43]
	v_mfma_f32_16x16x32_bf16 v[44:47], v[118:121], v[200:203], v[44:47]
	v_mfma_f32_16x16x32_bf16 v[44:47], v[122:125], v[204:207], v[44:47]
	v_mfma_f32_16x16x32_bf16 v[28:31], v[118:121], v[208:211], v[28:31]
	v_mfma_f32_16x16x32_bf16 v[28:31], v[122:125], v[212:215], v[28:31]
	v_mfma_f32_16x16x32_bf16 v[24:27], v[126:129], v[208:211], v[24:27]
	v_mfma_f32_16x16x32_bf16 v[24:27], v[170:173], v[212:215], v[24:27]
	v_mfma_f32_16x16x32_bf16 v[8:11], v[126:129], v[216:219], v[8:11]
	v_mfma_f32_16x16x32_bf16 v[8:11], v[170:173], v[220:223], v[8:11]
	v_mfma_f32_16x16x32_bf16 v[12:15], v[118:121], v[216:219], v[12:15]
	v_mfma_f32_16x16x32_bf16 v[12:15], v[122:125], v[220:223], v[12:15]
	v_mfma_f32_16x16x32_bf16 v[52:55], v[174:177], v[192:195], v[52:55]
	v_mfma_f32_16x16x32_bf16 v[52:55], v[178:181], v[196:199], v[52:55]
	v_mfma_f32_16x16x32_bf16 v[48:51], v[184:187], v[192:195], v[48:51]
	v_mfma_f32_16x16x32_bf16 v[48:51], v[188:191], v[196:199], v[48:51]
	v_mfma_f32_16x16x32_bf16 v[32:35], v[184:187], v[200:203], v[32:35]
	v_mfma_f32_16x16x32_bf16 v[32:35], v[188:191], v[204:207], v[32:35]
	v_mfma_f32_16x16x32_bf16 v[36:39], v[174:177], v[200:203], v[36:39]
	v_mfma_f32_16x16x32_bf16 v[36:39], v[178:181], v[204:207], v[36:39]
	v_mfma_f32_16x16x32_bf16 v[20:23], v[174:177], v[208:211], v[20:23]
	v_mfma_f32_16x16x32_bf16 v[20:23], v[178:181], v[212:215], v[20:23]
	v_mfma_f32_16x16x32_bf16 v[16:19], v[184:187], v[208:211], v[16:19]
	v_mfma_f32_16x16x32_bf16 v[16:19], v[188:191], v[212:215], v[16:19]
	v_mfma_f32_16x16x32_bf16 v[0:3], v[184:187], v[216:219], v[0:3]
	v_mfma_f32_16x16x32_bf16 v[0:3], v[188:191], v[220:223], v[0:3]
	v_mfma_f32_16x16x32_bf16 v[4:7], v[174:177], v[216:219], v[4:7]
	v_mfma_f32_16x16x32_bf16 v[4:7], v[178:181], v[220:223], v[4:7]
	s_setprio 0
	s_barrier
; #define PG8_STAGE(bufoff, gbase, voff) do { _Pragma("unroll") for (int _i = 0; _i < 2; ++_i) \
;         __builtin_amdgcn_global_load_lds((const unsigned*)((const char*)(gbase) + (voff)[_i]), (PG8_LAS unsigned*)(lds + (bufoff) + ldsw + _i * 8192), 16, 0, 0); } while (0)
; #define PG8_LDA(dst, b, h) do { _Pragma("unroll") for (int m = 0; m < 4; ++m) _Pragma("unroll") for (int k = 0; k < 2; ++k) dst[m][k] = *(const PG8_LAS bf16x8*)(lds + PG8_SA(b, h) + aoff + m * 2048 + k * 1024); } while (0)
; #define PG8_LDB(dst, b, h) do { _Pragma("unroll") for (int n = 0; n < 2; ++n) _Pragma("unroll") for (int k = 0; k < 2; ++k) dst[n][k] = *(const PG8_LAS bf16x8*)(lds + PG8_SB(b, h) + boff + n * 2048 + k * 1024); } while (0)
; #define PG8_MMA(ai, bj, At, Bt) do { __builtin_amdgcn_s_setprio(1); _Pragma("unroll") for (int m = 0; m < 4; ++m) _Pragma("unroll") for (int n = 0; n < 2; ++n) _Pragma("unroll") for (int k = 0; k < 2; ++k) \
;         acc[ai][bj][m][n] = __builtin_amdgcn_mfma_f32_16x16x32_bf16(Bt[n][k], At[m][k], acc[ai][bj][m][n], 0, 0, 0); __builtin_amdgcn_s_setprio(0); } while (0)
; #define PG8_WAIT_V(n) asm volatile("s_waitcnt vmcnt(" #n ")" ::: "memory")
; #define PG8_WAIT_L(n) asm volatile("s_waitcnt lgkmcnt(" #n ")" ::: "memory")
; #define PG8_BAR __builtin_amdgcn_s_barrier()
; #define PG8_SCHED __builtin_amdgcn_sched_barrier(0)
; template <class Epi, class Sched, bool ALIGN_EPI = false, bool SP2 = false>
; __device__ __forceinline__ void gemm_phase(PG8_LAS unsigned char* lds, const Gemm g, const Sched& S, const Epi& E) {
;     ...
;             PG8_LDB(B0, 1, 0); PG8_LDB(B1, 1, 1); PG8_SCHED; PG8_LDA(At, 1, 0); PG8_STAGE(PG8_SA(0, 1), a2 + hstep, voffA);
;             PG8_WAIT_V(8); PG8_WAIT_L(0); PG8_BAR; PG8_MMA(0, 0, At, B0); PG8_MMA(0, 1, At, B1); PG8_BAR; PG8_SCHED;
;             PG8_LDA(At, 1, 1); PG8_STAGE(PG8_SB(1, 0), b3, voffB); PG8_STAGE(PG8_SB(1, 1), b3 + hstep, voffB); PG8_STAGE(PG8_SA(1, 0), a3, voffA);
;             PG8_WAIT_V(8); PG8_WAIT_L(0); PG8_BAR; PG8_MMA(1, 0, At, B0); PG8_MMA(1, 1, At, B1); PG8_BAR; PG8_SCHED;
	s_add_i32 s14, 0, 0x18000
	v_add_u32_e32 v134, s14, v163
	s_add_i32 s15, 0, 0x1c000
	ds_read_b128 v[118:121], v134
	ds_read_b128 v[122:125], v134 offset:1024
	ds_read_b128 v[126:129], v134 offset:2048
	ds_read_b128 v[170:173], v134 offset:3072
	v_add_u32_e32 v134, s15, v163
	ds_read_b128 v[174:177], v134
	ds_read_b128 v[178:181], v134 offset:1024
	ds_read_b128 v[184:187], v134 offset:2048
	ds_read_b128 v[188:191], v134 offset:3072
	s_add_u32 s52, s52, 0x40000
	s_addc_u32 s53, s53, 0
	s_mov_b32 m0, s60
	ds_read_b128 v[192:195], v168 offset:32768
	ds_read_b128 v[196:199], v168 offset:33792
	ds_read_b128 v[200:203], v168 offset:34816
	ds_read_b128 v[204:207], v168 offset:35840
	ds_read_b128 v[208:211], v168 offset:36864
	ds_read_b128 v[212:215], v168 offset:37888
	ds_read_b128 v[216:219], v168 offset:38912
	ds_read_b128 v[220:223], v168 offset:39936
	global_load_lds_dwordx4 v150, s[52:53]
	s_mov_b32 m0, s61
	s_nop 0
	global_load_lds_dwordx4 v146, s[52:53]
	s_waitcnt vmcnt(8)
	s_waitcnt lgkmcnt(0)
	s_barrier
	s_setprio 1
	s_waitcnt lgkmcnt(0)
	v_mfma_f32_16x16x32_bf16 v[140:143], v[118:121], v[192:195], v[140:143]
	v_mfma_f32_16x16x32_bf16 v[140:143], v[122:125], v[196:199], v[140:143]
	v_mfma_f32_16x16x32_bf16 v[134:137], v[126:129], v[192:195], v[136:139]
	v_mfma_f32_16x16x32_bf16 v[136:139], v[170:173], v[196:199], v[134:137]
	v_mfma_f32_16x16x32_bf16 v[104:107], v[126:129], v[200:203], v[104:107]
	v_mfma_f32_16x16x32_bf16 v[104:107], v[170:173], v[204:207], v[104:107]
	v_mfma_f32_16x16x32_bf16 v[108:111], v[118:121], v[200:203], v[108:111]
	v_mfma_f32_16x16x32_bf16 v[108:111], v[122:125], v[204:207], v[108:111]
	v_mfma_f32_16x16x32_bf16 v[92:95], v[118:121], v[208:211], v[92:95]
	v_mfma_f32_16x16x32_bf16 v[92:95], v[122:125], v[212:215], v[92:95]
	v_mfma_f32_16x16x32_bf16 v[88:91], v[126:129], v[208:211], v[88:91]
	v_mfma_f32_16x16x32_bf16 v[88:91], v[170:173], v[212:215], v[88:91]
	v_mfma_f32_16x16x32_bf16 v[72:75], v[126:129], v[216:219], v[72:75]
	v_mfma_f32_16x16x32_bf16 v[72:75], v[170:173], v[220:223], v[72:75]
	v_mfma_f32_16x16x32_bf16 v[76:79], v[118:121], v[216:219], v[76:79]
	v_mfma_f32_16x16x32_bf16 v[76:79], v[122:125], v[220:223], v[76:79]
	v_mfma_f32_16x16x32_bf16 v[130:133], v[174:177], v[192:195], v[130:133]
	v_mfma_f32_16x16x32_bf16 v[132:135], v[178:181], v[196:199], v[130:133]
	v_mfma_f32_16x16x32_bf16 v[112:115], v[184:187], v[192:195], v[112:115]
	v_mfma_f32_16x16x32_bf16 v[112:115], v[188:191], v[196:199], v[112:115]
	v_mfma_f32_16x16x32_bf16 v[96:99], v[184:187], v[200:203], v[96:99]
	v_mfma_f32_16x16x32_bf16 v[96:99], v[188:191], v[204:207], v[96:99]
	v_mfma_f32_16x16x32_bf16 v[100:103], v[174:177], v[200:203], v[100:103]
	v_mfma_f32_16x16x32_bf16 v[100:103], v[178:181], v[204:207], v[100:103]
	v_mfma_f32_16x16x32_bf16 v[84:87], v[174:177], v[208:211], v[84:87]
	v_mfma_f32_16x16x32_bf16 v[84:87], v[178:181], v[212:215], v[84:87]
	v_mfma_f32_16x16x32_bf16 v[80:83], v[184:187], v[208:211], v[80:83]
	v_mfma_f32_16x16x32_bf16 v[80:83], v[188:191], v[212:215], v[80:83]
	v_mfma_f32_16x16x32_bf16 v[64:67], v[184:187], v[216:219], v[64:67]
	v_mfma_f32_16x16x32_bf16 v[64:67], v[188:191], v[220:223], v[64:67]
	v_mfma_f32_16x16x32_bf16 v[68:71], v[174:177], v[216:219], v[68:71]
	v_mfma_f32_16x16x32_bf16 v[68:71], v[178:181], v[220:223], v[68:71]
	s_setprio 0
	s_barrier
	s_add_i32 s14, s14, s55
	s_add_u32 s98, s50, s18
	s_addc_u32 s99, s51, s19
	s_mov_b32 m0, s14
	ds_read_b128 v[192:195], v168 offset:49152
	ds_read_b128 v[196:199], v168 offset:50176
	ds_read_b128 v[200:203], v168 offset:51200
	ds_read_b128 v[204:207], v168 offset:52224
	ds_read_b128 v[208:211], v168 offset:53248
	ds_read_b128 v[212:215], v168 offset:54272
	ds_read_b128 v[216:219], v168 offset:55296
	ds_read_b128 v[220:223], v168 offset:56320
	global_load_lds_dwordx4 v148, s[98:99]
	s_add_i32 m0, s14, 0x2000
	s_add_u32 s50, s50, 0x40080
	v_lshl_add_u64 v[130:131], v[226:227], 0, s[18:19]
	s_addc_u32 s51, s51, 0
	s_add_i32 s14, s15, s55
	global_load_lds_dwordx4 v[130:131], off
	s_mov_b32 m0, s14
	s_nop 0
	global_load_lds_dwordx4 v148, s[50:51]
	s_add_i32 m0, s14, 0x2000
	s_nop 0
	global_load_lds_dwordx4 v144, s[50:51]
	v_lshl_add_u64 v[130:131], v[228:229], 0, s[18:19]
	s_mov_b32 m0, s64
	s_nop 0
	global_load_lds_dwordx4 v[130:131], off
	v_lshl_add_u64 v[130:131], v[230:231], 0, s[18:19]
	s_mov_b32 m0, s65
	s_nop 0
	global_load_lds_dwordx4 v[130:131], off
	s_waitcnt vmcnt(8)
	s_waitcnt lgkmcnt(0)
	s_barrier
	s_setprio 1
	s_waitcnt lgkmcnt(0)
	v_mfma_f32_16x16x32_bf16 v[60:63], v[118:121], v[192:195], v[60:63]
	v_mfma_f32_16x16x32_bf16 v[60:63], v[122:125], v[196:199], v[60:63]
	v_mfma_f32_16x16x32_bf16 v[56:59], v[126:129], v[192:195], v[56:59]
	v_mfma_f32_16x16x32_bf16 v[56:59], v[170:173], v[196:199], v[56:59]
	v_mfma_f32_16x16x32_bf16 v[40:43], v[126:129], v[200:203], v[40:43]
	v_mfma_f32_16x16x32_bf16 v[40:43], v[170:173], v[204:207], v[40:43]
	v_mfma_f32_16x16x32_bf16 v[44:47], v[118:121], v[200:203], v[44:47]
	v_mfma_f32_16x16x32_bf16 v[44:47], v[122:125], v[204:207], v[44:47]
	v_mfma_f32_16x16x32_bf16 v[28:31], v[118:121], v[208:211], v[28:31]
	v_mfma_f32_16x16x32_bf16 v[28:31], v[122:125], v[212:215], v[28:31]
	v_mfma_f32_16x16x32_bf16 v[24:27], v[126:129], v[208:211], v[24:27]
	v_mfma_f32_16x16x32_bf16 v[24:27], v[170:173], v[212:215], v[24:27]
	v_mfma_f32_16x16x32_bf16 v[8:11], v[126:129], v[216:219], v[8:11]
	v_mfma_f32_16x16x32_bf16 v[8:11], v[170:173], v[220:223], v[8:11]
	v_mfma_f32_16x16x32_bf16 v[12:15], v[118:121], v[216:219], v[12:15]
	v_mfma_f32_16x16x32_bf16 v[12:15], v[122:125], v[220:223], v[12:15]
	v_mfma_f32_16x16x32_bf16 v[52:55], v[174:177], v[192:195], v[52:55]
	v_mfma_f32_16x16x32_bf16 v[52:55], v[178:181], v[196:199], v[52:55]
	v_mfma_f32_16x16x32_bf16 v[48:51], v[184:187], v[192:195], v[48:51]
	v_mfma_f32_16x16x32_bf16 v[48:51], v[188:191], v[196:199], v[48:51]
	v_mfma_f32_16x16x32_bf16 v[32:35], v[184:187], v[200:203], v[32:35]
	v_mfma_f32_16x16x32_bf16 v[32:35], v[188:191], v[204:207], v[32:35]
	v_mfma_f32_16x16x32_bf16 v[36:39], v[174:177], v[200:203], v[36:39]
	v_mfma_f32_16x16x32_bf16 v[36:39], v[178:181], v[204:207], v[36:39]
	v_mfma_f32_16x16x32_bf16 v[20:23], v[174:177], v[208:211], v[20:23]
	v_mfma_f32_16x16x32_bf16 v[20:23], v[178:181], v[212:215], v[20:23]
	v_mfma_f32_16x16x32_bf16 v[16:19], v[184:187], v[208:211], v[16:19]
	v_mfma_f32_16x16x32_bf16 v[16:19], v[188:191], v[212:215], v[16:19]
	v_mfma_f32_16x16x32_bf16 v[0:3], v[184:187], v[216:219], v[0:3]
	v_mfma_f32_16x16x32_bf16 v[0:3], v[188:191], v[220:223], v[0:3]
	v_mfma_f32_16x16x32_bf16 v[4:7], v[174:177], v[216:219], v[4:7]
	v_mfma_f32_16x16x32_bf16 v[4:7], v[178:181], v[220:223], v[4:7]
	s_setprio 0
	s_barrier
	s_add_i32 s75, s75, 2
	s_add_u32 s45, s45, 0x100
	s_addc_u32 s47, s47, 0
	s_add_u32 s48, s48, 0x100
	s_addc_u32 s49, s49, 0
	s_cmp_gt_u32 s75, 13
	s_cbranch_scc1 .LBB0_1361

; #define PG8_STAGE(bufoff, gbase, voff) do { _Pragma("unroll") for (int _i = 0; _i < 2; ++_i) \
;         __builtin_amdgcn_global_load_lds((const unsigned*)((const char*)(gbase) + (voff)[_i]), (PG8_LAS unsigned*)(lds + (bufoff) + ldsw + _i * 8192), 16, 0, 0); } while (0)
; #define PG8_LDA(dst, b, h) do { _Pragma("unroll") for (int m = 0; m < 4; ++m) _Pragma("unroll") for (int k = 0; k < 2; ++k) dst[m][k] = *(const PG8_LAS bf16x8*)(lds + PG8_SA(b, h) + aoff + m * 2048 + k * 1024); } while (0)
; #define PG8_LDB(dst, b, h) do { _Pragma("unroll") for (int n = 0; n < 2; ++n) _Pragma("unroll") for (int k = 0; k < 2; ++k) dst[n][k] = *(const PG8_LAS bf16x8*)(lds + PG8_SB(b, h) + boff + n * 2048 + k * 1024); } while (0)
; #define PG8_MMA(ai, bj, At, Bt) do { __builtin_amdgcn_s_setprio(1); _Pragma("unroll") for (int m = 0; m < 4; ++m) _Pragma("unroll") for (int n = 0; n < 2; ++n) _Pragma("unroll") for (int k = 0; k < 2; ++k) \
;         acc[ai][bj][m][n] = __builtin_amdgcn_mfma_f32_16x16x32_bf16(Bt[n][k], At[m][k], acc[ai][bj][m][n], 0, 0, 0); __builtin_amdgcn_s_setprio(0); } while (0)
; #define PG8_WAIT_V(n) asm volatile("s_waitcnt vmcnt(" #n ")" ::: "memory")
; #define PG8_BAR __builtin_amdgcn_s_barrier()
; template <class Epi, class Sched, bool ALIGN_EPI = false, bool SP2 = false>
; __device__ __forceinline__ void gemm_phase(PG8_LAS unsigned char* lds, const Gemm g, const Sched& S, const Epi& E) {
;     ...
;             const bool last = (t == nt - 2);
;             const char* a1 = cA + (size_t)(t + 1) * kstep;
;             const char* a2 = last ? nA : cA + (size_t)(t + 2) * kstep; const char* b2 = last ? nB : cB + (size_t)(t + 2) * kstep;
;             const char* a3 = a2 + kstep; const char* b3 = b2 + kstep;
;             if (last && has_next) S.a_ready(nxt);
;             if (last) E.prefetch(lds + 139264, cur, wid, lane);
;             if constexpr (SP2) {
;             PG8_LDB(B0, 0, 0); PG8_LDB(B1, 0, 1); PG8_SCHED; PG8_LDA(At, 0, 0); PG8_STAGE(PG8_SA(1, 1), a1 + hstep, voffA);
;             PG8_WAIT_V(8); PG8_WAIT_L(0); PG8_BAR; PG8_MMA(0, 0, At, B0); PG8_MMA(0, 1, At, B1); PG8_BAR; PG8_SCHED;
;             PG8_LDA(At, 0, 1); PG8_STAGE(PG8_SB(0, 0), b2, voffB); PG8_STAGE(PG8_SB(0, 1), b2 + hstep, voffB); PG8_STAGE(PG8_SA(0, 0), a2, voffA);
;             PG8_WAIT_V(8); PG8_WAIT_L(0); PG8_BAR; PG8_MMA(1, 0, At, B0); PG8_MMA(1, 1, At, B1); PG8_BAR; PG8_SCHED;
.LBB0_1432:
	ds_read_b128 v[128:131], v167
	ds_read_b128 v[132:135], v167 offset:1024
	ds_read_b128 v[136:139], v167 offset:2048
	ds_read_b128 v[140:143], v167 offset:3072
	ds_read_b128 v[160:163], v168
	ds_read_b128 v[170:173], v168 offset:1024
	ds_read_b128 v[174:177], v168 offset:2048
	ds_read_b128 v[178:181], v168 offset:3072
	s_add_u32 s20, s18, 0x100
	s_addc_u32 s21, s19, 0
	s_cmp_eq_u32 s52, 40
	s_cselect_b32 s27, s5, s21
	s_cselect_b32 s26, s4, s20
	s_cselect_b32 s23, s17, s51
	s_cselect_b32 s22, s16, s50
	v_lshl_add_u64 v[214:215], s[18:19], 0, v[154:155]
	s_add_i32 m0, s36, 0xc000
	ds_read_b128 v[182:185], v169
	ds_read_b128 v[186:189], v169 offset:1024
	ds_read_b128 v[190:193], v169 offset:2048
	ds_read_b128 v[194:197], v169 offset:3072
	ds_read_b128 v[198:201], v169 offset:4096
	ds_read_b128 v[202:205], v169 offset:5120
	ds_read_b128 v[206:209], v169 offset:6144
	ds_read_b128 v[210:213], v169 offset:7168
	global_load_lds_dwordx4 v[214:215], off
	v_lshl_add_u64 v[214:215], s[18:19], 0, v[152:153]
	s_add_i32 m0, s36, 0xe000
	s_nop 0
	global_load_lds_dwordx4 v[214:215], off
	s_waitcnt vmcnt(8)
	s_waitcnt lgkmcnt(0)
	s_barrier
	s_setprio 1
	s_waitcnt lgkmcnt(0)
	v_mfma_f32_16x16x32_bf16 v[124:127], v[128:131], v[182:185], v[124:127]
	v_mfma_f32_16x16x32_bf16 v[124:127], v[132:135], v[186:189], v[124:127]
	v_mfma_f32_16x16x32_bf16 v[120:123], v[136:139], v[182:185], v[120:123]
	v_mfma_f32_16x16x32_bf16 v[120:123], v[140:143], v[186:189], v[120:123]
	v_mfma_f32_16x16x32_bf16 v[108:111], v[136:139], v[190:193], v[108:111]
	v_mfma_f32_16x16x32_bf16 v[108:111], v[140:143], v[194:197], v[108:111]
	v_mfma_f32_16x16x32_bf16 v[116:119], v[128:131], v[190:193], v[116:119]
	v_mfma_f32_16x16x32_bf16 v[116:119], v[132:135], v[194:197], v[116:119]
	v_mfma_f32_16x16x32_bf16 v[100:103], v[128:131], v[198:201], v[100:103]
	v_mfma_f32_16x16x32_bf16 v[100:103], v[132:135], v[202:205], v[100:103]
	v_mfma_f32_16x16x32_bf16 v[92:95], v[136:139], v[198:201], v[92:95]
	v_mfma_f32_16x16x32_bf16 v[92:95], v[140:143], v[202:205], v[92:95]
	v_mfma_f32_16x16x32_bf16 v[76:79], v[136:139], v[206:209], v[76:79]
	v_mfma_f32_16x16x32_bf16 v[76:79], v[140:143], v[210:213], v[76:79]
	v_mfma_f32_16x16x32_bf16 v[84:87], v[128:131], v[206:209], v[84:87]
	v_mfma_f32_16x16x32_bf16 v[84:87], v[132:135], v[210:213], v[84:87]
	v_mfma_f32_16x16x32_bf16 v[112:115], v[160:163], v[182:185], v[112:115]
	v_mfma_f32_16x16x32_bf16 v[112:115], v[170:173], v[186:189], v[112:115]
	v_mfma_f32_16x16x32_bf16 v[104:107], v[174:177], v[182:185], v[104:107]
	v_mfma_f32_16x16x32_bf16 v[104:107], v[178:181], v[186:189], v[104:107]
	v_mfma_f32_16x16x32_bf16 v[88:91], v[174:177], v[190:193], v[88:91]
	v_mfma_f32_16x16x32_bf16 v[88:91], v[178:181], v[194:197], v[88:91]
	v_mfma_f32_16x16x32_bf16 v[96:99], v[160:163], v[190:193], v[96:99]
	v_mfma_f32_16x16x32_bf16 v[96:99], v[170:173], v[194:197], v[96:99]
	v_mfma_f32_16x16x32_bf16 v[80:83], v[160:163], v[198:201], v[80:83]
	v_mfma_f32_16x16x32_bf16 v[80:83], v[170:173], v[202:205], v[80:83]
	v_mfma_f32_16x16x32_bf16 v[72:75], v[174:177], v[198:201], v[72:75]
	v_mfma_f32_16x16x32_bf16 v[72:75], v[178:181], v[202:205], v[72:75]
	v_mfma_f32_16x16x32_bf16 v[64:67], v[174:177], v[206:209], v[64:67]
	v_mfma_f32_16x16x32_bf16 v[64:67], v[178:181], v[210:213], v[64:67]
	v_mfma_f32_16x16x32_bf16 v[68:71], v[160:163], v[206:209], v[68:71]
	v_mfma_f32_16x16x32_bf16 v[68:71], v[170:173], v[210:213], v[68:71]
	s_setprio 0
	s_barrier
	s_add_i32 s18, s44, s33
	s_mov_b32 m0, s18
	ds_read_b128 v[182:185], v169 offset:16384
	ds_read_b128 v[186:189], v169 offset:17408
	ds_read_b128 v[190:193], v169 offset:18432
	ds_read_b128 v[194:197], v169 offset:19456
	ds_read_b128 v[198:201], v169 offset:20480
	ds_read_b128 v[202:205], v169 offset:21504
	ds_read_b128 v[206:209], v169 offset:22528
	ds_read_b128 v[210:213], v169 offset:23552
	global_load_lds_dwordx4 v148, s[22:23]
	s_add_i32 m0, s18, 0x2000
	s_add_u32 s18, s22, 0xb0000
	v_lshl_add_u64 v[216:217], s[22:23], 0, v[144:145]
	s_addc_u32 s19, s23, 0
	s_add_i32 s53, s45, s33
	global_load_lds_dwordx4 v144, s[22:23]
	s_mov_b32 m0, s53
	s_nop 0
	global_load_lds_dwordx4 v148, s[18:19]
	s_add_i32 m0, s53, 0x2000
	s_nop 0
	global_load_lds_dwordx4 v144, s[18:19]
	s_mov_b32 m0, s36
	s_nop 0
	global_load_lds_dwordx4 v150, s[26:27]
	s_mov_b32 m0, s37
	s_nop 0
	global_load_lds_dwordx4 v146, s[26:27]
	s_waitcnt vmcnt(8)
	s_waitcnt lgkmcnt(0)
	s_barrier
	s_setprio 1
	s_waitcnt lgkmcnt(0)
	v_mfma_f32_16x16x32_bf16 v[60:63], v[128:131], v[182:185], v[60:63]
	v_mfma_f32_16x16x32_bf16 v[60:63], v[132:135], v[186:189], v[60:63]
	v_mfma_f32_16x16x32_bf16 v[56:59], v[136:139], v[182:185], v[56:59]
	v_mfma_f32_16x16x32_bf16 v[56:59], v[140:143], v[186:189], v[56:59]
	v_mfma_f32_16x16x32_bf16 v[44:47], v[136:139], v[190:193], v[44:47]
	v_mfma_f32_16x16x32_bf16 v[44:47], v[140:143], v[194:197], v[44:47]
	v_mfma_f32_16x16x32_bf16 v[48:51], v[128:131], v[190:193], v[48:51]
	v_mfma_f32_16x16x32_bf16 v[48:51], v[132:135], v[194:197], v[48:51]
	v_mfma_f32_16x16x32_bf16 v[36:39], v[128:131], v[198:201], v[36:39]
	v_mfma_f32_16x16x32_bf16 v[36:39], v[132:135], v[202:205], v[36:39]
	v_mfma_f32_16x16x32_bf16 v[28:31], v[136:139], v[198:201], v[28:31]
	v_mfma_f32_16x16x32_bf16 v[28:31], v[140:143], v[202:205], v[28:31]
	v_mfma_f32_16x16x32_bf16 v[12:15], v[136:139], v[206:209], v[12:15]
	v_mfma_f32_16x16x32_bf16 v[12:15], v[140:143], v[210:213], v[12:15]
	v_mfma_f32_16x16x32_bf16 v[20:23], v[128:131], v[206:209], v[20:23]
	v_mfma_f32_16x16x32_bf16 v[20:23], v[132:135], v[210:213], v[20:23]
	v_mfma_f32_16x16x32_bf16 v[52:55], v[160:163], v[182:185], v[52:55]
	v_mfma_f32_16x16x32_bf16 v[52:55], v[170:173], v[186:189], v[52:55]
	v_mfma_f32_16x16x32_bf16 v[40:43], v[174:177], v[182:185], v[40:43]
	v_mfma_f32_16x16x32_bf16 v[40:43], v[178:181], v[186:189], v[40:43]
	v_mfma_f32_16x16x32_bf16 v[24:27], v[174:177], v[190:193], v[24:27]
	v_mfma_f32_16x16x32_bf16 v[24:27], v[178:181], v[194:197], v[24:27]
	v_mfma_f32_16x16x32_bf16 v[32:35], v[160:163], v[190:193], v[32:35]
	v_mfma_f32_16x16x32_bf16 v[32:35], v[170:173], v[194:197], v[32:35]
	v_mfma_f32_16x16x32_bf16 v[16:19], v[160:163], v[198:201], v[16:19]
	v_mfma_f32_16x16x32_bf16 v[16:19], v[170:173], v[202:205], v[16:19]
	v_mfma_f32_16x16x32_bf16 v[8:11], v[174:177], v[198:201], v[8:11]
	v_mfma_f32_16x16x32_bf16 v[8:11], v[178:181], v[202:205], v[8:11]
	v_mfma_f32_16x16x32_bf16 v[0:3], v[174:177], v[206:209], v[0:3]
	v_mfma_f32_16x16x32_bf16 v[0:3], v[178:181], v[210:213], v[0:3]
	v_mfma_f32_16x16x32_bf16 v[4:7], v[160:163], v[206:209], v[4:7]
	v_mfma_f32_16x16x32_bf16 v[4:7], v[170:173], v[210:213], v[4:7]
	s_setprio 0
	s_barrier
; #define PG8_STAGE(bufoff, gbase, voff) do { _Pragma("unroll") for (int _i = 0; _i < 2; ++_i) \
;         __builtin_amdgcn_global_load_lds((const unsigned*)((const char*)(gbase) + (voff)[_i]), (PG8_LAS unsigned*)(lds + (bufoff) + ldsw + _i * 8192), 16, 0, 0); } while (0)
; #define PG8_LDA(dst, b, h) do { _Pragma("unroll") for (int m = 0; m < 4; ++m) _Pragma("unroll") for (int k = 0; k < 2; ++k) dst[m][k] = *(const PG8_LAS bf16x8*)(lds + PG8_SA(b, h) + aoff + m * 2048 + k * 1024); } while (0)
; #define PG8_LDB(dst, b, h) do { _Pragma("unroll") for (int n = 0; n < 2; ++n) _Pragma("unroll") for (int k = 0; k < 2; ++k) dst[n][k] = *(const PG8_LAS bf16x8*)(lds + PG8_SB(b, h) + boff + n * 2048 + k * 1024); } while (0)
; #define PG8_MMA(ai, bj, At, Bt) do { __builtin_amdgcn_s_setprio(1); _Pragma("unroll") for (int m = 0; m < 4; ++m) _Pragma("unroll") for (int n = 0; n < 2; ++n) _Pragma("unroll") for (int k = 0; k < 2; ++k) \
;         acc[ai][bj][m][n] = __builtin_amdgcn_mfma_f32_16x16x32_bf16(Bt[n][k], At[m][k], acc[ai][bj][m][n], 0, 0, 0); __builtin_amdgcn_s_setprio(0); } while (0)
; #define PG8_WAIT_V(n) asm volatile("s_waitcnt vmcnt(" #n ")" ::: "memory")
; #define PG8_WAIT_L(n) asm volatile("s_waitcnt lgkmcnt(" #n ")" ::: "memory")
; #define PG8_BAR __builtin_amdgcn_s_barrier()
; #define PG8_SCHED __builtin_amdgcn_sched_barrier(0)
; template <class Epi, class Sched, bool ALIGN_EPI = false, bool SP2 = false>
; __device__ __forceinline__ void gemm_phase(PG8_LAS unsigned char* lds, const Gemm g, const Sched& S, const Epi& E) {
;     ...
;             PG8_LDB(B0, 1, 0); PG8_LDB(B1, 1, 1); PG8_SCHED; PG8_LDA(At, 1, 0); PG8_STAGE(PG8_SA(0, 1), a2 + hstep, voffA);
;             PG8_WAIT_V(8); PG8_WAIT_L(0); PG8_BAR; PG8_MMA(0, 0, At, B0); PG8_MMA(0, 1, At, B1); PG8_BAR; PG8_SCHED;
;             PG8_LDA(At, 1, 1); PG8_STAGE(PG8_SB(1, 0), b3, voffB); PG8_STAGE(PG8_SB(1, 1), b3 + hstep, voffB); PG8_STAGE(PG8_SA(1, 0), a3, voffA);
;             PG8_WAIT_V(8); PG8_WAIT_L(0); PG8_BAR; PG8_MMA(1, 0, At, B0); PG8_MMA(1, 1, At, B1); PG8_BAR; PG8_SCHED;
;     ...
;         if constexpr (ALIGN_EPI) { if (wr == 0) PG8_BAR; }
	s_add_i32 s53, 0, 0x18000
	s_add_i32 s54, 0, 0x1c000
	v_add_u32_e32 v140, s53, v165
	v_add_u32_e32 v178, s54, v165
	ds_read_b128 v[128:131], v140
	ds_read_b128 v[132:135], v140 offset:1024
	ds_read_b128 v[136:139], v140 offset:2048
	ds_read_b128 v[140:143], v140 offset:3072
	ds_read_b128 v[160:163], v178
	ds_read_b128 v[170:173], v178 offset:1024
	ds_read_b128 v[174:177], v178 offset:2048
	ds_read_b128 v[178:181], v178 offset:3072
	s_add_u32 s18, s26, 0xb0000
	s_addc_u32 s19, s27, 0
	s_mov_b32 m0, s38
	ds_read_b128 v[182:185], v169 offset:32768
	ds_read_b128 v[186:189], v169 offset:33792
	ds_read_b128 v[190:193], v169 offset:34816
	ds_read_b128 v[194:197], v169 offset:35840
	ds_read_b128 v[198:201], v169 offset:36864
	ds_read_b128 v[202:205], v169 offset:37888
	ds_read_b128 v[206:209], v169 offset:38912
	ds_read_b128 v[210:213], v169 offset:39936
	global_load_lds_dwordx4 v150, s[18:19]
	s_mov_b32 m0, s39
	s_nop 0
	global_load_lds_dwordx4 v146, s[18:19]
	s_waitcnt vmcnt(8)
	s_waitcnt lgkmcnt(0)
	s_barrier
	s_setprio 1
	s_waitcnt lgkmcnt(0)
	v_mfma_f32_16x16x32_bf16 v[124:127], v[128:131], v[182:185], v[124:127]
	v_mfma_f32_16x16x32_bf16 v[124:127], v[132:135], v[186:189], v[124:127]
	v_mfma_f32_16x16x32_bf16 v[120:123], v[136:139], v[182:185], v[120:123]
	v_mfma_f32_16x16x32_bf16 v[120:123], v[140:143], v[186:189], v[120:123]
	v_mfma_f32_16x16x32_bf16 v[108:111], v[136:139], v[190:193], v[108:111]
	v_mfma_f32_16x16x32_bf16 v[108:111], v[140:143], v[194:197], v[108:111]
	v_mfma_f32_16x16x32_bf16 v[116:119], v[128:131], v[190:193], v[116:119]
	v_mfma_f32_16x16x32_bf16 v[116:119], v[132:135], v[194:197], v[116:119]
	v_mfma_f32_16x16x32_bf16 v[100:103], v[128:131], v[198:201], v[100:103]
	v_mfma_f32_16x16x32_bf16 v[100:103], v[132:135], v[202:205], v[100:103]
	v_mfma_f32_16x16x32_bf16 v[92:95], v[136:139], v[198:201], v[92:95]
	v_mfma_f32_16x16x32_bf16 v[92:95], v[140:143], v[202:205], v[92:95]
	v_mfma_f32_16x16x32_bf16 v[76:79], v[136:139], v[206:209], v[76:79]
	v_mfma_f32_16x16x32_bf16 v[76:79], v[140:143], v[210:213], v[76:79]
	v_mfma_f32_16x16x32_bf16 v[84:87], v[128:131], v[206:209], v[84:87]
	v_mfma_f32_16x16x32_bf16 v[84:87], v[132:135], v[210:213], v[84:87]
	v_mfma_f32_16x16x32_bf16 v[112:115], v[160:163], v[182:185], v[112:115]
	v_mfma_f32_16x16x32_bf16 v[112:115], v[170:173], v[186:189], v[112:115]
	v_mfma_f32_16x16x32_bf16 v[104:107], v[174:177], v[182:185], v[104:107]
	v_mfma_f32_16x16x32_bf16 v[104:107], v[178:181], v[186:189], v[104:107]
	v_mfma_f32_16x16x32_bf16 v[88:91], v[174:177], v[190:193], v[88:91]
	v_mfma_f32_16x16x32_bf16 v[88:91], v[178:181], v[194:197], v[88:91]
	v_mfma_f32_16x16x32_bf16 v[96:99], v[160:163], v[190:193], v[96:99]
	v_mfma_f32_16x16x32_bf16 v[96:99], v[170:173], v[194:197], v[96:99]
	v_mfma_f32_16x16x32_bf16 v[80:83], v[160:163], v[198:201], v[80:83]
	v_mfma_f32_16x16x32_bf16 v[80:83], v[170:173], v[202:205], v[80:83]
	v_mfma_f32_16x16x32_bf16 v[72:75], v[174:177], v[198:201], v[72:75]
	v_mfma_f32_16x16x32_bf16 v[72:75], v[178:181], v[202:205], v[72:75]
	v_mfma_f32_16x16x32_bf16 v[64:67], v[174:177], v[206:209], v[64:67]
	v_mfma_f32_16x16x32_bf16 v[64:67], v[178:181], v[210:213], v[64:67]
	v_mfma_f32_16x16x32_bf16 v[68:71], v[160:163], v[206:209], v[68:71]
	v_mfma_f32_16x16x32_bf16 v[68:71], v[170:173], v[210:213], v[68:71]
	s_setprio 0
	s_barrier
	s_add_i32 s18, s53, s33
	s_add_u32 s98, s22, s12
	s_addc_u32 s99, s23, s13
	s_add_u32 s100, s26, s12
	s_addc_u32 s101, s27, s13
	s_mov_b32 m0, s18
	ds_read_b128 v[182:185], v169 offset:49152
	ds_read_b128 v[186:189], v169 offset:50176
	ds_read_b128 v[190:193], v169 offset:51200
	ds_read_b128 v[194:197], v169 offset:52224
	ds_read_b128 v[198:201], v169 offset:53248
	ds_read_b128 v[202:205], v169 offset:54272
	ds_read_b128 v[206:209], v169 offset:55296
	ds_read_b128 v[210:213], v169 offset:56320
	global_load_lds_dwordx4 v148, s[98:99]
	s_add_i32 m0, s18, 0x2000
	s_add_u32 s18, s22, 0xb0080
	v_lshl_add_u64 v[214:215], v[216:217], 0, s[12:13]
	s_addc_u32 s19, s23, 0
	s_add_i32 s22, s54, s33
	global_load_lds_dwordx4 v[214:215], off
	s_mov_b32 m0, s22
	s_nop 0
	global_load_lds_dwordx4 v148, s[18:19]
	s_add_i32 m0, s22, 0x2000
	s_nop 0
	global_load_lds_dwordx4 v144, s[18:19]
	s_mov_b32 m0, s41
	s_nop 0
	global_load_lds_dwordx4 v150, s[100:101]
	s_mov_b32 m0, s42
	s_nop 0
	global_load_lds_dwordx4 v146, s[100:101]
	s_waitcnt vmcnt(8)
	s_waitcnt lgkmcnt(0)
	s_barrier
	s_setprio 1
	s_waitcnt lgkmcnt(0)
	v_mfma_f32_16x16x32_bf16 v[60:63], v[128:131], v[182:185], v[60:63]
	v_mfma_f32_16x16x32_bf16 v[60:63], v[132:135], v[186:189], v[60:63]
	v_mfma_f32_16x16x32_bf16 v[56:59], v[136:139], v[182:185], v[56:59]
	v_mfma_f32_16x16x32_bf16 v[56:59], v[140:143], v[186:189], v[56:59]
	v_mfma_f32_16x16x32_bf16 v[44:47], v[136:139], v[190:193], v[44:47]
	v_mfma_f32_16x16x32_bf16 v[44:47], v[140:143], v[194:197], v[44:47]
	v_mfma_f32_16x16x32_bf16 v[48:51], v[128:131], v[190:193], v[48:51]
	v_mfma_f32_16x16x32_bf16 v[48:51], v[132:135], v[194:197], v[48:51]
	v_mfma_f32_16x16x32_bf16 v[36:39], v[128:131], v[198:201], v[36:39]
	v_mfma_f32_16x16x32_bf16 v[36:39], v[132:135], v[202:205], v[36:39]
	v_mfma_f32_16x16x32_bf16 v[28:31], v[136:139], v[198:201], v[28:31]
	v_mfma_f32_16x16x32_bf16 v[28:31], v[140:143], v[202:205], v[28:31]
	v_mfma_f32_16x16x32_bf16 v[12:15], v[136:139], v[206:209], v[12:15]
	v_mfma_f32_16x16x32_bf16 v[12:15], v[140:143], v[210:213], v[12:15]
	v_mfma_f32_16x16x32_bf16 v[20:23], v[128:131], v[206:209], v[20:23]
	v_mfma_f32_16x16x32_bf16 v[20:23], v[132:135], v[210:213], v[20:23]
	v_mfma_f32_16x16x32_bf16 v[52:55], v[160:163], v[182:185], v[52:55]
	v_mfma_f32_16x16x32_bf16 v[52:55], v[170:173], v[186:189], v[52:55]
	v_mfma_f32_16x16x32_bf16 v[40:43], v[174:177], v[182:185], v[40:43]
	v_mfma_f32_16x16x32_bf16 v[40:43], v[178:181], v[186:189], v[40:43]
	v_mfma_f32_16x16x32_bf16 v[24:27], v[174:177], v[190:193], v[24:27]
	v_mfma_f32_16x16x32_bf16 v[24:27], v[178:181], v[194:197], v[24:27]
	v_mfma_f32_16x16x32_bf16 v[32:35], v[160:163], v[190:193], v[32:35]
	v_mfma_f32_16x16x32_bf16 v[32:35], v[170:173], v[194:197], v[32:35]
	v_mfma_f32_16x16x32_bf16 v[16:19], v[160:163], v[198:201], v[16:19]
	v_mfma_f32_16x16x32_bf16 v[16:19], v[170:173], v[202:205], v[16:19]
	v_mfma_f32_16x16x32_bf16 v[8:11], v[174:177], v[198:201], v[8:11]
	v_mfma_f32_16x16x32_bf16 v[8:11], v[178:181], v[202:205], v[8:11]
	v_mfma_f32_16x16x32_bf16 v[0:3], v[174:177], v[206:209], v[0:3]
	v_mfma_f32_16x16x32_bf16 v[0:3], v[178:181], v[210:213], v[0:3]
	v_mfma_f32_16x16x32_bf16 v[4:7], v[160:163], v[206:209], v[4:7]
	v_mfma_f32_16x16x32_bf16 v[4:7], v[170:173], v[210:213], v[4:7]
	s_setprio 0
	s_barrier
	s_add_i32 s52, s52, 2
	s_add_u32 s50, s50, 0x100
	s_addc_u32 s51, s51, 0
	s_cmp_gt_u32 s52, 41
	s_mov_b64 s[18:19], s[20:21]
	s_cbranch_scc0 .LBB0_1432
	s_and_b64 vcc, exec, s[14:15]
	s_cbranch_vccz .LBB0_1435
	s_barrier
